# GEMM phases: s_setprio 2 while a wave is in its MFMA main loop, 0 during the epilogue
# speedup vs baseline: 1.0014x; 1.0014x over previous
.LBB0_205:
	s_mul_hi_i32 s0, s2, 0x2e8ba2e9
	s_lshr_b32 s1, s0, 31
	s_ashr_i32 s0, s0, 3
	s_add_i32 s6, s0, s1
	s_lshl_b32 s4, s6, 1
	s_and_b32 s1, s2, 1
	s_add_i32 s7, s4, s26
	s_or_b32 s1, s7, s1
	s_lshl_b32 s4, s1, 8
	s_mul_i32 s0, s6, 0xffffffd4
	v_add_u32_e32 v0, s4, v145
	s_add_i32 s0, s0, s2
	v_ashrrev_i32_e32 v1, 31, v0
	v_lshlrev_b64 v[0:1], 11, v[0:1]
	s_lshl_b32 s48, s0, 6
	s_mov_b32 m0, s27
	v_lshl_add_u64 v[0:1], v[132:133], 0, v[0:1]
	s_and_b32 s5, s48, 0xffffff80
	v_add_u32_e32 v2, s5, v146
	s_setprio 2
	global_load_lds_dwordx4 v[0:1], off
	v_lshl_add_u64 v[4:5], v[0:1], 0, s[16:17]
	s_mov_b32 m0, s31
	s_mov_b64 s[0:1], 0x10000
	v_ashrrev_i32_e32 v3, 31, v2
	global_load_lds_dwordx4 v[4:5], off
	v_lshl_add_u64 v[4:5], v[0:1], 0, s[0:1]
	s_mov_b32 m0, s33
	s_mov_b64 s[0:1], 0x18000
	v_lshlrev_b64 v[2:3], 11, v[2:3]
	global_load_lds_dwordx4 v[4:5], off
	v_lshl_add_u64 v[4:5], v[0:1], 0, s[0:1]
	s_mov_b32 m0, s34
	v_lshl_add_u64 v[2:3], v[134:135], 0, v[2:3]
	global_load_lds_dwordx4 v[4:5], off
	s_mov_b32 m0, s35
	v_lshl_add_u64 v[4:5], v[2:3], 0, s[16:17]
	global_load_lds_dwordx4 v[2:3], off
	s_mov_b32 m0, s36
	s_mov_b64 s[0:1], 0x10040
	global_load_lds_dwordx4 v[4:5], off
	v_lshl_add_u64 v[4:5], v[0:1], 0, 64
	s_mov_b32 m0, s37
	s_mulk_i32 s6, 0xb00
	global_load_lds_dwordx4 v[4:5], off
	v_lshl_add_u64 v[4:5], v[0:1], 0, s[18:19]
	s_mov_b32 m0, s38
	v_cndmask_b32_e64 v6, 0, 1, s[12:13]
	global_load_lds_dwordx4 v[4:5], off
	v_lshl_add_u64 v[4:5], v[0:1], 0, s[0:1]
	s_mov_b32 m0, s39
	s_mov_b64 s[0:1], 0x18040
	global_load_lds_dwordx4 v[4:5], off
	v_lshl_add_u64 v[0:1], v[0:1], 0, s[0:1]
	s_mov_b32 m0, s40
	s_sub_i32 s0, s29, s6
	global_load_lds_dwordx4 v[0:1], off
	v_lshl_add_u64 v[0:1], v[2:3], 0, 64
	s_mov_b32 m0, s41
	s_and_b32 s0, s0, 0xffffff80
	global_load_lds_dwordx4 v[0:1], off
	v_lshl_add_u64 v[0:1], v[2:3], 0, s[18:19]
	s_mov_b32 m0, s42
	s_mov_b32 s6, 2
	global_load_lds_dwordx4 v[0:1], off
	v_add_u32_e32 v0, s0, v146
	v_ashrrev_i32_e32 v1, 31, v0
	v_lshlrev_b64 v[0:1], 11, v[0:1]
	v_lshl_add_u64 v[138:139], v[134:135], 0, v[0:1]
	v_add_u32_e32 v0, s7, v6
	v_lshl_add_u32 v0, v0, 8, v145
	v_ashrrev_i32_e32 v1, 31, v0
	v_lshlrev_b64 v[0:1], 11, v[0:1]
	v_lshl_add_u64 v[140:141], v[132:133], 0, v[0:1]
	s_mov_b64 s[0:1], 0
	s_mov_b32 s7, 0
	v_mov_b32_e32 v0, 0
	v_mov_b32_e32 v1, v131
	v_mov_b32_e32 v2, v131
	v_mov_b32_e32 v3, v131
	v_mov_b32_e32 v4, 0
	v_mov_b32_e32 v5, v131
	v_mov_b32_e32 v6, v131
	v_mov_b32_e32 v7, v131
	v_mov_b32_e32 v8, 0
	v_mov_b32_e32 v9, v131
	v_mov_b32_e32 v10, v131
	v_mov_b32_e32 v11, v131
	v_mov_b32_e32 v12, 0
	v_mov_b32_e32 v13, v131
	v_mov_b32_e32 v14, v131
	v_mov_b32_e32 v15, v131
	v_mov_b32_e32 v16, 0
	v_mov_b32_e32 v17, v131
	v_mov_b32_e32 v18, v131
	v_mov_b32_e32 v19, v131
	v_mov_b32_e32 v20, 0
	v_mov_b32_e32 v21, v131
	v_mov_b32_e32 v22, v131
	v_mov_b32_e32 v23, v131
	v_mov_b32_e32 v24, 0
	v_mov_b32_e32 v25, v131
	v_mov_b32_e32 v26, v131
	v_mov_b32_e32 v27, v131
	v_mov_b32_e32 v28, 0
	v_mov_b32_e32 v29, v131
	v_mov_b32_e32 v30, v131
	v_mov_b32_e32 v31, v131
	v_mov_b32_e32 v32, 0
	v_mov_b32_e32 v33, v131
	v_mov_b32_e32 v34, v131
	v_mov_b32_e32 v35, v131
	v_mov_b32_e32 v36, 0
	v_mov_b32_e32 v37, v131
	v_mov_b32_e32 v38, v131
	v_mov_b32_e32 v39, v131
	v_mov_b32_e32 v44, 0
	v_mov_b32_e32 v45, v131
	v_mov_b32_e32 v46, v131
	v_mov_b32_e32 v47, v131
	v_mov_b32_e32 v52, 0
	v_mov_b32_e32 v53, v131
	v_mov_b32_e32 v54, v131
	v_mov_b32_e32 v55, v131
	v_mov_b32_e32 v60, 0
	v_mov_b32_e32 v61, v131
	v_mov_b32_e32 v62, v131
	v_mov_b32_e32 v63, v131
	v_mov_b32_e32 v68, 0
	v_mov_b32_e32 v69, v131
	v_mov_b32_e32 v70, v131
	v_mov_b32_e32 v71, v131
	v_mov_b32_e32 v76, 0
	v_mov_b32_e32 v77, v131
	v_mov_b32_e32 v78, v131
	v_mov_b32_e32 v79, v131
	v_mov_b32_e32 v84, 0
	v_mov_b32_e32 v85, v131
	v_mov_b32_e32 v86, v131
	v_mov_b32_e32 v87, v131
	v_mov_b32_e32 v40, 0
	v_mov_b32_e32 v41, v131
	v_mov_b32_e32 v42, v131
	v_mov_b32_e32 v43, v131
	v_mov_b32_e32 v48, 0
	v_mov_b32_e32 v49, v131
	v_mov_b32_e32 v50, v131
	v_mov_b32_e32 v51, v131
	v_mov_b32_e32 v56, 0
	v_mov_b32_e32 v57, v131
	v_mov_b32_e32 v58, v131
	v_mov_b32_e32 v59, v131
	v_mov_b32_e32 v64, 0
	v_mov_b32_e32 v65, v131
	v_mov_b32_e32 v66, v131
	v_mov_b32_e32 v67, v131
	v_mov_b32_e32 v72, 0
	v_mov_b32_e32 v73, v131
	v_mov_b32_e32 v74, v131
	v_mov_b32_e32 v75, v131
	v_mov_b32_e32 v80, 0
	v_mov_b32_e32 v81, v131
	v_mov_b32_e32 v82, v131
	v_mov_b32_e32 v83, v131
	v_mov_b32_e32 v88, 0
	v_mov_b32_e32 v89, v131
	v_mov_b32_e32 v90, v131
	v_mov_b32_e32 v91, v131
	v_mov_b32_e32 v92, 0
	v_mov_b32_e32 v93, v131
	v_mov_b32_e32 v94, v131
	v_mov_b32_e32 v95, v131
	v_mov_b32_e32 v96, 0
	v_mov_b32_e32 v97, v131
	v_mov_b32_e32 v98, v131
	v_mov_b32_e32 v99, v131
	v_mov_b32_e32 v100, 0
	v_mov_b32_e32 v101, v131
	v_mov_b32_e32 v102, v131
	v_mov_b32_e32 v103, v131
	v_mov_b32_e32 v104, 0
	v_mov_b32_e32 v105, v131
	v_mov_b32_e32 v106, v131
	v_mov_b32_e32 v107, v131
	v_mov_b32_e32 v108, 0
	v_mov_b32_e32 v109, v131
	v_mov_b32_e32 v110, v131
	v_mov_b32_e32 v111, v131
	v_mov_b32_e32 v112, 0
	v_mov_b32_e32 v113, v131
	v_mov_b32_e32 v114, v131
	v_mov_b32_e32 v115, v131
	v_mov_b32_e32 v116, 0
	v_mov_b32_e32 v117, v131
	v_mov_b32_e32 v118, v131
	v_mov_b32_e32 v119, v131
	v_mov_b32_e32 v120, 0
	v_mov_b32_e32 v121, v131
	v_mov_b32_e32 v122, v131
	v_mov_b32_e32 v123, v131
	v_mov_b32_e32 v124, 0
	v_mov_b32_e32 v125, v131
	v_mov_b32_e32 v126, v131
	v_mov_b32_e32 v127, v131
.LBB0_206:
	s_mul_i32 s8, s6, 0x6000
	s_waitcnt vmcnt(6)
	s_add_i32 s10, s27, s8
	s_mul_i32 s98, s7, 0x6000
	v_lshl_add_u64 v[200:201], v[140:141], 0, s[0:1]
	v_lshl_add_u64 v[202:203], v[138:139], 0, s[0:1]
	s_add_i32 s99, s10, s28
	s_waitcnt lgkmcnt(0)
	s_barrier
	v_add_u32_e32 v182, s98, v142
	v_add_u32_e32 v183, s98, v144
	ds_read_b128 v[166:169], v183
	ds_read_b128 v[150:153], v182
	ds_read_b128 v[170:173], v183 offset:1024
	ds_read_b128 v[174:177], v183 offset:2048
	ds_read_b128 v[178:181], v183 offset:3072
	ds_read_b128 v[154:157], v182 offset:1024
	ds_read_b128 v[158:161], v182 offset:2048
	ds_read_b128 v[162:165], v182 offset:3072
	ds_read_b128 v[184:187], v182 offset:4096
	ds_read_b128 v[188:191], v182 offset:5120
	ds_read_b128 v[192:195], v182 offset:6144
	ds_read_b128 v[196:199], v182 offset:7168
	v_lshl_add_u64 v[204:205], v[200:201], 0, s[20:21]
	s_mov_b32 m0, s10
	s_waitcnt lgkmcnt(10)
	v_mfma_f32_16x16x32_bf16 v[84:87], v[150:153], v[166:169], v[84:87]
	global_load_lds_dwordx4 v[204:205], off
	s_waitcnt lgkmcnt(9)
	v_mfma_f32_16x16x32_bf16 v[76:79], v[150:153], v[170:173], v[76:79]
	v_lshl_add_u64 v[204:205], v[200:201], 0, s[22:23]
	s_add_i32 m0, s10, 0x400
	s_waitcnt lgkmcnt(8)
	v_mfma_f32_16x16x32_bf16 v[68:71], v[150:153], v[174:177], v[68:71]
	global_load_lds_dwordx4 v[204:205], off
	s_waitcnt lgkmcnt(7)
	v_mfma_f32_16x16x32_bf16 v[60:63], v[150:153], v[178:181], v[60:63]
	s_mov_b64 s[100:101], 0x10080
	v_lshl_add_u64 v[204:205], v[200:201], 0, s[100:101]
	s_add_i32 m0, s10, 0x800
	s_waitcnt lgkmcnt(6)
	v_mfma_f32_16x16x32_bf16 v[52:55], v[154:157], v[166:169], v[52:55]
	global_load_lds_dwordx4 v[204:205], off
	v_mfma_f32_16x16x32_bf16 v[44:47], v[154:157], v[170:173], v[44:47]
	v_mfma_f32_16x16x32_bf16 v[36:39], v[154:157], v[174:177], v[36:39]
	s_mov_b64 s[100:101], 0x18080
	v_lshl_add_u64 v[204:205], v[200:201], 0, s[100:101]
	s_add_i32 m0, s10, 0xc00
	v_mfma_f32_16x16x32_bf16 v[32:35], v[154:157], v[178:181], v[32:35]
	global_load_lds_dwordx4 v[204:205], off
	s_waitcnt lgkmcnt(5)
	v_mfma_f32_16x16x32_bf16 v[28:31], v[158:161], v[166:169], v[28:31]
	v_lshl_add_u64 v[204:205], v[202:203], 0, s[20:21]
	s_add_i32 m0, s99, 0x4000
	v_mfma_f32_16x16x32_bf16 v[24:27], v[158:161], v[170:173], v[24:27]
	global_load_lds_dwordx4 v[204:205], off
	v_mfma_f32_16x16x32_bf16 v[20:23], v[158:161], v[174:177], v[20:23]
	v_lshl_add_u64 v[204:205], v[202:203], 0, s[22:23]
	s_add_i32 m0, s99, 0x4400
	v_mfma_f32_16x16x32_bf16 v[16:19], v[158:161], v[178:181], v[16:19]
	global_load_lds_dwordx4 v[204:205], off
	s_waitcnt lgkmcnt(4)
	v_mfma_f32_16x16x32_bf16 v[12:15], v[162:165], v[166:169], v[12:15]
	v_mfma_f32_16x16x32_bf16 v[8:11], v[162:165], v[170:173], v[8:11]
	v_mfma_f32_16x16x32_bf16 v[4:7], v[162:165], v[174:177], v[4:7]
	v_mfma_f32_16x16x32_bf16 v[0:3], v[162:165], v[178:181], v[0:3]
	s_waitcnt lgkmcnt(3)
	v_mfma_f32_16x16x32_bf16 v[124:127], v[184:187], v[166:169], v[124:127]
	v_mfma_f32_16x16x32_bf16 v[120:123], v[184:187], v[170:173], v[120:123]
	v_mfma_f32_16x16x32_bf16 v[116:119], v[184:187], v[174:177], v[116:119]
	v_mfma_f32_16x16x32_bf16 v[112:115], v[184:187], v[178:181], v[112:115]
	s_waitcnt lgkmcnt(2)
	v_mfma_f32_16x16x32_bf16 v[108:111], v[188:191], v[166:169], v[108:111]
	v_mfma_f32_16x16x32_bf16 v[104:107], v[188:191], v[170:173], v[104:107]
	v_mfma_f32_16x16x32_bf16 v[100:103], v[188:191], v[174:177], v[100:103]
	v_mfma_f32_16x16x32_bf16 v[96:99], v[188:191], v[178:181], v[96:99]
	s_waitcnt lgkmcnt(1)
	v_mfma_f32_16x16x32_bf16 v[92:95], v[192:195], v[166:169], v[92:95]
	v_mfma_f32_16x16x32_bf16 v[88:91], v[192:195], v[170:173], v[88:91]
	v_mfma_f32_16x16x32_bf16 v[80:83], v[192:195], v[174:177], v[80:83]
	v_mfma_f32_16x16x32_bf16 v[72:75], v[192:195], v[178:181], v[72:75]
	s_waitcnt lgkmcnt(0)
	v_mfma_f32_16x16x32_bf16 v[64:67], v[196:199], v[166:169], v[64:67]
	v_mfma_f32_16x16x32_bf16 v[56:59], v[196:199], v[170:173], v[56:59]
	v_mfma_f32_16x16x32_bf16 v[48:51], v[196:199], v[174:177], v[48:51]
	v_mfma_f32_16x16x32_bf16 v[40:43], v[196:199], v[178:181], v[40:43]
	s_add_i32 s8, s7, 1
	s_cmp_lg_u32 s7, 2
	s_cselect_b32 s7, s8, 0
	s_add_i32 s8, s6, 1
	s_cmp_lg_u32 s6, 2
	s_cselect_b32 s6, s8, 0
	s_add_u32 s0, s0, 64
	s_addc_u32 s1, s1, 0
	s_cmpk_eq_i32 s0, 0x780
	s_cbranch_scc0 .LBB0_206
	s_waitcnt vmcnt(6)
	s_waitcnt lgkmcnt(0)
	s_barrier
	ds_read_b128 v[138:141], v142
	ds_read_b128 v[150:153], v142 offset:1024
	ds_read_b128 v[154:157], v142 offset:2048
	ds_read_b128 v[158:161], v142 offset:3072
	ds_read_b128 v[162:165], v144
	ds_read_b128 v[166:169], v144 offset:1024
	ds_read_b128 v[170:173], v144 offset:2048
	ds_read_b128 v[174:177], v144 offset:3072
	s_waitcnt lgkmcnt(0)
	s_nop 0
	v_mfma_f32_16x16x32_bf16 v[84:87], v[138:141], v[162:165], v[84:87]
	v_mfma_f32_16x16x32_bf16 v[76:79], v[138:141], v[166:169], v[76:79]
	v_mfma_f32_16x16x32_bf16 v[68:71], v[138:141], v[170:173], v[68:71]
	v_mfma_f32_16x16x32_bf16 v[60:63], v[138:141], v[174:177], v[60:63]
	v_mfma_f32_16x16x32_bf16 v[52:55], v[150:153], v[162:165], v[52:55]
	v_mfma_f32_16x16x32_bf16 v[44:47], v[150:153], v[166:169], v[44:47]
	v_mfma_f32_16x16x32_bf16 v[36:39], v[150:153], v[170:173], v[36:39]
	v_mfma_f32_16x16x32_bf16 v[32:35], v[150:153], v[174:177], v[32:35]
	v_mfma_f32_16x16x32_bf16 v[28:31], v[154:157], v[162:165], v[28:31]
	v_mfma_f32_16x16x32_bf16 v[24:27], v[154:157], v[166:169], v[24:27]
	v_mfma_f32_16x16x32_bf16 v[20:23], v[154:157], v[170:173], v[20:23]
	v_mfma_f32_16x16x32_bf16 v[16:19], v[154:157], v[174:177], v[16:19]
	v_mfma_f32_16x16x32_bf16 v[12:15], v[158:161], v[162:165], v[12:15]
	v_mfma_f32_16x16x32_bf16 v[8:11], v[158:161], v[166:169], v[8:11]
	v_mfma_f32_16x16x32_bf16 v[4:7], v[158:161], v[170:173], v[4:7]
	v_mfma_f32_16x16x32_bf16 v[0:3], v[158:161], v[174:177], v[0:3]
	ds_read_b128 v[138:141], v142 offset:4096
	ds_read_b128 v[150:153], v142 offset:5120
	ds_read_b128 v[154:157], v142 offset:6144
	ds_read_b128 v[158:161], v142 offset:7168
	s_waitcnt lgkmcnt(0)
	s_nop 0
	v_mfma_f32_16x16x32_bf16 v[178:181], v[138:141], v[162:165], v[124:127]
	v_mfma_f32_16x16x32_bf16 v[182:185], v[138:141], v[166:169], v[120:123]
	v_mfma_f32_16x16x32_bf16 v[186:189], v[138:141], v[170:173], v[116:119]
	v_mfma_f32_16x16x32_bf16 v[138:141], v[138:141], v[174:177], v[112:115]
	v_mfma_f32_16x16x32_bf16 v[190:193], v[150:153], v[162:165], v[108:111]
	v_mfma_f32_16x16x32_bf16 v[194:197], v[150:153], v[166:169], v[104:107]
	v_mfma_f32_16x16x32_bf16 v[198:201], v[150:153], v[170:173], v[100:103]
	v_mfma_f32_16x16x32_bf16 v[150:153], v[150:153], v[174:177], v[96:99]
	v_mfma_f32_16x16x32_bf16 v[202:205], v[154:157], v[162:165], v[92:95]
	v_mfma_f32_16x16x32_bf16 v[206:209], v[154:157], v[166:169], v[88:91]
	v_mfma_f32_16x16x32_bf16 v[210:213], v[154:157], v[170:173], v[80:83]
	v_mfma_f32_16x16x32_bf16 v[154:157], v[154:157], v[174:177], v[72:75]
	v_mfma_f32_16x16x32_bf16 v[162:165], v[158:161], v[162:165], v[64:67]
	v_mfma_f32_16x16x32_bf16 v[166:169], v[158:161], v[166:169], v[56:59]
	v_mfma_f32_16x16x32_bf16 v[170:173], v[158:161], v[170:173], v[48:51]
	v_mfma_f32_16x16x32_bf16 v[158:161], v[158:161], v[174:177], v[40:43]
	s_waitcnt vmcnt(0)
	s_waitcnt lgkmcnt(0)
	s_barrier
	ds_read_b128 v[40:43], v148
	ds_read_b128 v[48:51], v148 offset:1024
	ds_read_b128 v[56:59], v148 offset:2048
	ds_read_b128 v[174:177], v148 offset:3072
	ds_read_b128 v[214:217], v149
	ds_read_b128 v[218:221], v149 offset:1024
	ds_read_b128 v[222:225], v149 offset:2048
	ds_read_b128 v[228:231], v149 offset:3072
	s_waitcnt lgkmcnt(0)
	s_nop 0
	v_mfma_f32_16x16x32_bf16 v[116:119], v[40:43], v[218:221], v[76:79]
	v_mfma_f32_16x16x32_bf16 v[120:123], v[40:43], v[222:225], v[68:71]
	v_mfma_f32_16x16x32_bf16 v[64:67], v[174:177], v[214:217], v[12:15]
	v_mfma_f32_16x16x32_bf16 v[68:71], v[174:177], v[218:221], v[8:11]
	v_mfma_f32_16x16x32_bf16 v[72:75], v[174:177], v[222:225], v[4:7]
	v_mfma_f32_16x16x32_bf16 v[76:79], v[174:177], v[228:231], v[0:3]
	ds_read_b128 v[0:3], v148 offset:4096
	ds_read_b128 v[4:7], v148 offset:5120
	ds_read_b128 v[8:11], v148 offset:6144
	ds_read_b128 v[12:15], v148 offset:7168
	s_waitcnt lgkmcnt(0)
	v_mfma_f32_16x16x32_bf16 v[112:115], v[40:43], v[214:217], v[84:87]
	v_mfma_f32_16x16x32_bf16 v[124:127], v[40:43], v[228:231], v[60:63]
	v_mfma_f32_16x16x32_bf16 v[96:99], v[48:51], v[214:217], v[52:55]
	v_mfma_f32_16x16x32_bf16 v[100:103], v[48:51], v[218:221], v[44:47]
	v_mfma_f32_16x16x32_bf16 v[104:107], v[48:51], v[222:225], v[36:39]
	v_mfma_f32_16x16x32_bf16 v[108:111], v[48:51], v[228:231], v[32:35]
	v_mfma_f32_16x16x32_bf16 v[80:83], v[56:59], v[214:217], v[28:31]
	v_mfma_f32_16x16x32_bf16 v[84:87], v[56:59], v[218:221], v[24:27]
	v_mfma_f32_16x16x32_bf16 v[88:91], v[56:59], v[222:225], v[20:23]
	v_mfma_f32_16x16x32_bf16 v[92:95], v[56:59], v[228:231], v[16:19]
	v_mfma_f32_16x16x32_bf16 v[48:51], v[0:3], v[214:217], v[178:181]
	v_mfma_f32_16x16x32_bf16 v[52:55], v[0:3], v[218:221], v[182:185]
	v_mfma_f32_16x16x32_bf16 v[56:59], v[0:3], v[222:225], v[186:189]
	v_mfma_f32_16x16x32_bf16 v[60:63], v[0:3], v[228:231], v[138:141]
	v_mfma_f32_16x16x32_bf16 v[32:35], v[4:7], v[214:217], v[190:193]
	v_mfma_f32_16x16x32_bf16 v[36:39], v[4:7], v[218:221], v[194:197]
	v_mfma_f32_16x16x32_bf16 v[40:43], v[4:7], v[222:225], v[198:201]
	v_mfma_f32_16x16x32_bf16 v[44:47], v[4:7], v[228:231], v[150:153]
	v_mfma_f32_16x16x32_bf16 v[16:19], v[8:11], v[214:217], v[202:205]
	v_mfma_f32_16x16x32_bf16 v[20:23], v[8:11], v[218:221], v[206:209]
	v_mfma_f32_16x16x32_bf16 v[24:27], v[8:11], v[222:225], v[210:213]
	v_mfma_f32_16x16x32_bf16 v[28:31], v[8:11], v[228:231], v[154:157]
	v_mfma_f32_16x16x32_bf16 v[0:3], v[12:15], v[214:217], v[162:165]
	v_mfma_f32_16x16x32_bf16 v[4:7], v[12:15], v[218:221], v[166:169]
	v_mfma_f32_16x16x32_bf16 v[8:11], v[12:15], v[222:225], v[170:173]
	v_mfma_f32_16x16x32_bf16 v[12:15], v[12:15], v[228:231], v[158:161]
	s_setprio 0
	v_add_u32_e32 v150, s4, v129
	v_or_b32_e32 v151, v150, v147
	v_or_b32_e32 v138, s5, v143
	v_mov_b32_e32 v153, v151
	v_mov_b64_e32 v[140:141], s[94:95]
	s_waitcnt lgkmcnt(0)
	s_barrier
	v_ashrrev_i32_e32 v139, 31, v138
	v_or_b32_e32 v152, v138, v128
	v_mad_i64_i32 v[140:141], s[0:1], v153, s43, v[140:141]
	v_lshl_add_u64 v[140:141], v[138:139], 1, v[140:141]
	v_lshl_add_u64 v[140:141], v[140:141], 0, v[130:131]
	v_cmp_gt_i32_e32 vcc, s44, v152
	s_and_saveexec_b64 s[0:1], vcc
	s_cbranch_execz .LBB0_209
	v_cvt_pk_bf16_f32 v153, v112, v112
	global_store_short_d16_hi v[140:141], v153, off

.LBB0_633:
	s_mul_hi_i32 s30, s2, 0x66666667
	s_lshr_b32 s31, s30, 31
	s_ashr_i32 s30, s30, 4
	s_add_i32 s30, s30, s31
	s_lshl_b32 s34, s30, 2
	s_and_b32 s31, s2, 3
	s_add_i32 s34, s34, s33
	s_or_b32 s31, s34, s31
	s_lshl_b32 s54, s31, 7
	s_mulk_i32 s30, 0xfb00
	v_add_u32_e32 v0, s54, v80
	s_add_i32 s53, s37, s30
	v_ashrrev_i32_e32 v1, 31, v0
	s_and_b32 s30, s53, 0xffffff80
	v_add_u32_e32 v2, s30, v80
	v_lshlrev_b64 v[0:1], 9, v[0:1]
	s_mov_b32 m0, s36
	v_ashrrev_i32_e32 v3, 31, v2
	v_lshl_add_u64 v[78:79], v[74:75], 0, v[0:1]
	v_lshlrev_b64 v[2:3], 9, v[2:3]
	s_setprio 2
	global_load_lds_dwordx4 v[78:79], off
	v_lshl_add_u64 v[0:1], v[78:79], 0, s[0:1]
	s_mov_b32 m0, s39
	v_lshl_add_u64 v[68:69], v[72:73], 0, v[2:3]
	global_load_lds_dwordx4 v[0:1], off
	s_mov_b32 m0, s40
	v_lshl_add_u64 v[0:1], v[68:69], 0, s[0:1]
	global_load_lds_dwordx4 v[68:69], off
	s_mov_b32 m0, s41
	v_lshl_add_u64 v[4:5], v[78:79], 0, s[8:9]
	global_load_lds_dwordx4 v[0:1], off
	v_lshl_add_u64 v[0:1], v[78:79], 0, 64
	s_mov_b32 m0, s42
	v_lshl_add_u64 v[6:7], v[78:79], 0, s[6:7]
	global_load_lds_dwordx4 v[0:1], off
	v_lshl_add_u64 v[0:1], v[78:79], 0, s[4:5]
	s_mov_b32 m0, s43
	v_lshl_add_u64 v[2:3], v[68:69], 0, s[8:9]
	global_load_lds_dwordx4 v[0:1], off
	v_lshl_add_u64 v[0:1], v[68:69], 0, 64
	s_mov_b32 m0, s44
	v_lshl_add_u64 v[90:91], v[78:79], 0, s[12:13]
	global_load_lds_dwordx4 v[0:1], off
	v_lshl_add_u64 v[0:1], v[68:69], 0, s[4:5]
	s_mov_b32 m0, s45
	v_lshl_add_u64 v[92:93], v[78:79], 0, s[10:11]
	global_load_lds_dwordx4 v[0:1], off
	s_waitcnt vmcnt(4)
	s_waitcnt lgkmcnt(0)
	s_barrier
	s_mov_b32 m0, s46
	v_lshl_add_u64 v[0:1], v[68:69], 0, s[6:7]
	global_load_lds_dwordx4 v[4:5], off
	s_mov_b32 m0, s47
	s_nop 0
	global_load_lds_dwordx4 v[6:7], off
	s_mov_b32 m0, s48
	s_nop 0
	global_load_lds_dwordx4 v[2:3], off
	s_mov_b32 m0, s49
	s_nop 0
	global_load_lds_dwordx4 v[0:1], off
	ds_read_b128 v[0:3], v82
	ds_read_b128 v[4:7], v82 offset:1024
	ds_read_b128 v[8:11], v82 offset:2048
	ds_read_b128 v[12:15], v82 offset:3072
	ds_read_b128 v[16:19], v83
	ds_read_b128 v[20:23], v83 offset:1024
	ds_read_b128 v[24:27], v83 offset:2048
	ds_read_b128 v[28:31], v83 offset:3072
	s_waitcnt lgkmcnt(0)
	s_waitcnt vmcnt(4)
	s_waitcnt lgkmcnt(0)
	s_barrier
	s_mov_b32 m0, s36
	v_mfma_f32_16x16x32_bf16 v[32:35], v[16:19], v[0:3], 0
	global_load_lds_dwordx4 v[90:91], off
	s_mov_b32 m0, s39
	v_mfma_f32_16x16x32_bf16 v[36:39], v[20:23], v[0:3], 0
	global_load_lds_dwordx4 v[92:93], off
	s_mov_b32 m0, s40
	v_mfma_f32_16x16x32_bf16 v[40:43], v[24:27], v[0:3], 0
	v_mfma_f32_16x16x32_bf16 v[0:3], v[28:31], v[0:3], 0
	v_mfma_f32_16x16x32_bf16 v[44:47], v[16:19], v[4:7], 0
	v_mfma_f32_16x16x32_bf16 v[48:51], v[20:23], v[4:7], 0
	v_mfma_f32_16x16x32_bf16 v[52:55], v[24:27], v[4:7], 0
	v_mfma_f32_16x16x32_bf16 v[4:7], v[28:31], v[4:7], 0
	v_mfma_f32_16x16x32_bf16 v[56:59], v[16:19], v[8:11], 0
	v_mfma_f32_16x16x32_bf16 v[60:63], v[20:23], v[8:11], 0
	v_mfma_f32_16x16x32_bf16 v[64:67], v[24:27], v[8:11], 0
	v_mfma_f32_16x16x32_bf16 v[8:11], v[28:31], v[8:11], 0
	v_mfma_f32_16x16x32_bf16 v[16:19], v[16:19], v[12:15], 0
	v_mfma_f32_16x16x32_bf16 v[20:23], v[20:23], v[12:15], 0
	v_mfma_f32_16x16x32_bf16 v[24:27], v[24:27], v[12:15], 0
	v_mfma_f32_16x16x32_bf16 v[12:15], v[28:31], v[12:15], 0
	v_lshl_add_u64 v[30:31], v[68:69], 0, s[12:13]
	v_lshl_add_u64 v[28:29], v[68:69], 0, s[10:11]
	global_load_lds_dwordx4 v[30:31], off
	s_mov_b32 m0, s41
	s_nop 0
	global_load_lds_dwordx4 v[28:29], off
	ds_read_b128 v[28:31], v85
	ds_read_b128 v[90:93], v85 offset:1024
	ds_read_b128 v[94:97], v85 offset:2048
	ds_read_b128 v[98:101], v85 offset:3072
	ds_read_b128 v[102:105], v86
	ds_read_b128 v[106:109], v86 offset:1024
	ds_read_b128 v[110:113], v86 offset:2048
	ds_read_b128 v[114:117], v86 offset:3072
	s_waitcnt lgkmcnt(0)
	s_waitcnt vmcnt(4)
	s_waitcnt lgkmcnt(0)
	s_barrier
	v_mfma_f32_16x16x32_bf16 v[32:35], v[102:105], v[28:31], v[32:35]
	s_mov_b32 m0, s42
	v_mfma_f32_16x16x32_bf16 v[36:39], v[106:109], v[28:31], v[36:39]
	v_mfma_f32_16x16x32_bf16 v[40:43], v[110:113], v[28:31], v[40:43]
	v_mfma_f32_16x16x32_bf16 v[0:3], v[114:117], v[28:31], v[0:3]
	v_mfma_f32_16x16x32_bf16 v[28:31], v[102:105], v[90:93], v[44:47]
	v_mfma_f32_16x16x32_bf16 v[44:47], v[106:109], v[90:93], v[48:51]
	v_mfma_f32_16x16x32_bf16 v[48:51], v[110:113], v[90:93], v[52:55]
	v_mfma_f32_16x16x32_bf16 v[4:7], v[114:117], v[90:93], v[4:7]
	v_lshl_add_u64 v[90:91], v[78:79], 0, s[16:17]
	v_lshl_add_u64 v[92:93], v[78:79], 0, s[14:15]
	global_load_lds_dwordx4 v[90:91], off
	s_mov_b32 m0, s43
	v_mfma_f32_16x16x32_bf16 v[52:55], v[102:105], v[94:97], v[56:59]
	global_load_lds_dwordx4 v[92:93], off
	s_mov_b32 m0, s44
	v_mfma_f32_16x16x32_bf16 v[56:59], v[106:109], v[94:97], v[60:63]
	v_mfma_f32_16x16x32_bf16 v[60:63], v[110:113], v[94:97], v[64:67]
	s_nop 2
	v_lshl_add_u64 v[66:67], v[68:69], 0, s[16:17]
	v_lshl_add_u64 v[64:65], v[68:69], 0, s[14:15]
	global_load_lds_dwordx4 v[66:67], off
	s_mov_b32 m0, s45
	v_mfma_f32_16x16x32_bf16 v[8:11], v[114:117], v[94:97], v[8:11]
	global_load_lds_dwordx4 v[64:65], off
	s_mov_b32 m0, s46
	v_mfma_f32_16x16x32_bf16 v[16:19], v[102:105], v[98:101], v[16:19]
	v_mfma_f32_16x16x32_bf16 v[20:23], v[106:109], v[98:101], v[20:23]
	v_mfma_f32_16x16x32_bf16 v[24:27], v[110:113], v[98:101], v[24:27]
	v_mfma_f32_16x16x32_bf16 v[12:15], v[114:117], v[98:101], v[12:15]
	ds_read_b128 v[64:67], v87
	ds_read_b128 v[90:93], v87 offset:1024
	ds_read_b128 v[94:97], v87 offset:2048
	ds_read_b128 v[98:101], v87 offset:3072
	ds_read_b128 v[102:105], v88
	ds_read_b128 v[106:109], v88 offset:1024
	ds_read_b128 v[110:113], v88 offset:2048
	ds_read_b128 v[114:117], v88 offset:3072
	s_waitcnt lgkmcnt(0)
	s_waitcnt vmcnt(4)
	s_waitcnt lgkmcnt(0)
	s_barrier
	v_mfma_f32_16x16x32_bf16 v[28:31], v[102:105], v[90:93], v[28:31]
	v_mfma_f32_16x16x32_bf16 v[44:47], v[106:109], v[90:93], v[44:47]
	v_mfma_f32_16x16x32_bf16 v[48:51], v[110:113], v[90:93], v[48:51]
	v_mfma_f32_16x16x32_bf16 v[4:7], v[114:117], v[90:93], v[4:7]
	v_lshl_add_u64 v[90:91], v[78:79], 0, s[20:21]
	v_lshl_add_u64 v[92:93], v[78:79], 0, s[18:19]
	global_load_lds_dwordx4 v[90:91], off
	s_mov_b32 m0, s47
	v_mfma_f32_16x16x32_bf16 v[32:35], v[102:105], v[64:67], v[32:35]
	global_load_lds_dwordx4 v[92:93], off
	s_mov_b32 m0, s48
	v_mfma_f32_16x16x32_bf16 v[36:39], v[106:109], v[64:67], v[36:39]
	v_mfma_f32_16x16x32_bf16 v[40:43], v[110:113], v[64:67], v[40:43]
	v_mfma_f32_16x16x32_bf16 v[0:3], v[114:117], v[64:67], v[0:3]
	v_lshl_add_u64 v[66:67], v[68:69], 0, s[20:21]
	v_lshl_add_u64 v[64:65], v[68:69], 0, s[18:19]
	global_load_lds_dwordx4 v[66:67], off
	s_mov_b32 m0, s49
	v_mfma_f32_16x16x32_bf16 v[52:55], v[102:105], v[94:97], v[52:55]
	global_load_lds_dwordx4 v[64:65], off
	s_mov_b32 m0, s36
	v_mfma_f32_16x16x32_bf16 v[56:59], v[106:109], v[94:97], v[56:59]
	v_mfma_f32_16x16x32_bf16 v[60:63], v[110:113], v[94:97], v[60:63]
	v_mfma_f32_16x16x32_bf16 v[8:11], v[114:117], v[94:97], v[8:11]
	v_mfma_f32_16x16x32_bf16 v[16:19], v[102:105], v[98:101], v[16:19]
	v_mfma_f32_16x16x32_bf16 v[20:23], v[106:109], v[98:101], v[20:23]
	v_mfma_f32_16x16x32_bf16 v[24:27], v[110:113], v[98:101], v[24:27]
	v_mfma_f32_16x16x32_bf16 v[12:15], v[114:117], v[98:101], v[12:15]
	ds_read_b128 v[64:67], v82
	ds_read_b128 v[90:93], v82 offset:1024
	ds_read_b128 v[94:97], v82 offset:2048
	ds_read_b128 v[98:101], v82 offset:3072
	ds_read_b128 v[102:105], v83
	ds_read_b128 v[106:109], v83 offset:1024
	ds_read_b128 v[110:113], v83 offset:2048
	ds_read_b128 v[114:117], v83 offset:3072
	s_waitcnt lgkmcnt(0)
	s_waitcnt vmcnt(4)
	s_waitcnt lgkmcnt(0)
	s_barrier
	v_mfma_f32_16x16x32_bf16 v[28:31], v[102:105], v[90:93], v[28:31]
	v_mfma_f32_16x16x32_bf16 v[44:47], v[106:109], v[90:93], v[44:47]
	v_mfma_f32_16x16x32_bf16 v[48:51], v[110:113], v[90:93], v[48:51]
	v_mfma_f32_16x16x32_bf16 v[4:7], v[114:117], v[90:93], v[4:7]
	v_lshl_add_u64 v[90:91], v[78:79], 0, s[24:25]
	v_lshl_add_u64 v[92:93], v[78:79], 0, s[22:23]
	global_load_lds_dwordx4 v[90:91], off
	s_mov_b32 m0, s39
	v_mfma_f32_16x16x32_bf16 v[32:35], v[102:105], v[64:67], v[32:35]
	global_load_lds_dwordx4 v[92:93], off
	s_mov_b32 m0, s40
	v_mfma_f32_16x16x32_bf16 v[36:39], v[106:109], v[64:67], v[36:39]
	v_mfma_f32_16x16x32_bf16 v[40:43], v[110:113], v[64:67], v[40:43]
	v_mfma_f32_16x16x32_bf16 v[0:3], v[114:117], v[64:67], v[0:3]
	v_lshl_add_u64 v[66:67], v[68:69], 0, s[24:25]
	v_lshl_add_u64 v[64:65], v[68:69], 0, s[22:23]
	global_load_lds_dwordx4 v[66:67], off
	s_mov_b32 m0, s41
	v_mfma_f32_16x16x32_bf16 v[52:55], v[102:105], v[94:97], v[52:55]
	global_load_lds_dwordx4 v[64:65], off
	s_mov_b32 m0, s42
	v_mfma_f32_16x16x32_bf16 v[56:59], v[106:109], v[94:97], v[56:59]
	v_mfma_f32_16x16x32_bf16 v[60:63], v[110:113], v[94:97], v[60:63]
	v_mfma_f32_16x16x32_bf16 v[8:11], v[114:117], v[94:97], v[8:11]
	v_mfma_f32_16x16x32_bf16 v[16:19], v[102:105], v[98:101], v[16:19]
	v_mfma_f32_16x16x32_bf16 v[20:23], v[106:109], v[98:101], v[20:23]
	v_mfma_f32_16x16x32_bf16 v[24:27], v[110:113], v[98:101], v[24:27]
	v_mfma_f32_16x16x32_bf16 v[12:15], v[114:117], v[98:101], v[12:15]
	ds_read_b128 v[64:67], v85
	ds_read_b128 v[90:93], v85 offset:1024
	ds_read_b128 v[94:97], v85 offset:2048
	ds_read_b128 v[98:101], v85 offset:3072
	ds_read_b128 v[102:105], v86
	ds_read_b128 v[106:109], v86 offset:1024
	ds_read_b128 v[110:113], v86 offset:2048
	ds_read_b128 v[114:117], v86 offset:3072
	s_waitcnt lgkmcnt(0)
	s_waitcnt vmcnt(4)
	s_waitcnt lgkmcnt(0)
	s_barrier
	v_mfma_f32_16x16x32_bf16 v[32:35], v[102:105], v[64:67], v[32:35]
	v_mfma_f32_16x16x32_bf16 v[36:39], v[106:109], v[64:67], v[36:39]
	v_mfma_f32_16x16x32_bf16 v[40:43], v[110:113], v[64:67], v[40:43]
	v_mfma_f32_16x16x32_bf16 v[0:3], v[114:117], v[64:67], v[0:3]
	v_lshl_add_u64 v[64:65], v[68:69], 0, s[26:27]
	v_lshl_add_u64 v[66:67], v[68:69], 0, s[28:29]
	v_lshl_add_u64 v[68:69], v[78:79], 0, s[28:29]
	v_lshl_add_u64 v[78:79], v[78:79], 0, s[26:27]
	global_load_lds_dwordx4 v[68:69], off
	s_mov_b32 m0, s43
	v_mfma_f32_16x16x32_bf16 v[28:31], v[102:105], v[90:93], v[28:31]
	global_load_lds_dwordx4 v[78:79], off
	s_mov_b32 m0, s44
	v_mfma_f32_16x16x32_bf16 v[44:47], v[106:109], v[90:93], v[44:47]
	global_load_lds_dwordx4 v[66:67], off
	s_mov_b32 m0, s45
	v_mfma_f32_16x16x32_bf16 v[48:51], v[110:113], v[90:93], v[48:51]
	global_load_lds_dwordx4 v[64:65], off
	v_or_b32_e32 v78, s30, v84
	v_mfma_f32_16x16x32_bf16 v[4:7], v[114:117], v[90:93], v[4:7]
	v_cmp_lt_i32_e32 vcc, s50, v78
	v_mfma_f32_16x16x32_bf16 v[52:55], v[102:105], v[94:97], v[52:55]
	v_mfma_f32_16x16x32_bf16 v[56:59], v[106:109], v[94:97], v[56:59]
	v_mfma_f32_16x16x32_bf16 v[60:63], v[110:113], v[94:97], v[60:63]
	v_mfma_f32_16x16x32_bf16 v[8:11], v[114:117], v[94:97], v[8:11]
	v_mfma_f32_16x16x32_bf16 v[16:19], v[102:105], v[98:101], v[16:19]
	v_mfma_f32_16x16x32_bf16 v[20:23], v[106:109], v[98:101], v[20:23]
	v_mfma_f32_16x16x32_bf16 v[24:27], v[110:113], v[98:101], v[24:27]
	v_mfma_f32_16x16x32_bf16 v[12:15], v[114:117], v[98:101], v[12:15]
	ds_read_b128 v[64:67], v87
	ds_read_b128 v[90:93], v87 offset:1024
	ds_read_b128 v[94:97], v87 offset:2048
	ds_read_b128 v[98:101], v87 offset:3072
	ds_read_b128 v[102:105], v88
	ds_read_b128 v[106:109], v88 offset:1024
	ds_read_b128 v[110:113], v88 offset:2048
	ds_read_b128 v[114:117], v88 offset:3072
	s_waitcnt lgkmcnt(0)
	s_waitcnt vmcnt(4)
	s_waitcnt lgkmcnt(0)
	s_barrier
	v_mfma_f32_16x16x32_bf16 v[32:35], v[102:105], v[64:67], v[32:35]
	v_mfma_f32_16x16x32_bf16 v[36:39], v[106:109], v[64:67], v[36:39]
	v_mfma_f32_16x16x32_bf16 v[40:43], v[110:113], v[64:67], v[40:43]
	v_mfma_f32_16x16x32_bf16 v[0:3], v[114:117], v[64:67], v[0:3]
	v_mfma_f32_16x16x32_bf16 v[28:31], v[102:105], v[90:93], v[28:31]
	v_mfma_f32_16x16x32_bf16 v[44:47], v[106:109], v[90:93], v[44:47]
	v_mfma_f32_16x16x32_bf16 v[48:51], v[110:113], v[90:93], v[48:51]
	v_mfma_f32_16x16x32_bf16 v[4:7], v[114:117], v[90:93], v[4:7]
	v_mfma_f32_16x16x32_bf16 v[52:55], v[102:105], v[94:97], v[52:55]
	v_mfma_f32_16x16x32_bf16 v[56:59], v[106:109], v[94:97], v[56:59]
	v_mfma_f32_16x16x32_bf16 v[60:63], v[110:113], v[94:97], v[60:63]
	v_mfma_f32_16x16x32_bf16 v[8:11], v[114:117], v[94:97], v[8:11]
	v_mfma_f32_16x16x32_bf16 v[16:19], v[102:105], v[98:101], v[16:19]
	v_mfma_f32_16x16x32_bf16 v[20:23], v[106:109], v[98:101], v[20:23]
	v_mfma_f32_16x16x32_bf16 v[24:27], v[110:113], v[98:101], v[24:27]
	v_mfma_f32_16x16x32_bf16 v[12:15], v[114:117], v[98:101], v[12:15]
	ds_read_b128 v[64:67], v82
	ds_read_b128 v[90:93], v82 offset:1024
	ds_read_b128 v[94:97], v82 offset:2048
	ds_read_b128 v[98:101], v82 offset:3072
	ds_read_b128 v[102:105], v83
	ds_read_b128 v[106:109], v83 offset:1024
	ds_read_b128 v[110:113], v83 offset:2048
	ds_read_b128 v[114:117], v83 offset:3072
	s_waitcnt lgkmcnt(0)
	s_waitcnt vmcnt(0)
	s_waitcnt lgkmcnt(0)
	s_barrier
	v_mfma_f32_16x16x32_bf16 v[32:35], v[102:105], v[64:67], v[32:35]
	v_mfma_f32_16x16x32_bf16 v[36:39], v[106:109], v[64:67], v[36:39]
	v_mfma_f32_16x16x32_bf16 v[40:43], v[110:113], v[64:67], v[40:43]
	v_mfma_f32_16x16x32_bf16 v[0:3], v[114:117], v[64:67], v[0:3]
	v_mfma_f32_16x16x32_bf16 v[118:121], v[102:105], v[90:93], v[28:31]
	v_mfma_f32_16x16x32_bf16 v[122:125], v[106:109], v[90:93], v[44:47]
	v_mfma_f32_16x16x32_bf16 v[48:51], v[110:113], v[90:93], v[48:51]
	v_mfma_f32_16x16x32_bf16 v[4:7], v[114:117], v[90:93], v[4:7]
	v_mfma_f32_16x16x32_bf16 v[52:55], v[102:105], v[94:97], v[52:55]
	v_mfma_f32_16x16x32_bf16 v[90:93], v[106:109], v[94:97], v[56:59]
	v_mfma_f32_16x16x32_bf16 v[126:129], v[110:113], v[94:97], v[60:63]
	v_mfma_f32_16x16x32_bf16 v[94:97], v[114:117], v[94:97], v[8:11]
	v_mfma_f32_16x16x32_bf16 v[16:19], v[102:105], v[98:101], v[16:19]
	v_mfma_f32_16x16x32_bf16 v[102:105], v[106:109], v[98:101], v[20:23]
	v_mfma_f32_16x16x32_bf16 v[106:109], v[110:113], v[98:101], v[24:27]
	v_mfma_f32_16x16x32_bf16 v[98:101], v[114:117], v[98:101], v[12:15]
	ds_read_b128 v[8:11], v85
	ds_read_b128 v[20:23], v85 offset:1024
	ds_read_b128 v[110:113], v85 offset:2048
	ds_read_b128 v[114:117], v85 offset:3072
	ds_read_b128 v[130:133], v86
	ds_read_b128 v[134:137], v86 offset:1024
	ds_read_b128 v[138:141], v86 offset:2048
	ds_read_b128 v[142:145], v86 offset:3072
	s_waitcnt lgkmcnt(0)
	s_waitcnt lgkmcnt(0)
	s_barrier
	v_mfma_f32_16x16x32_bf16 v[66:69], v[130:133], v[8:11], v[32:35]
	v_mfma_f32_16x16x32_bf16 v[44:47], v[134:137], v[8:11], v[36:39]
	v_mfma_f32_16x16x32_bf16 v[28:31], v[138:141], v[8:11], v[40:43]
	v_mfma_f32_16x16x32_bf16 v[12:15], v[142:145], v[8:11], v[0:3]
	v_mfma_f32_16x16x32_bf16 v[62:65], v[130:133], v[20:23], v[118:121]
	v_mfma_f32_16x16x32_bf16 v[40:43], v[134:137], v[20:23], v[122:125]
	v_mfma_f32_16x16x32_bf16 v[24:27], v[138:141], v[20:23], v[48:51]
	v_mfma_f32_16x16x32_bf16 v[8:11], v[142:145], v[20:23], v[4:7]
	v_mfma_f32_16x16x32_bf16 v[58:61], v[130:133], v[110:113], v[52:55]
	v_mfma_f32_16x16x32_bf16 v[36:39], v[134:137], v[110:113], v[90:93]
	v_mfma_f32_16x16x32_bf16 v[20:23], v[138:141], v[110:113], v[126:129]
	v_mfma_f32_16x16x32_bf16 v[4:7], v[142:145], v[110:113], v[94:97]
	v_mfma_f32_16x16x32_bf16 v[48:51], v[130:133], v[114:117], v[16:19]
	v_mfma_f32_16x16x32_bf16 v[32:35], v[134:137], v[114:117], v[102:105]
	v_mfma_f32_16x16x32_bf16 v[16:19], v[138:141], v[114:117], v[106:109]
	v_mfma_f32_16x16x32_bf16 v[0:3], v[142:145], v[114:117], v[98:101]
	s_setprio 0
	s_and_saveexec_b64 s[34:35], vcc
	s_xor_b64 s[34:35], exec, s[34:35]
	s_cbranch_execz .LBB0_636
	s_cmpk_gt_u32 s53, 0x3ff
	s_cbranch_scc1 .LBB0_649
	v_readlane_b32 s56, v241, 57
	v_mov_b32_e32 v79, v71
	v_readlane_b32 s68, v240, 5
	v_readlane_b32 s69, v240, 6
	v_readlane_b32 s57, v241, 58
	v_readlane_b32 s58, v241, 59
	v_lshl_add_u64 v[52:53], v[78:79], 2, s[68:69]
	global_load_dwordx4 v[54:57], v[52:53], off offset:-2048
	v_readlane_b32 s59, v241, 60
	v_readlane_b32 s60, v241, 61
	v_readlane_b32 s61, v241, 62
	v_readlane_b32 s62, v241, 63
	v_readlane_b32 s63, v240, 0
	v_readlane_b32 s64, v240, 1
	v_readlane_b32 s65, v240, 2
	v_readlane_b32 s66, v240, 3
	v_readlane_b32 s67, v240, 4
	v_readlane_b32 s70, v240, 7
	v_readlane_b32 s71, v240, 8
	s_mov_b64 s[30:31], -1
	s_waitcnt vmcnt(0)
	v_mov_b32_e32 v53, v56
	v_mov_b32_e32 v52, v54
	v_mov_b32_e32 v56, v55

.LBB0_1405:
	s_ashr_i32 s0, s2, 31
	s_lshr_b32 s0, s0, 27
	s_add_i32 s0, s2, s0
	s_ashr_i32 s0, s0, 5
	s_lshl_b32 s10, s0, 2
	s_and_b32 s11, s2, 3
	s_add_i32 s10, s10, s9
	s_or_b32 s10, s10, s11
	s_lshl_b32 s24, s10, 7
	s_lshl_b32 s0, s0, 10
	s_lshl_b32 s10, s2, 5
	s_sub_i32 s10, s10, s0
	v_add_u32_e32 v64, s24, v85
	s_and_b32 s25, s10, 0xffffff80
	s_movk_i32 s10, 0x300
	v_add_u32_e32 v0, s25, v85
	v_mad_i64_i32 v[2:3], s[10:11], v64, s10, v[72:73]
	s_mov_b32 m0, s14
	v_ashrrev_i32_e32 v1, 31, v0
	s_mov_b64 s[10:11], 0x3000
	v_lshlrev_b64 v[0:1], 11, v[0:1]
	s_setprio 2
	global_load_lds_dwordx4 v[2:3], off
	v_lshl_add_u64 v[4:5], v[2:3], 0, s[10:11]
	s_mov_b32 m0, s17
	v_lshl_add_u64 v[0:1], v[70:71], 0, v[0:1]
	global_load_lds_dwordx4 v[4:5], off
	s_mov_b32 m0, s18
	s_mov_b64 s[10:11], 0x8000
	global_load_lds_dwordx4 v[0:1], off
	v_lshl_add_u64 v[4:5], v[0:1], 0, s[10:11]
	s_mov_b32 m0, s19
	s_mov_b64 s[10:11], 0x3040
	global_load_lds_dwordx4 v[4:5], off
	v_lshl_add_u64 v[4:5], v[2:3], 0, 64
	s_mov_b32 m0, s20
	v_lshl_add_u64 v[2:3], v[2:3], 0, s[10:11]
	global_load_lds_dwordx4 v[4:5], off
	s_mov_b32 m0, s21
	s_mov_b64 s[10:11], 0x8040
	global_load_lds_dwordx4 v[2:3], off
	v_lshl_add_u64 v[2:3], v[0:1], 0, 64
	s_mov_b32 m0, s22
	v_lshl_add_u64 v[0:1], v[0:1], 0, s[10:11]
	global_load_lds_dwordx4 v[2:3], off
	s_mov_b32 m0, s23
	s_sub_i32 s0, s15, s0
	global_load_lds_dwordx4 v[0:1], off
	s_and_b32 s0, s0, 0xffffff80
	v_add_u32_e32 v0, s0, v85
	v_ashrrev_i32_e32 v1, 31, v0
	v_lshlrev_b64 v[0:1], 11, v[0:1]
	v_readlane_b32 s36, v241, 17
	v_lshl_add_u64 v[66:67], v[70:71], 0, v[0:1]
	s_mov_b64 s[10:11], 0
	s_mov_b64 s[12:13], 0
	s_mov_b32 s26, s1
	s_mov_b32 s28, 2
	s_mov_b32 s27, s1
	v_mov_b32_e32 v0, 0
	v_mov_b32_e32 v1, v69
	v_mov_b32_e32 v2, v69
	v_mov_b32_e32 v3, v69
	v_mov_b32_e32 v4, 0
	v_mov_b32_e32 v5, v69
	v_mov_b32_e32 v6, v69
	v_mov_b32_e32 v7, v69
	v_mov_b32_e32 v8, 0
	v_mov_b32_e32 v9, v69
	v_mov_b32_e32 v10, v69
	v_mov_b32_e32 v11, v69
	v_mov_b32_e32 v12, 0
	v_mov_b32_e32 v13, v69
	v_mov_b32_e32 v14, v69
	v_mov_b32_e32 v15, v69
	v_mov_b32_e32 v16, 0
	v_mov_b32_e32 v17, v69
	v_mov_b32_e32 v18, v69
	v_mov_b32_e32 v19, v69
	v_mov_b32_e32 v20, 0
	v_mov_b32_e32 v21, v69
	v_mov_b32_e32 v22, v69
	v_mov_b32_e32 v23, v69
	v_mov_b32_e32 v24, 0
	v_mov_b32_e32 v25, v69
	v_mov_b32_e32 v26, v69
	v_mov_b32_e32 v27, v69
	v_mov_b32_e32 v28, 0
	v_mov_b32_e32 v29, v69
	v_mov_b32_e32 v30, v69
	v_mov_b32_e32 v31, v69
	v_mov_b32_e32 v32, 0
	v_mov_b32_e32 v33, v69
	v_mov_b32_e32 v34, v69
	v_mov_b32_e32 v35, v69
	v_mov_b32_e32 v36, 0
	v_mov_b32_e32 v37, v69
	v_mov_b32_e32 v38, v69
	v_mov_b32_e32 v39, v69
	v_mov_b32_e32 v40, 0
	v_mov_b32_e32 v41, v69
	v_mov_b32_e32 v42, v69
	v_mov_b32_e32 v43, v69
	v_mov_b32_e32 v44, 0
	v_mov_b32_e32 v45, v69
	v_mov_b32_e32 v46, v69
	v_mov_b32_e32 v47, v69
	v_mov_b32_e32 v48, 0
	v_mov_b32_e32 v49, v69
	v_mov_b32_e32 v50, v69
	v_mov_b32_e32 v51, v69
	v_mov_b32_e32 v52, 0
	v_mov_b32_e32 v53, v69
	v_mov_b32_e32 v54, v69
	v_mov_b32_e32 v55, v69
	v_mov_b32_e32 v56, 0
	v_mov_b32_e32 v57, v69
	v_mov_b32_e32 v58, v69
	v_mov_b32_e32 v59, v69
	v_mov_b32_e32 v60, 0
	v_mov_b32_e32 v61, v69
	v_mov_b32_e32 v62, v69
	v_mov_b32_e32 v63, v69
	v_readlane_b32 s40, v241, 21
	v_readlane_b32 s41, v241, 22
	v_readlane_b32 s42, v241, 23
	v_readlane_b32 s43, v241, 24
	v_readlane_b32 s37, v241, 18
	v_readlane_b32 s38, v241, 19
	v_readlane_b32 s39, v241, 20
.LBB0_1406:
	s_cmp_lt_u32 s26, 10
	s_cselect_b32 s0, s41, s43
	v_mov_b32_e32 v79, s0
	s_movk_i32 s0, 0x180
	s_cselect_b32 s0, s0, 0x500
	v_mad_i64_i32 v[80:81], s[30:31], s0, v64, 0
	s_cselect_b32 s29, s40, s42
	s_cselect_b32 s30, 0, 0xfffffe80
	v_mov_b32_e32 v78, s29
	s_cselect_b32 s29, 0, -1
	s_add_u32 s30, s10, s30
	v_lshl_add_u64 v[78:79], v[80:81], 1, v[78:79]
	s_addc_u32 s31, s11, s29
	v_lshl_add_u64 v[78:79], s[30:31], 1, v[78:79]
	s_lshl_b32 s29, s28, 14
	s_waitcnt vmcnt(0)
	v_lshl_add_u64 v[82:83], v[78:79], 0, v[68:69]
	s_add_i32 s29, s14, s29
	s_lshl_b32 s0, s0, 5
	s_waitcnt lgkmcnt(0)
	s_barrier
	s_lshl_b32 s98, s27, 14
	v_add_u32_e32 v65, s98, v88
	v_or_b32_e32 v124, s98, v89
	ds_read_b128 v[78:81], v65
	ds_read_b128 v[92:95], v65 offset:1024
	ds_read_b128 v[96:99], v65 offset:2048
	ds_read_b128 v[100:103], v65 offset:3072
	ds_read_b128 v[104:107], v124
	ds_read_b128 v[108:111], v124 offset:1024
	ds_read_b128 v[112:115], v124 offset:2048
	ds_read_b128 v[116:119], v124 offset:3072
	v_lshl_add_u64 v[128:129], v[82:83], 0, s[4:5]
	s_mov_b32 m0, s29
	v_lshl_add_u64 v[120:121], v[82:83], 0, s[0:1]
	global_load_lds_dwordx4 v[128:129], off
	v_lshl_add_u64 v[128:129], v[120:121], 0, s[4:5]
	s_add_i32 m0, s29, 0x400
	v_lshl_add_u64 v[122:123], v[66:67], 0, s[12:13]
	global_load_lds_dwordx4 v[128:129], off
	s_add_i32 m0, s29, 0x2000
	v_lshl_add_u64 v[128:129], v[122:123], 0, s[4:5]
	s_lshl_b32 s0, s27, 14
	global_load_lds_dwordx4 v[128:129], off
	s_add_i32 m0, s29, 0x2400
	s_add_i32 s0, s27, 1
	s_cmp_lg_u32 s27, 3
	s_mov_b64 s[30:31], 0x8080
	s_cselect_b32 s27, s0, 0
	s_add_i32 s0, s28, 1
	v_lshl_add_u64 v[128:129], v[122:123], 0, s[30:31]
	s_cmp_lg_u32 s28, 3
	global_load_lds_dwordx4 v[128:129], off
	s_cselect_b32 s0, s0, 0
	s_waitcnt lgkmcnt(0)
	s_lshl_b32 s28, s0, 14
	s_add_i32 s30, s14, s28
	v_mfma_f32_16x16x32_bf16 v[60:63], v[104:107], v[78:81], v[60:63]
	v_mfma_f32_16x16x32_bf16 v[56:59], v[108:111], v[78:81], v[56:59]
	s_mov_b32 m0, s30
	s_mov_b64 s[28:29], 0x80c0
	s_add_i32 s26, s26, 2
	v_mfma_f32_16x16x32_bf16 v[52:55], v[112:115], v[78:81], v[52:55]
	v_mfma_f32_16x16x32_bf16 v[48:51], v[116:119], v[78:81], v[48:51]
	v_lshl_add_u64 v[78:79], v[82:83], 0, s[6:7]
	global_load_lds_dwordx4 v[78:79], off
	v_lshl_add_u64 v[78:79], v[120:121], 0, s[6:7]
	s_add_i32 m0, s30, 0x400
	v_mfma_f32_16x16x32_bf16 v[44:47], v[104:107], v[92:95], v[44:47]
	global_load_lds_dwordx4 v[78:79], off
	s_add_i32 m0, s30, 0x2000
	v_lshl_add_u64 v[78:79], v[122:123], 0, s[6:7]
	global_load_lds_dwordx4 v[78:79], off
	v_lshl_add_u64 v[78:79], v[122:123], 0, s[28:29]
	s_add_i32 m0, s30, 0x2400
	s_lshl_b32 s28, s27, 14
	global_load_lds_dwordx4 v[78:79], off
	v_add_u32_e32 v65, s28, v88
	v_or_b32_e32 v82, s28, v89
	s_add_i32 s28, s27, 1
	v_mfma_f32_16x16x32_bf16 v[40:43], v[108:111], v[92:95], v[40:43]
	s_cmp_lg_u32 s27, 3
	s_cselect_b32 s27, s28, 0
	s_add_i32 s28, s0, 1
	v_mfma_f32_16x16x32_bf16 v[36:39], v[112:115], v[92:95], v[36:39]
	s_cmp_lg_u32 s0, 3
	s_cselect_b32 s28, s28, 0
	s_add_u32 s12, s12, 0x80
	v_mfma_f32_16x16x32_bf16 v[32:35], v[116:119], v[92:95], v[32:35]
	s_addc_u32 s13, s13, 0
	s_add_u32 s10, s10, 64
	s_addc_u32 s11, s11, 0
	v_mfma_f32_16x16x32_bf16 v[28:31], v[104:107], v[96:99], v[28:31]
	s_cmpk_eq_i32 s12, 0x780
	v_mfma_f32_16x16x32_bf16 v[24:27], v[108:111], v[96:99], v[24:27]
	v_mfma_f32_16x16x32_bf16 v[20:23], v[112:115], v[96:99], v[20:23]
	v_mfma_f32_16x16x32_bf16 v[16:19], v[116:119], v[96:99], v[16:19]
	v_mfma_f32_16x16x32_bf16 v[12:15], v[104:107], v[100:103], v[12:15]
	v_mfma_f32_16x16x32_bf16 v[8:11], v[108:111], v[100:103], v[8:11]
	v_mfma_f32_16x16x32_bf16 v[4:7], v[112:115], v[100:103], v[4:7]
	v_mfma_f32_16x16x32_bf16 v[0:3], v[116:119], v[100:103], v[0:3]
	ds_read_b128 v[78:81], v65
	ds_read_b128 v[92:95], v65 offset:1024
	ds_read_b128 v[96:99], v65 offset:2048
	ds_read_b128 v[100:103], v65 offset:3072
	ds_read_b128 v[104:107], v82
	ds_read_b128 v[108:111], v82 offset:1024
	ds_read_b128 v[112:115], v82 offset:2048
	ds_read_b128 v[116:119], v82 offset:3072
	s_waitcnt lgkmcnt(0)
	s_nop 0
	v_mfma_f32_16x16x32_bf16 v[60:63], v[104:107], v[78:81], v[60:63]
	v_mfma_f32_16x16x32_bf16 v[56:59], v[108:111], v[78:81], v[56:59]
	v_mfma_f32_16x16x32_bf16 v[52:55], v[112:115], v[78:81], v[52:55]
	v_mfma_f32_16x16x32_bf16 v[48:51], v[116:119], v[78:81], v[48:51]
	v_mfma_f32_16x16x32_bf16 v[44:47], v[104:107], v[92:95], v[44:47]
	v_mfma_f32_16x16x32_bf16 v[40:43], v[108:111], v[92:95], v[40:43]
	v_mfma_f32_16x16x32_bf16 v[36:39], v[112:115], v[92:95], v[36:39]
	v_mfma_f32_16x16x32_bf16 v[32:35], v[116:119], v[92:95], v[32:35]
	v_mfma_f32_16x16x32_bf16 v[28:31], v[104:107], v[96:99], v[28:31]
	v_mfma_f32_16x16x32_bf16 v[24:27], v[108:111], v[96:99], v[24:27]
	v_mfma_f32_16x16x32_bf16 v[20:23], v[112:115], v[96:99], v[20:23]
	v_mfma_f32_16x16x32_bf16 v[16:19], v[116:119], v[96:99], v[16:19]
	v_mfma_f32_16x16x32_bf16 v[12:15], v[104:107], v[100:103], v[12:15]
	v_mfma_f32_16x16x32_bf16 v[8:11], v[108:111], v[100:103], v[8:11]
	v_mfma_f32_16x16x32_bf16 v[4:7], v[112:115], v[100:103], v[4:7]
	v_mfma_f32_16x16x32_bf16 v[0:3], v[116:119], v[100:103], v[0:3]
	s_cbranch_scc0 .LBB0_1406
	s_waitcnt vmcnt(4)
	s_waitcnt lgkmcnt(0)
	s_barrier
	ds_read_b128 v[64:67], v88 offset:32768
	ds_read_b128 v[78:81], v88 offset:33792
	ds_read_b128 v[92:95], v88 offset:34816
	ds_read_b128 v[96:99], v88 offset:35840
	ds_read_b128 v[100:103], v89 offset:32768
	ds_read_b128 v[104:107], v89 offset:33792
	ds_read_b128 v[108:111], v89 offset:34816
	ds_read_b128 v[112:115], v89 offset:35840
	s_waitcnt lgkmcnt(0)
	s_waitcnt vmcnt(0)
	s_waitcnt lgkmcnt(0)
	s_barrier
	v_mfma_f32_16x16x32_bf16 v[56:59], v[104:107], v[64:67], v[56:59]
	s_movk_i32 s0, 0xfff
	v_readlane_b32 s36, v241, 1
	v_mfma_f32_16x16x32_bf16 v[40:43], v[104:107], v[78:81], v[40:43]
	v_readlane_b32 s44, v241, 9
	v_readlane_b32 s45, v241, 10
	s_add_i32 s2, s2, s3
	v_mfma_f32_16x16x32_bf16 v[24:27], v[104:107], v[92:95], v[24:27]
	s_add_i32 s15, s15, s16
	s_cmpk_gt_i32 s2, 0x9f
	v_readlane_b32 s37, v241, 2
	v_mfma_f32_16x16x32_bf16 v[52:55], v[108:111], v[64:67], v[52:55]
	v_readlane_b32 s38, v241, 3
	v_readlane_b32 s39, v241, 4
	v_readlane_b32 s40, v241, 5
	v_mfma_f32_16x16x32_bf16 v[36:39], v[108:111], v[78:81], v[36:39]
	v_readlane_b32 s41, v241, 6
	v_readlane_b32 s42, v241, 7
	v_readlane_b32 s43, v241, 8
	v_mfma_f32_16x16x32_bf16 v[20:23], v[108:111], v[92:95], v[20:23]
	v_readlane_b32 s46, v241, 11
	v_readlane_b32 s47, v241, 12
	v_readlane_b32 s48, v241, 13
	v_mfma_f32_16x16x32_bf16 v[60:63], v[100:103], v[64:67], v[60:63]
	v_readlane_b32 s49, v241, 14
	v_readlane_b32 s50, v241, 15
	v_readlane_b32 s51, v241, 16
	v_mfma_f32_16x16x32_bf16 v[48:51], v[112:115], v[64:67], v[48:51]
	v_mfma_f32_16x16x32_bf16 v[44:47], v[100:103], v[78:81], v[44:47]
	v_mfma_f32_16x16x32_bf16 v[32:35], v[112:115], v[78:81], v[32:35]
	v_mfma_f32_16x16x32_bf16 v[28:31], v[100:103], v[92:95], v[28:31]
	v_mfma_f32_16x16x32_bf16 v[16:19], v[112:115], v[92:95], v[16:19]
	v_mfma_f32_16x16x32_bf16 v[12:15], v[100:103], v[96:99], v[12:15]
	v_mfma_f32_16x16x32_bf16 v[8:11], v[104:107], v[96:99], v[8:11]
	v_mfma_f32_16x16x32_bf16 v[4:7], v[108:111], v[96:99], v[4:7]
	v_mfma_f32_16x16x32_bf16 v[0:3], v[112:115], v[96:99], v[0:3]
	ds_read_b128 v[64:67], v88 offset:49152
	ds_read_b128 v[78:81], v88 offset:50176
	ds_read_b128 v[92:95], v88 offset:51200
	ds_read_b128 v[96:99], v88 offset:52224
	ds_read_b128 v[100:103], v89 offset:49152
	ds_read_b128 v[104:107], v89 offset:50176
	ds_read_b128 v[108:111], v89 offset:51200
	ds_read_b128 v[112:115], v89 offset:52224
	s_waitcnt lgkmcnt(0)
	s_waitcnt lgkmcnt(0)
	s_barrier
	v_mfma_f32_16x16x32_bf16 v[120:123], v[104:107], v[64:67], v[56:59]
	v_mfma_f32_16x16x32_bf16 v[56:59], v[104:107], v[78:81], v[40:43]
	v_mfma_f32_16x16x32_bf16 v[40:43], v[104:107], v[92:95], v[24:27]
	s_nop 2
	v_add_u32_e32 v24, s24, v86
	v_mfma_f32_16x16x32_bf16 v[124:127], v[108:111], v[64:67], v[52:55]
	v_cmp_lt_i32_e32 vcc, s0, v24
	s_movk_i32 s0, 0x6000
	v_mfma_f32_16x16x32_bf16 v[52:55], v[108:111], v[78:81], v[36:39]
	v_mfma_f32_16x16x32_bf16 v[36:39], v[108:111], v[92:95], v[20:23]
	s_nop 2
	v_add_u32_e32 v21, 0xfffff000, v24
	v_lshrrev_b32_e32 v21, 12, v21
	v_add_u32_e32 v21, 1, v21
	v_or_b32_e32 v20, s25, v87
	v_cndmask_b32_e32 v21, 0, v21, vcc
	v_mad_u64_u32 v[22:23], s[10:11], v21, s0, v[74:75]
	v_ashrrev_i32_e32 v21, 31, v20
	v_mfma_f32_16x16x32_bf16 v[116:119], v[100:103], v[64:67], v[60:63]
	s_mov_b64 s[10:11], 0x2000
	s_movk_i32 s0, 0x2000
	v_mfma_f32_16x16x32_bf16 v[64:67], v[112:115], v[64:67], v[48:51]
	v_mfma_f32_16x16x32_bf16 v[60:63], v[100:103], v[78:81], v[44:47]
	v_mfma_f32_16x16x32_bf16 v[48:51], v[112:115], v[78:81], v[32:35]
	v_lshlrev_b64 v[78:79], 2, v[20:21]
	v_lshl_add_u64 v[20:21], v[22:23], 0, v[78:79]
	v_lshl_add_u64 v[20:21], v[20:21], 0, v[76:77]
	v_lshl_add_u64 v[22:23], v[20:21], 0, s[10:11]
	v_add_co_u32_e32 v20, vcc, s0, v20
	v_mfma_f32_16x16x32_bf16 v[44:47], v[100:103], v[92:95], v[28:31]
	s_nop 0
	v_addc_co_u32_e32 v21, vcc, 0, v21, vcc
	v_mfma_f32_16x16x32_bf16 v[16:19], v[112:115], v[92:95], v[16:19]
	v_or_b32_e32 v92, v24, v84
	v_or_b32_e32 v82, 32, v92
	v_or_b32_e32 v80, 48, v92
	v_mfma_f32_16x16x32_bf16 v[12:15], v[100:103], v[96:99], v[12:15]
	global_load_dwordx4 v[32:35], v[20:21], off
	global_load_dwordx4 v[28:31], v[22:23], off offset:64
	global_load_dwordx4 v[24:27], v[22:23], off offset:128
	s_nop 0
	global_load_dwordx4 v[20:23], v[22:23], off offset:192
	v_mfma_f32_16x16x32_bf16 v[8:11], v[104:107], v[96:99], v[8:11]
	v_mfma_f32_16x16x32_bf16 v[4:7], v[108:111], v[96:99], v[4:7]
	v_mfma_f32_16x16x32_bf16 v[0:3], v[112:115], v[96:99], v[0:3]
	s_setprio 0
	v_or_b32_e32 v96, 16, v92
	s_nop 0
	v_mov_b32_e32 v194, v92
	v_ashrrev_i32_e32 v195, 31, v92
	v_lshlrev_b64 v[194:195], 12, v[194:195]
	v_lshl_add_u64 v[194:195], s[44:45], 0, v[194:195]
	v_lshl_add_u64 v[194:195], v[194:195], 0, v[78:79]
	v_lshl_add_u64 v[194:195], v[194:195], 0, v[76:77]
	v_mov_b32_e32 v196, v96
	v_ashrrev_i32_e32 v197, 31, v96
	v_lshlrev_b64 v[196:197], 12, v[196:197]
	v_lshl_add_u64 v[196:197], s[44:45], 0, v[196:197]
	v_lshl_add_u64 v[196:197], v[196:197], 0, v[78:79]
	v_lshl_add_u64 v[196:197], v[196:197], 0, v[76:77]
	v_mov_b32_e32 v198, v82
	v_ashrrev_i32_e32 v199, 31, v82
	v_lshlrev_b64 v[198:199], 12, v[198:199]
	v_lshl_add_u64 v[198:199], s[44:45], 0, v[198:199]
	v_lshl_add_u64 v[198:199], v[198:199], 0, v[78:79]
	v_lshl_add_u64 v[198:199], v[198:199], 0, v[76:77]
	v_mov_b32_e32 v200, v80
	v_ashrrev_i32_e32 v201, 31, v80
	v_lshlrev_b64 v[200:201], 12, v[200:201]
	v_lshl_add_u64 v[200:201], s[44:45], 0, v[200:201]
	v_lshl_add_u64 v[200:201], v[200:201], 0, v[78:79]
	v_lshl_add_u64 v[200:201], v[200:201], 0, v[76:77]
	global_load_dwordx4 v[130:133], v[194:195], off
	global_load_dwordx4 v[134:137], v[194:195], off offset:64
	global_load_dwordx4 v[138:141], v[194:195], off offset:128
	global_load_dwordx4 v[142:145], v[194:195], off offset:192
	global_load_dwordx4 v[146:149], v[196:197], off
	global_load_dwordx4 v[150:153], v[196:197], off offset:64
	global_load_dwordx4 v[154:157], v[196:197], off offset:128
	global_load_dwordx4 v[158:161], v[196:197], off offset:192
	global_load_dwordx4 v[162:165], v[198:199], off
	global_load_dwordx4 v[166:169], v[198:199], off offset:64
	global_load_dwordx4 v[170:173], v[198:199], off offset:128
	global_load_dwordx4 v[174:177], v[198:199], off offset:192
	global_load_dwordx4 v[178:181], v[200:201], off
	global_load_dwordx4 v[182:185], v[200:201], off offset:64
	global_load_dwordx4 v[186:189], v[200:201], off offset:128
	global_load_dwordx4 v[190:193], v[200:201], off offset:192
	s_waitcnt vmcnt(15)
	v_pk_mul_f32 v[130:131], v[130:131], s[8:9] op_sel_hi:[1,0]
	v_pk_mul_f32 v[132:133], v[132:133], s[8:9] op_sel_hi:[1,0]
	v_pk_fma_f32 v[130:131], v[116:117], v[32:33], v[130:131]
	v_pk_fma_f32 v[132:133], v[118:119], v[34:35], v[132:133]
	global_store_dwordx4 v[194:195], v[130:133], off
	s_waitcnt vmcnt(15)
	v_pk_mul_f32 v[134:135], v[134:135], s[8:9] op_sel_hi:[1,0]
	v_pk_mul_f32 v[136:137], v[136:137], s[8:9] op_sel_hi:[1,0]
	v_pk_fma_f32 v[134:135], v[120:121], v[28:29], v[134:135]
	v_pk_fma_f32 v[136:137], v[122:123], v[30:31], v[136:137]
	global_store_dwordx4 v[194:195], v[134:137], off offset:64
	s_waitcnt vmcnt(15)
	v_pk_mul_f32 v[138:139], v[138:139], s[8:9] op_sel_hi:[1,0]
	v_pk_mul_f32 v[140:141], v[140:141], s[8:9] op_sel_hi:[1,0]
	v_pk_fma_f32 v[138:139], v[124:125], v[24:25], v[138:139]
	v_pk_fma_f32 v[140:141], v[126:127], v[26:27], v[140:141]
	global_store_dwordx4 v[194:195], v[138:141], off offset:128
	s_waitcnt vmcnt(15)
	v_pk_mul_f32 v[142:143], v[142:143], s[8:9] op_sel_hi:[1,0]
	v_pk_fma_f32 v[64:65], v[64:65], v[20:21], v[142:143]
	v_pk_mul_f32 v[142:143], v[144:145], s[8:9] op_sel_hi:[1,0]
	v_pk_fma_f32 v[66:67], v[66:67], v[22:23], v[142:143]
	global_store_dwordx4 v[194:195], v[64:67], off offset:192
	s_waitcnt vmcnt(15)
	v_pk_mul_f32 v[146:147], v[146:147], s[8:9] op_sel_hi:[1,0]
	v_pk_fma_f32 v[60:61], v[60:61], v[32:33], v[146:147]
	v_pk_mul_f32 v[146:147], v[148:149], s[8:9] op_sel_hi:[1,0]
	v_pk_fma_f32 v[62:63], v[62:63], v[34:35], v[146:147]
	global_store_dwordx4 v[196:197], v[60:63], off
	s_waitcnt vmcnt(15)
	v_pk_mul_f32 v[150:151], v[150:151], s[8:9] op_sel_hi:[1,0]
	v_pk_fma_f32 v[56:57], v[56:57], v[28:29], v[150:151]
	v_pk_mul_f32 v[150:151], v[152:153], s[8:9] op_sel_hi:[1,0]
	v_pk_fma_f32 v[58:59], v[58:59], v[30:31], v[150:151]
	global_store_dwordx4 v[196:197], v[56:59], off offset:64
	s_waitcnt vmcnt(15)
	v_pk_mul_f32 v[154:155], v[154:155], s[8:9] op_sel_hi:[1,0]
	v_pk_fma_f32 v[52:53], v[52:53], v[24:25], v[154:155]
	v_pk_mul_f32 v[154:155], v[156:157], s[8:9] op_sel_hi:[1,0]
	v_pk_fma_f32 v[54:55], v[54:55], v[26:27], v[154:155]
	global_store_dwordx4 v[196:197], v[52:55], off offset:128
	s_waitcnt vmcnt(15)
	v_pk_mul_f32 v[158:159], v[158:159], s[8:9] op_sel_hi:[1,0]
	v_pk_fma_f32 v[48:49], v[48:49], v[20:21], v[158:159]
	v_pk_mul_f32 v[158:159], v[160:161], s[8:9] op_sel_hi:[1,0]
	v_pk_fma_f32 v[50:51], v[50:51], v[22:23], v[158:159]
	global_store_dwordx4 v[196:197], v[48:51], off offset:192
	s_waitcnt vmcnt(15)
	v_pk_mul_f32 v[162:163], v[162:163], s[8:9] op_sel_hi:[1,0]
	v_pk_fma_f32 v[44:45], v[44:45], v[32:33], v[162:163]
	v_pk_mul_f32 v[162:163], v[164:165], s[8:9] op_sel_hi:[1,0]
	v_pk_fma_f32 v[46:47], v[46:47], v[34:35], v[162:163]
	global_store_dwordx4 v[198:199], v[44:47], off
	s_waitcnt vmcnt(15)
	v_pk_mul_f32 v[166:167], v[166:167], s[8:9] op_sel_hi:[1,0]
	v_pk_fma_f32 v[40:41], v[40:41], v[28:29], v[166:167]
	v_pk_mul_f32 v[166:167], v[168:169], s[8:9] op_sel_hi:[1,0]
	v_pk_fma_f32 v[42:43], v[42:43], v[30:31], v[166:167]
	global_store_dwordx4 v[198:199], v[40:43], off offset:64
	s_waitcnt vmcnt(15)
	v_pk_mul_f32 v[170:171], v[170:171], s[8:9] op_sel_hi:[1,0]
	v_pk_fma_f32 v[36:37], v[36:37], v[24:25], v[170:171]
	v_pk_mul_f32 v[170:171], v[172:173], s[8:9] op_sel_hi:[1,0]
	v_pk_fma_f32 v[38:39], v[38:39], v[26:27], v[170:171]
	global_store_dwordx4 v[198:199], v[36:39], off offset:128
	s_waitcnt vmcnt(15)
	v_pk_mul_f32 v[174:175], v[174:175], s[8:9] op_sel_hi:[1,0]
	v_pk_fma_f32 v[16:17], v[16:17], v[20:21], v[174:175]
	v_pk_mul_f32 v[174:175], v[176:177], s[8:9] op_sel_hi:[1,0]
	v_pk_fma_f32 v[18:19], v[18:19], v[22:23], v[174:175]
	global_store_dwordx4 v[198:199], v[16:19], off offset:192
	s_waitcnt vmcnt(15)
	v_pk_mul_f32 v[178:179], v[178:179], s[8:9] op_sel_hi:[1,0]
	v_pk_fma_f32 v[12:13], v[12:13], v[32:33], v[178:179]
	v_pk_mul_f32 v[178:179], v[180:181], s[8:9] op_sel_hi:[1,0]
	v_pk_fma_f32 v[14:15], v[14:15], v[34:35], v[178:179]
	global_store_dwordx4 v[200:201], v[12:15], off
	s_waitcnt vmcnt(15)
	v_pk_mul_f32 v[182:183], v[182:183], s[8:9] op_sel_hi:[1,0]
	v_pk_fma_f32 v[8:9], v[8:9], v[28:29], v[182:183]
	v_pk_mul_f32 v[182:183], v[184:185], s[8:9] op_sel_hi:[1,0]
	v_pk_fma_f32 v[10:11], v[10:11], v[30:31], v[182:183]
	global_store_dwordx4 v[200:201], v[8:11], off offset:64
	s_waitcnt vmcnt(15)
	v_pk_mul_f32 v[186:187], v[186:187], s[8:9] op_sel_hi:[1,0]
	v_pk_fma_f32 v[4:5], v[4:5], v[24:25], v[186:187]
	v_pk_mul_f32 v[186:187], v[188:189], s[8:9] op_sel_hi:[1,0]
	v_pk_fma_f32 v[6:7], v[6:7], v[26:27], v[186:187]
	global_store_dwordx4 v[200:201], v[4:7], off offset:128
	s_waitcnt vmcnt(15)
	v_pk_mul_f32 v[190:191], v[190:191], s[8:9] op_sel_hi:[1,0]
	v_pk_fma_f32 v[0:1], v[0:1], v[20:21], v[190:191]
	v_pk_mul_f32 v[190:191], v[192:193], s[8:9] op_sel_hi:[1,0]
	v_pk_fma_f32 v[2:3], v[2:3], v[22:23], v[190:191]
	global_store_dwordx4 v[200:201], v[0:3], off offset:192
	s_cbranch_scc0 .LBB0_1405

.LBB0_1519:
	s_mul_hi_i32 s14, s2, 0x2e8ba2e9
	s_lshr_b32 s15, s14, 31
	s_ashr_i32 s14, s14, 4
	s_add_i32 s37, s14, s15
	s_lshl_b32 s35, s37, 1
	s_and_b32 s15, s2, 1
	s_add_i32 s38, s35, s16
	s_or_b32 s15, s38, s15
	s_lshl_b32 s35, s15, 8
	s_mul_i32 s14, s37, 0xffffffa8
	v_add_u32_e32 v0, s35, v142
	s_add_i32 s14, s14, s2
	v_ashrrev_i32_e32 v1, 31, v0
	v_lshlrev_b64 v[0:1], 11, v[0:1]
	s_lshl_b32 s14, s14, 6
	s_mov_b32 m0, s17
	v_lshl_add_u64 v[0:1], v[130:131], 0, v[0:1]
	s_and_b32 s36, s14, 0xffffff80
	v_add_u32_e32 v2, s36, v143
	s_setprio 2
	global_load_lds_dwordx4 v[0:1], off
	v_lshl_add_u64 v[4:5], v[0:1], 0, s[6:7]
	s_mov_b32 m0, s21
	s_mov_b64 s[14:15], 0x10000
	v_ashrrev_i32_e32 v3, 31, v2
	global_load_lds_dwordx4 v[4:5], off
	v_lshl_add_u64 v[4:5], v[0:1], 0, s[14:15]
	s_mov_b32 m0, s22
	s_mov_b64 s[14:15], 0x18000
	v_lshlrev_b64 v[2:3], 11, v[2:3]
	global_load_lds_dwordx4 v[4:5], off
	v_lshl_add_u64 v[4:5], v[0:1], 0, s[14:15]
	s_mov_b32 m0, s23
	v_lshl_add_u64 v[2:3], v[132:133], 0, v[2:3]
	global_load_lds_dwordx4 v[4:5], off
	s_mov_b32 m0, s24
	v_lshl_add_u64 v[4:5], v[2:3], 0, s[6:7]
	global_load_lds_dwordx4 v[2:3], off
	s_mov_b32 m0, s25
	s_mov_b64 s[14:15], 0x10040
	global_load_lds_dwordx4 v[4:5], off
	v_lshl_add_u64 v[4:5], v[0:1], 0, 64
	s_mov_b32 m0, s26
	s_mulk_i32 s37, 0x1600
	global_load_lds_dwordx4 v[4:5], off
	v_lshl_add_u64 v[4:5], v[0:1], 0, s[8:9]
	s_mov_b32 m0, s27
	v_cndmask_b32_e64 v6, 0, 1, s[0:1]
	global_load_lds_dwordx4 v[4:5], off
	v_lshl_add_u64 v[4:5], v[0:1], 0, s[14:15]
	s_mov_b32 m0, s28
	s_mov_b64 s[14:15], 0x18040
	global_load_lds_dwordx4 v[4:5], off
	v_lshl_add_u64 v[0:1], v[0:1], 0, s[14:15]
	s_mov_b32 m0, s29
	s_sub_i32 s14, s19, s37
	global_load_lds_dwordx4 v[0:1], off
	v_lshl_add_u64 v[0:1], v[2:3], 0, 64
	s_mov_b32 m0, s30
	s_and_b32 s14, s14, 0xffffff80
	global_load_lds_dwordx4 v[0:1], off
	v_lshl_add_u64 v[0:1], v[2:3], 0, s[8:9]
	s_mov_b32 m0, s31
	s_mov_b32 s37, 2
	global_load_lds_dwordx4 v[0:1], off
	v_add_u32_e32 v0, s14, v143
	v_ashrrev_i32_e32 v1, 31, v0
	v_lshlrev_b64 v[0:1], 11, v[0:1]
	v_lshl_add_u64 v[134:135], v[132:133], 0, v[0:1]
	v_add_u32_e32 v0, s38, v6
	v_lshl_add_u32 v0, v0, 8, v142
	v_ashrrev_i32_e32 v1, 31, v0
	v_lshlrev_b64 v[0:1], 11, v[0:1]
	v_lshl_add_u64 v[136:137], v[130:131], 0, v[0:1]
	s_mov_b64 s[14:15], 0
	s_mov_b32 s38, 0
	v_mov_b32_e32 v0, 0
	v_mov_b32_e32 v1, v129
	v_mov_b32_e32 v2, v129
	v_mov_b32_e32 v3, v129
	v_mov_b32_e32 v4, 0
	v_mov_b32_e32 v5, v129
	v_mov_b32_e32 v6, v129
	v_mov_b32_e32 v7, v129
	v_mov_b32_e32 v8, 0
	v_mov_b32_e32 v9, v129
	v_mov_b32_e32 v10, v129
	v_mov_b32_e32 v11, v129
	v_mov_b32_e32 v12, 0
	v_mov_b32_e32 v13, v129
	v_mov_b32_e32 v14, v129
	v_mov_b32_e32 v15, v129
	v_mov_b32_e32 v16, 0
	v_mov_b32_e32 v17, v129
	v_mov_b32_e32 v18, v129
	v_mov_b32_e32 v19, v129
	v_mov_b32_e32 v20, 0
	v_mov_b32_e32 v21, v129
	v_mov_b32_e32 v22, v129
	v_mov_b32_e32 v23, v129
	v_mov_b32_e32 v24, 0
	v_mov_b32_e32 v25, v129
	v_mov_b32_e32 v26, v129
	v_mov_b32_e32 v27, v129
	v_mov_b32_e32 v28, 0
	v_mov_b32_e32 v29, v129
	v_mov_b32_e32 v30, v129
	v_mov_b32_e32 v31, v129
	v_mov_b32_e32 v32, 0
	v_mov_b32_e32 v33, v129
	v_mov_b32_e32 v34, v129
	v_mov_b32_e32 v35, v129
	v_mov_b32_e32 v36, 0
	v_mov_b32_e32 v37, v129
	v_mov_b32_e32 v38, v129
	v_mov_b32_e32 v39, v129
	v_mov_b32_e32 v44, 0
	v_mov_b32_e32 v45, v129
	v_mov_b32_e32 v46, v129
	v_mov_b32_e32 v47, v129
	v_mov_b32_e32 v52, 0
	v_mov_b32_e32 v53, v129
	v_mov_b32_e32 v54, v129
	v_mov_b32_e32 v55, v129
	v_mov_b32_e32 v60, 0
	v_mov_b32_e32 v61, v129
	v_mov_b32_e32 v62, v129
	v_mov_b32_e32 v63, v129
	v_mov_b32_e32 v68, 0
	v_mov_b32_e32 v69, v129
	v_mov_b32_e32 v70, v129
	v_mov_b32_e32 v71, v129
	v_mov_b32_e32 v76, 0
	v_mov_b32_e32 v77, v129
	v_mov_b32_e32 v78, v129
	v_mov_b32_e32 v79, v129
	v_mov_b32_e32 v84, 0
	v_mov_b32_e32 v85, v129
	v_mov_b32_e32 v86, v129
	v_mov_b32_e32 v87, v129
	v_mov_b32_e32 v40, 0
	v_mov_b32_e32 v41, v129
	v_mov_b32_e32 v42, v129
	v_mov_b32_e32 v43, v129
	v_mov_b32_e32 v48, 0
	v_mov_b32_e32 v49, v129
	v_mov_b32_e32 v50, v129
	v_mov_b32_e32 v51, v129
	v_mov_b32_e32 v56, 0
	v_mov_b32_e32 v57, v129
	v_mov_b32_e32 v58, v129
	v_mov_b32_e32 v59, v129
	v_mov_b32_e32 v64, 0
	v_mov_b32_e32 v65, v129
	v_mov_b32_e32 v66, v129
	v_mov_b32_e32 v67, v129
	v_mov_b32_e32 v72, 0
	v_mov_b32_e32 v73, v129
	v_mov_b32_e32 v74, v129
	v_mov_b32_e32 v75, v129
	v_mov_b32_e32 v80, 0
	v_mov_b32_e32 v81, v129
	v_mov_b32_e32 v82, v129
	v_mov_b32_e32 v83, v129
	v_mov_b32_e32 v88, 0
	v_mov_b32_e32 v89, v129
	v_mov_b32_e32 v90, v129
	v_mov_b32_e32 v91, v129
	v_mov_b32_e32 v92, 0
	v_mov_b32_e32 v93, v129
	v_mov_b32_e32 v94, v129
	v_mov_b32_e32 v95, v129
	v_mov_b32_e32 v96, 0
	v_mov_b32_e32 v97, v129
	v_mov_b32_e32 v98, v129
	v_mov_b32_e32 v99, v129
	v_mov_b32_e32 v100, 0
	v_mov_b32_e32 v101, v129
	v_mov_b32_e32 v102, v129
	v_mov_b32_e32 v103, v129
	v_mov_b32_e32 v104, 0
	v_mov_b32_e32 v105, v129
	v_mov_b32_e32 v106, v129
	v_mov_b32_e32 v107, v129
	v_mov_b32_e32 v108, 0
	v_mov_b32_e32 v109, v129
	v_mov_b32_e32 v110, v129
	v_mov_b32_e32 v111, v129
	v_mov_b32_e32 v112, 0
	v_mov_b32_e32 v113, v129
	v_mov_b32_e32 v114, v129
	v_mov_b32_e32 v115, v129
	v_mov_b32_e32 v116, 0
	v_mov_b32_e32 v117, v129
	v_mov_b32_e32 v118, v129
	v_mov_b32_e32 v119, v129
	v_mov_b32_e32 v120, 0
	v_mov_b32_e32 v121, v129
	v_mov_b32_e32 v122, v129
	v_mov_b32_e32 v123, v129
	v_mov_b32_e32 v124, 0
	v_mov_b32_e32 v125, v129
	v_mov_b32_e32 v126, v129
	v_mov_b32_e32 v127, v129
.LBB0_1520:
	s_mul_i32 s39, s37, 0x6000
	s_waitcnt vmcnt(6)
	s_add_i32 s39, s17, s39
	s_mul_i32 s98, s38, 0x6000
	v_lshl_add_u64 v[196:197], v[136:137], 0, s[14:15]
	v_lshl_add_u64 v[198:199], v[134:135], 0, s[14:15]
	s_add_i32 s99, s39, s18
	s_waitcnt lgkmcnt(0)
	s_barrier
	v_add_u32_e32 v178, s98, v139
	v_add_u32_e32 v179, s98, v141
	ds_read_b128 v[162:165], v179
	ds_read_b128 v[146:149], v178
	ds_read_b128 v[166:169], v179 offset:1024
	ds_read_b128 v[170:173], v179 offset:2048
	ds_read_b128 v[174:177], v179 offset:3072
	ds_read_b128 v[150:153], v178 offset:1024
	ds_read_b128 v[154:157], v178 offset:2048
	ds_read_b128 v[158:161], v178 offset:3072
	ds_read_b128 v[180:183], v178 offset:4096
	ds_read_b128 v[184:187], v178 offset:5120
	ds_read_b128 v[188:191], v178 offset:6144
	ds_read_b128 v[192:195], v178 offset:7168
	v_lshl_add_u64 v[200:201], v[196:197], 0, s[10:11]
	s_mov_b32 m0, s39
	s_waitcnt lgkmcnt(10)
	v_mfma_f32_16x16x32_bf16 v[84:87], v[146:149], v[162:165], v[84:87]
	global_load_lds_dwordx4 v[200:201], off
	s_waitcnt lgkmcnt(9)
	v_mfma_f32_16x16x32_bf16 v[76:79], v[146:149], v[166:169], v[76:79]
	v_lshl_add_u64 v[200:201], v[196:197], 0, s[12:13]
	s_add_i32 m0, s39, 0x400
	s_waitcnt lgkmcnt(8)
	v_mfma_f32_16x16x32_bf16 v[68:71], v[146:149], v[170:173], v[68:71]
	global_load_lds_dwordx4 v[200:201], off
	s_waitcnt lgkmcnt(7)
	v_mfma_f32_16x16x32_bf16 v[60:63], v[146:149], v[174:177], v[60:63]
	s_mov_b64 s[100:101], 0x10080
	v_lshl_add_u64 v[200:201], v[196:197], 0, s[100:101]
	s_add_i32 m0, s39, 0x800
	s_waitcnt lgkmcnt(6)
	v_mfma_f32_16x16x32_bf16 v[52:55], v[150:153], v[162:165], v[52:55]
	global_load_lds_dwordx4 v[200:201], off
	v_mfma_f32_16x16x32_bf16 v[44:47], v[150:153], v[166:169], v[44:47]
	v_mfma_f32_16x16x32_bf16 v[36:39], v[150:153], v[170:173], v[36:39]
	s_mov_b64 s[100:101], 0x18080
	v_lshl_add_u64 v[200:201], v[196:197], 0, s[100:101]
	s_add_i32 m0, s39, 0xc00
	v_mfma_f32_16x16x32_bf16 v[32:35], v[150:153], v[174:177], v[32:35]
	global_load_lds_dwordx4 v[200:201], off
	s_waitcnt lgkmcnt(5)
	v_mfma_f32_16x16x32_bf16 v[28:31], v[154:157], v[162:165], v[28:31]
	v_lshl_add_u64 v[200:201], v[198:199], 0, s[10:11]
	s_add_i32 m0, s99, 0x4000
	v_mfma_f32_16x16x32_bf16 v[24:27], v[154:157], v[166:169], v[24:27]
	global_load_lds_dwordx4 v[200:201], off
	v_mfma_f32_16x16x32_bf16 v[20:23], v[154:157], v[170:173], v[20:23]
	v_lshl_add_u64 v[200:201], v[198:199], 0, s[12:13]
	s_add_i32 m0, s99, 0x4400
	v_mfma_f32_16x16x32_bf16 v[16:19], v[154:157], v[174:177], v[16:19]
	global_load_lds_dwordx4 v[200:201], off
	s_waitcnt lgkmcnt(4)
	v_mfma_f32_16x16x32_bf16 v[12:15], v[158:161], v[162:165], v[12:15]
	v_mfma_f32_16x16x32_bf16 v[8:11], v[158:161], v[166:169], v[8:11]
	v_mfma_f32_16x16x32_bf16 v[4:7], v[158:161], v[170:173], v[4:7]
	v_mfma_f32_16x16x32_bf16 v[0:3], v[158:161], v[174:177], v[0:3]
	s_waitcnt lgkmcnt(3)
	v_mfma_f32_16x16x32_bf16 v[124:127], v[180:183], v[162:165], v[124:127]
	v_mfma_f32_16x16x32_bf16 v[120:123], v[180:183], v[166:169], v[120:123]
	v_mfma_f32_16x16x32_bf16 v[116:119], v[180:183], v[170:173], v[116:119]
	v_mfma_f32_16x16x32_bf16 v[112:115], v[180:183], v[174:177], v[112:115]
	s_waitcnt lgkmcnt(2)
	v_mfma_f32_16x16x32_bf16 v[108:111], v[184:187], v[162:165], v[108:111]
	v_mfma_f32_16x16x32_bf16 v[104:107], v[184:187], v[166:169], v[104:107]
	v_mfma_f32_16x16x32_bf16 v[100:103], v[184:187], v[170:173], v[100:103]
	v_mfma_f32_16x16x32_bf16 v[96:99], v[184:187], v[174:177], v[96:99]
	s_waitcnt lgkmcnt(1)
	v_mfma_f32_16x16x32_bf16 v[92:95], v[188:191], v[162:165], v[92:95]
	v_mfma_f32_16x16x32_bf16 v[88:91], v[188:191], v[166:169], v[88:91]
	v_mfma_f32_16x16x32_bf16 v[80:83], v[188:191], v[170:173], v[80:83]
	v_mfma_f32_16x16x32_bf16 v[72:75], v[188:191], v[174:177], v[72:75]
	s_waitcnt lgkmcnt(0)
	v_mfma_f32_16x16x32_bf16 v[64:67], v[192:195], v[162:165], v[64:67]
	v_mfma_f32_16x16x32_bf16 v[56:59], v[192:195], v[166:169], v[56:59]
	v_mfma_f32_16x16x32_bf16 v[48:51], v[192:195], v[170:173], v[48:51]
	v_mfma_f32_16x16x32_bf16 v[40:43], v[192:195], v[174:177], v[40:43]
	s_add_i32 s39, s38, 1
	s_cmp_lg_u32 s38, 2
	s_cselect_b32 s38, s39, 0
	s_add_i32 s39, s37, 1
	s_cmp_lg_u32 s37, 2
	s_cselect_b32 s37, s39, 0
	s_add_u32 s14, s14, 64
	s_addc_u32 s15, s15, 0
	s_cmpk_eq_i32 s14, 0x780
	s_cbranch_scc0 .LBB0_1520
	s_waitcnt vmcnt(6)
	s_waitcnt lgkmcnt(0)
	s_barrier
	ds_read_b128 v[134:137], v139
	ds_read_b128 v[146:149], v139 offset:1024
	ds_read_b128 v[150:153], v139 offset:2048
	ds_read_b128 v[154:157], v139 offset:3072
	ds_read_b128 v[158:161], v141
	ds_read_b128 v[162:165], v141 offset:1024
	ds_read_b128 v[166:169], v141 offset:2048
	ds_read_b128 v[170:173], v141 offset:3072
	s_waitcnt lgkmcnt(0)
	s_nop 0
	v_mfma_f32_16x16x32_bf16 v[84:87], v[134:137], v[158:161], v[84:87]
	v_mfma_f32_16x16x32_bf16 v[76:79], v[134:137], v[162:165], v[76:79]
	v_mfma_f32_16x16x32_bf16 v[68:71], v[134:137], v[166:169], v[68:71]
	v_mfma_f32_16x16x32_bf16 v[60:63], v[134:137], v[170:173], v[60:63]
	v_mfma_f32_16x16x32_bf16 v[52:55], v[146:149], v[158:161], v[52:55]
	v_mfma_f32_16x16x32_bf16 v[44:47], v[146:149], v[162:165], v[44:47]
	v_mfma_f32_16x16x32_bf16 v[36:39], v[146:149], v[166:169], v[36:39]
	v_mfma_f32_16x16x32_bf16 v[32:35], v[146:149], v[170:173], v[32:35]
	v_mfma_f32_16x16x32_bf16 v[28:31], v[150:153], v[158:161], v[28:31]
	v_mfma_f32_16x16x32_bf16 v[24:27], v[150:153], v[162:165], v[24:27]
	v_mfma_f32_16x16x32_bf16 v[20:23], v[150:153], v[166:169], v[20:23]
	v_mfma_f32_16x16x32_bf16 v[16:19], v[150:153], v[170:173], v[16:19]
	v_mfma_f32_16x16x32_bf16 v[12:15], v[154:157], v[158:161], v[12:15]
	v_mfma_f32_16x16x32_bf16 v[8:11], v[154:157], v[162:165], v[8:11]
	v_mfma_f32_16x16x32_bf16 v[4:7], v[154:157], v[166:169], v[4:7]
	v_mfma_f32_16x16x32_bf16 v[0:3], v[154:157], v[170:173], v[0:3]
	ds_read_b128 v[134:137], v139 offset:4096
	ds_read_b128 v[146:149], v139 offset:5120
	ds_read_b128 v[150:153], v139 offset:6144
	ds_read_b128 v[154:157], v139 offset:7168
	s_waitcnt lgkmcnt(0)
	s_nop 0
	v_mfma_f32_16x16x32_bf16 v[124:127], v[134:137], v[158:161], v[124:127]
	v_mfma_f32_16x16x32_bf16 v[120:123], v[134:137], v[162:165], v[120:123]
	v_mfma_f32_16x16x32_bf16 v[174:177], v[134:137], v[166:169], v[116:119]
	v_mfma_f32_16x16x32_bf16 v[134:137], v[134:137], v[170:173], v[112:115]
	v_mfma_f32_16x16x32_bf16 v[178:181], v[146:149], v[158:161], v[108:111]
	v_mfma_f32_16x16x32_bf16 v[182:185], v[146:149], v[162:165], v[104:107]
	v_mfma_f32_16x16x32_bf16 v[186:189], v[146:149], v[166:169], v[100:103]
	v_mfma_f32_16x16x32_bf16 v[146:149], v[146:149], v[170:173], v[96:99]
	v_mfma_f32_16x16x32_bf16 v[190:193], v[150:153], v[158:161], v[92:95]
	v_mfma_f32_16x16x32_bf16 v[194:197], v[150:153], v[162:165], v[88:91]
	v_mfma_f32_16x16x32_bf16 v[198:201], v[150:153], v[166:169], v[80:83]
	v_mfma_f32_16x16x32_bf16 v[150:153], v[150:153], v[170:173], v[72:75]
	v_mfma_f32_16x16x32_bf16 v[158:161], v[154:157], v[158:161], v[64:67]
	v_mfma_f32_16x16x32_bf16 v[162:165], v[154:157], v[162:165], v[56:59]
	v_mfma_f32_16x16x32_bf16 v[166:169], v[154:157], v[166:169], v[48:51]
	v_mfma_f32_16x16x32_bf16 v[154:157], v[154:157], v[170:173], v[40:43]
	s_waitcnt vmcnt(0)
	s_waitcnt lgkmcnt(0)
	s_barrier
	ds_read_b128 v[40:43], v128
	ds_read_b128 v[48:51], v128 offset:1024
	ds_read_b128 v[56:59], v128 offset:2048
	ds_read_b128 v[170:173], v128 offset:3072
	ds_read_b128 v[202:205], v144
	ds_read_b128 v[206:209], v144 offset:1024
	ds_read_b128 v[210:213], v144 offset:2048
	ds_read_b128 v[214:217], v144 offset:3072
	s_waitcnt lgkmcnt(0)
	s_nop 0
	v_mfma_f32_16x16x32_bf16 v[222:225], v[40:43], v[206:209], v[76:79]
	v_mfma_f32_16x16x32_bf16 v[112:115], v[40:43], v[210:213], v[68:71]
	v_mfma_f32_16x16x32_bf16 v[72:75], v[170:173], v[202:205], v[12:15]
	v_mfma_f32_16x16x32_bf16 v[76:79], v[170:173], v[206:209], v[8:11]
	v_mfma_f32_16x16x32_bf16 v[64:67], v[170:173], v[210:213], v[4:7]
	v_mfma_f32_16x16x32_bf16 v[68:71], v[170:173], v[214:217], v[0:3]
	ds_read_b128 v[0:3], v128 offset:4096
	ds_read_b128 v[4:7], v128 offset:5120
	ds_read_b128 v[8:11], v128 offset:6144
	ds_read_b128 v[170:173], v128 offset:7168
	s_waitcnt lgkmcnt(0)
	v_mfma_f32_16x16x32_bf16 v[218:221], v[40:43], v[202:205], v[84:87]
	v_mfma_f32_16x16x32_bf16 v[116:119], v[40:43], v[214:217], v[60:63]
	v_mfma_f32_16x16x32_bf16 v[104:107], v[48:51], v[202:205], v[52:55]
	v_mfma_f32_16x16x32_bf16 v[108:111], v[48:51], v[206:209], v[44:47]
	v_mfma_f32_16x16x32_bf16 v[96:99], v[48:51], v[210:213], v[36:39]
	v_mfma_f32_16x16x32_bf16 v[100:103], v[48:51], v[214:217], v[32:35]
	v_mfma_f32_16x16x32_bf16 v[88:91], v[56:59], v[202:205], v[28:31]
	v_mfma_f32_16x16x32_bf16 v[92:95], v[56:59], v[206:209], v[24:27]
	v_mfma_f32_16x16x32_bf16 v[80:83], v[56:59], v[210:213], v[20:23]
	v_mfma_f32_16x16x32_bf16 v[84:87], v[56:59], v[214:217], v[16:19]
	v_mfma_f32_16x16x32_bf16 v[56:59], v[0:3], v[202:205], v[124:127]
	v_mfma_f32_16x16x32_bf16 v[60:63], v[0:3], v[206:209], v[120:123]
	v_mfma_f32_16x16x32_bf16 v[48:51], v[0:3], v[210:213], v[174:177]
	v_mfma_f32_16x16x32_bf16 v[52:55], v[0:3], v[214:217], v[134:137]
	v_mfma_f32_16x16x32_bf16 v[40:43], v[4:7], v[202:205], v[178:181]
	v_mfma_f32_16x16x32_bf16 v[44:47], v[4:7], v[206:209], v[182:185]
	v_mfma_f32_16x16x32_bf16 v[32:35], v[4:7], v[210:213], v[186:189]
	v_mfma_f32_16x16x32_bf16 v[36:39], v[4:7], v[214:217], v[146:149]
	v_mfma_f32_16x16x32_bf16 v[24:27], v[8:11], v[202:205], v[190:193]
	v_mfma_f32_16x16x32_bf16 v[28:31], v[8:11], v[206:209], v[194:197]
	v_mfma_f32_16x16x32_bf16 v[16:19], v[8:11], v[210:213], v[198:201]
	v_mfma_f32_16x16x32_bf16 v[20:23], v[8:11], v[214:217], v[150:153]
	v_mfma_f32_16x16x32_bf16 v[8:11], v[170:173], v[202:205], v[158:161]
	v_mfma_f32_16x16x32_bf16 v[12:15], v[170:173], v[206:209], v[162:165]
	v_mfma_f32_16x16x32_bf16 v[0:3], v[170:173], v[210:213], v[166:169]
	v_mfma_f32_16x16x32_bf16 v[4:7], v[170:173], v[214:217], v[154:157]
	s_setprio 0
	v_mul_f32_e32 v121, 0xbfb8aa3b, v218
	v_exp_f32_e32 v121, v121
	v_or_b32_e32 v120, s36, v140
	v_ashrrev_i32_e32 v120, 1, v120
	v_or_b32_e32 v122, v120, v138
	v_add_f32_e32 v120, 1.0, v121
	v_rcp_f32_e32 v125, v120
	v_add_u32_e32 v124, s35, v145
	v_readlane_b32 s36, v241, 17
	v_mov_b32_e32 v126, v124
	v_mul_f32_e32 v120, v218, v125
	v_mul_f32_e32 v120, v222, v120
	v_mul_f32_e32 v134, 0xbfb8aa3b, v219
	v_readlane_b32 s37, v241, 18
	v_exp_f32_e32 v134, v134
	s_waitcnt lgkmcnt(0)
	s_barrier
	v_ashrrev_i32_e32 v123, 31, v122
	v_cvt_pk_bf16_f32 v125, v120, v120
	v_mov_b64_e32 v[120:121], s[36:37]
	v_mad_i64_i32 v[126:127], s[14:15], v126, s33, v[120:121]
	v_lshlrev_b64 v[122:123], 1, v[122:123]
	v_lshl_add_u64 v[126:127], v[126:127], 0, v[122:123]
	global_store_short_d16_hi v[126:127], v125, off
	v_add_f32_e32 v125, 1.0, v134
	v_rcp_f32_e32 v127, v125
	v_or_b32_e32 v134, 1, v124
	v_mov_b32_e32 v135, v134
	v_mul_f32_e32 v125, v219, v127
	v_mul_f32_e32 v125, v223, v125
	v_cvt_pk_bf16_f32 v125, v125, v125
	v_mul_f32_e32 v126, 0xbfb8aa3b, v220
	v_exp_f32_e32 v136, v126
	v_mad_i64_i32 v[126:127], s[14:15], v135, s33, v[120:121]
	v_lshl_add_u64 v[126:127], v[126:127], 0, v[122:123]
	global_store_short_d16_hi v[126:127], v125, off
	v_add_f32_e32 v125, 1.0, v136
	v_rcp_f32_e32 v127, v125
	v_or_b32_e32 v135, 2, v124
	v_mov_b32_e32 v136, v135
	v_mul_f32_e32 v125, v220, v127
	v_mul_f32_e32 v125, v224, v125
	v_cvt_pk_bf16_f32 v125, v125, v125
	v_mul_f32_e32 v126, 0xbfb8aa3b, v221
	v_exp_f32_e32 v137, v126
	v_mad_i64_i32 v[126:127], s[14:15], v136, s33, v[120:121]
	v_lshl_add_u64 v[126:127], v[126:127], 0, v[122:123]
	global_store_short_d16_hi v[126:127], v125, off
	v_add_f32_e32 v125, 1.0, v137
	v_rcp_f32_e32 v127, v125
	v_or_b32_e32 v136, 3, v124
	v_mov_b32_e32 v137, v136
	v_mul_f32_e32 v125, v221, v127
	v_mul_f32_e32 v125, v225, v125
	v_cvt_pk_bf16_f32 v125, v125, v125
	v_mul_f32_e32 v126, 0xbfb8aa3b, v112
	v_exp_f32_e32 v146, v126
	v_mad_i64_i32 v[126:127], s[14:15], v137, s33, v[120:121]
	v_lshl_add_u64 v[126:127], v[126:127], 0, v[122:123]
	v_add_f32_e32 v137, 1.0, v146
	v_rcp_f32_e32 v147, v137
	global_store_short_d16_hi v[126:127], v125, off
	v_mov_b32_e32 v125, v124
	v_mul_f32_e32 v112, v112, v147
	v_mul_f32_e32 v126, 0xbfb8aa3b, v113
	v_exp_f32_e32 v137, v126
	v_mul_f32_e32 v112, v116, v112
	v_cvt_pk_bf16_f32 v112, v112, v112
	v_add_f32_e32 v116, 1.0, v137
	v_mad_i64_i32 v[126:127], s[14:15], v125, s33, v[120:121]
	v_rcp_f32_e32 v137, v116
	v_lshl_add_u64 v[126:127], v[126:127], 0, v[122:123]
	global_store_short_d16_hi v[126:127], v112, off offset:32
	v_mul_f32_e32 v112, v113, v137
	v_mul_f32_e32 v116, 0xbfb8aa3b, v114
	v_exp_f32_e32 v116, v116
	v_mul_f32_e32 v112, v117, v112
	v_cvt_pk_bf16_f32 v117, v112, v112
	v_add_f32_e32 v116, 1.0, v116
	v_rcp_f32_e32 v126, v116
	v_mad_i64_i32 v[112:113], s[14:15], v134, s33, v[120:121]
	v_lshl_add_u64 v[112:113], v[112:113], 0, v[122:123]
	global_store_short_d16_hi v[112:113], v117, off offset:32
	v_mul_f32_e32 v112, v114, v126
	v_mul_f32_e32 v114, 0xbfb8aa3b, v115
	v_exp_f32_e32 v114, v114
	v_mul_f32_e32 v112, v118, v112
	v_add_f32_e32 v114, 1.0, v114
	v_rcp_f32_e32 v118, v114
	v_cvt_pk_bf16_f32 v116, v112, v112
	v_mad_i64_i32 v[112:113], s[14:15], v135, s33, v[120:121]
	v_lshl_add_u64 v[112:113], v[112:113], 0, v[122:123]
	global_store_short_d16_hi v[112:113], v116, off offset:32
	v_mul_f32_e32 v112, v115, v118
	v_mul_f32_e32 v112, v119, v112
	v_cvt_pk_bf16_f32 v114, v112, v112
	v_mul_f32_e32 v112, 0xbfb8aa3b, v104
	v_exp_f32_e32 v115, v112
	v_readlane_b32 s38, v241, 19
	v_mad_i64_i32 v[112:113], s[14:15], v136, s33, v[120:121]
	v_lshl_add_u64 v[112:113], v[112:113], 0, v[122:123]
	global_store_short_d16_hi v[112:113], v114, off offset:32
	v_add_f32_e32 v112, 1.0, v115
	v_rcp_f32_e32 v114, v112
	v_or_b32_e32 v115, 16, v124
	v_mov_b32_e32 v116, v115
	v_mul_f32_e32 v104, v104, v114
	v_mul_f32_e32 v104, v108, v104
	v_cvt_pk_bf16_f32 v104, v104, v104
	v_mul_f32_e32 v108, 0xbfb8aa3b, v105
	v_exp_f32_e32 v108, v108
	v_mad_i64_i32 v[112:113], s[14:15], v116, s33, v[120:121]
	v_lshl_add_u64 v[112:113], v[112:113], 0, v[122:123]
	global_store_short_d16_hi v[112:113], v104, off
	v_add_f32_e32 v104, 1.0, v108
	v_rcp_f32_e32 v112, v104
	v_or_b32_e32 v113, 17, v124
	v_mov_b32_e32 v114, v113
	v_mul_f32_e32 v104, v105, v112
	v_mul_f32_e32 v104, v109, v104
	v_cvt_pk_bf16_f32 v108, v104, v104
	v_mul_f32_e32 v104, 0xbfb8aa3b, v106
	v_exp_f32_e32 v109, v104
	v_mad_i64_i32 v[104:105], s[14:15], v114, s33, v[120:121]
	v_lshl_add_u64 v[104:105], v[104:105], 0, v[122:123]
	global_store_short_d16_hi v[104:105], v108, off
	v_add_f32_e32 v104, 1.0, v109
	v_rcp_f32_e32 v108, v104
	v_or_b32_e32 v109, 18, v124
	v_mov_b32_e32 v112, v109
	v_mul_f32_e32 v104, v106, v108
	v_mul_f32_e32 v104, v110, v104
	v_cvt_pk_bf16_f32 v106, v104, v104
	v_mul_f32_e32 v104, 0xbfb8aa3b, v107
	v_exp_f32_e32 v108, v104
	v_mad_i64_i32 v[104:105], s[14:15], v112, s33, v[120:121]
	v_lshl_add_u64 v[104:105], v[104:105], 0, v[122:123]
	global_store_short_d16_hi v[104:105], v106, off
	v_add_f32_e32 v104, 1.0, v108
	v_rcp_f32_e32 v106, v104
	v_or_b32_e32 v108, 19, v124
	v_mov_b32_e32 v110, v108
	v_mul_f32_e32 v104, v107, v106
	v_mul_f32_e32 v106, 0xbfb8aa3b, v96
	v_exp_f32_e32 v106, v106
	v_mul_f32_e32 v104, v111, v104
	v_add_f32_e32 v106, 1.0, v106
	v_cvt_pk_bf16_f32 v107, v104, v104
	v_mad_i64_i32 v[104:105], s[14:15], v110, s33, v[120:121]
	v_rcp_f32_e32 v111, v106
	v_lshl_add_u64 v[104:105], v[104:105], 0, v[122:123]
	global_store_short_d16_hi v[104:105], v107, off
	v_mul_f32_e32 v96, v96, v111
	v_mul_f32_e32 v104, 0xbfb8aa3b, v97
	v_exp_f32_e32 v106, v104
	v_mul_f32_e32 v96, v100, v96
	v_cvt_pk_bf16_f32 v96, v96, v96
	v_add_f32_e32 v100, 1.0, v106
	v_rcp_f32_e32 v107, v100
	v_mad_i64_i32 v[104:105], s[14:15], v115, s33, v[120:121]
	v_lshl_add_u64 v[104:105], v[104:105], 0, v[122:123]
	global_store_short_d16_hi v[104:105], v96, off offset:32
	v_mul_f32_e32 v96, v97, v107
	v_mul_f32_e32 v100, 0xbfb8aa3b, v98
	v_exp_f32_e32 v100, v100
	v_mul_f32_e32 v96, v101, v96
	v_add_f32_e32 v100, 1.0, v100
	v_rcp_f32_e32 v105, v100
	v_cvt_pk_bf16_f32 v101, v96, v96
	v_mad_i64_i32 v[96:97], s[14:15], v113, s33, v[120:121]
	v_lshl_add_u64 v[96:97], v[96:97], 0, v[122:123]
	global_store_short_d16_hi v[96:97], v101, off offset:32
	v_mul_f32_e32 v96, v98, v105
	v_mul_f32_e32 v98, 0xbfb8aa3b, v99
	v_exp_f32_e32 v98, v98
	v_mul_f32_e32 v96, v102, v96
	v_add_f32_e32 v98, 1.0, v98
	v_rcp_f32_e32 v102, v98
	v_cvt_pk_bf16_f32 v100, v96, v96
	v_mad_i64_i32 v[96:97], s[14:15], v109, s33, v[120:121]
	v_lshl_add_u64 v[96:97], v[96:97], 0, v[122:123]
	global_store_short_d16_hi v[96:97], v100, off offset:32
	v_mul_f32_e32 v96, v99, v102
	v_mul_f32_e32 v96, v103, v96
	v_cvt_pk_bf16_f32 v98, v96, v96
	v_mul_f32_e32 v96, 0xbfb8aa3b, v88
	v_exp_f32_e32 v99, v96
	v_readlane_b32 s39, v241, 20
	v_mad_i64_i32 v[96:97], s[14:15], v108, s33, v[120:121]
	v_lshl_add_u64 v[96:97], v[96:97], 0, v[122:123]
	global_store_short_d16_hi v[96:97], v98, off offset:32
	v_add_f32_e32 v96, 1.0, v99
	v_rcp_f32_e32 v98, v96
	v_or_b32_e32 v99, 32, v124
	v_mov_b32_e32 v100, v99
	v_mul_f32_e32 v88, v88, v98
	v_mul_f32_e32 v88, v92, v88
	v_cvt_pk_bf16_f32 v88, v88, v88
	v_mul_f32_e32 v92, 0xbfb8aa3b, v89
	v_exp_f32_e32 v92, v92
	v_mad_i64_i32 v[96:97], s[14:15], v100, s33, v[120:121]
	v_lshl_add_u64 v[96:97], v[96:97], 0, v[122:123]
	global_store_short_d16_hi v[96:97], v88, off
	v_add_f32_e32 v88, 1.0, v92
	v_rcp_f32_e32 v96, v88
	v_or_b32_e32 v97, 33, v124
	v_mov_b32_e32 v98, v97
	v_mul_f32_e32 v88, v89, v96
	v_mul_f32_e32 v88, v93, v88
	v_cvt_pk_bf16_f32 v92, v88, v88
	v_mul_f32_e32 v88, 0xbfb8aa3b, v90
	v_exp_f32_e32 v93, v88
	v_mad_i64_i32 v[88:89], s[14:15], v98, s33, v[120:121]
	v_lshl_add_u64 v[88:89], v[88:89], 0, v[122:123]
	global_store_short_d16_hi v[88:89], v92, off
	v_add_f32_e32 v88, 1.0, v93
	v_rcp_f32_e32 v92, v88
	v_or_b32_e32 v93, 34, v124
	v_mov_b32_e32 v96, v93
	v_mul_f32_e32 v88, v90, v92
	v_mul_f32_e32 v88, v94, v88
	v_cvt_pk_bf16_f32 v90, v88, v88
	v_mul_f32_e32 v88, 0xbfb8aa3b, v91
	v_exp_f32_e32 v92, v88
	v_mad_i64_i32 v[88:89], s[14:15], v96, s33, v[120:121]
	v_lshl_add_u64 v[88:89], v[88:89], 0, v[122:123]
	global_store_short_d16_hi v[88:89], v90, off
	v_add_f32_e32 v88, 1.0, v92
	v_rcp_f32_e32 v90, v88
	v_or_b32_e32 v92, 35, v124
	v_mov_b32_e32 v94, v92
	v_mul_f32_e32 v88, v91, v90
	v_mul_f32_e32 v90, 0xbfb8aa3b, v80
	v_exp_f32_e32 v90, v90
	v_mul_f32_e32 v88, v95, v88
	v_add_f32_e32 v90, 1.0, v90
	v_cvt_pk_bf16_f32 v91, v88, v88
	v_mad_i64_i32 v[88:89], s[14:15], v94, s33, v[120:121]
	v_rcp_f32_e32 v95, v90
	v_lshl_add_u64 v[88:89], v[88:89], 0, v[122:123]
	global_store_short_d16_hi v[88:89], v91, off
	v_mul_f32_e32 v80, v80, v95
	v_mul_f32_e32 v88, 0xbfb8aa3b, v81
	v_exp_f32_e32 v90, v88
	v_mul_f32_e32 v80, v84, v80
	v_cvt_pk_bf16_f32 v80, v80, v80
	v_add_f32_e32 v84, 1.0, v90
	v_rcp_f32_e32 v91, v84
	v_mad_i64_i32 v[88:89], s[14:15], v99, s33, v[120:121]
	v_lshl_add_u64 v[88:89], v[88:89], 0, v[122:123]
	global_store_short_d16_hi v[88:89], v80, off offset:32
	v_mul_f32_e32 v80, v81, v91
	v_mul_f32_e32 v84, 0xbfb8aa3b, v82
	v_exp_f32_e32 v84, v84
	v_mul_f32_e32 v80, v85, v80
	v_add_f32_e32 v84, 1.0, v84
	v_rcp_f32_e32 v89, v84
	v_cvt_pk_bf16_f32 v85, v80, v80
	v_mad_i64_i32 v[80:81], s[14:15], v97, s33, v[120:121]
	v_lshl_add_u64 v[80:81], v[80:81], 0, v[122:123]
	global_store_short_d16_hi v[80:81], v85, off offset:32
	v_mul_f32_e32 v80, v82, v89
	v_mul_f32_e32 v82, 0xbfb8aa3b, v83
	v_exp_f32_e32 v82, v82
	v_mul_f32_e32 v80, v86, v80
	v_add_f32_e32 v82, 1.0, v82
	v_rcp_f32_e32 v86, v82
	v_cvt_pk_bf16_f32 v84, v80, v80
	v_mad_i64_i32 v[80:81], s[14:15], v93, s33, v[120:121]
	v_lshl_add_u64 v[80:81], v[80:81], 0, v[122:123]
	global_store_short_d16_hi v[80:81], v84, off offset:32
	v_mul_f32_e32 v80, v83, v86
	v_mul_f32_e32 v80, v87, v80
	v_cvt_pk_bf16_f32 v82, v80, v80
	v_mul_f32_e32 v80, 0xbfb8aa3b, v72
	v_exp_f32_e32 v83, v80
	v_readlane_b32 s40, v241, 21
	v_mad_i64_i32 v[80:81], s[14:15], v92, s33, v[120:121]
	v_lshl_add_u64 v[80:81], v[80:81], 0, v[122:123]
	global_store_short_d16_hi v[80:81], v82, off offset:32
	v_add_f32_e32 v80, 1.0, v83
	v_rcp_f32_e32 v82, v80
	v_or_b32_e32 v83, 48, v124
	v_mov_b32_e32 v84, v83
	v_mul_f32_e32 v72, v72, v82
	v_mul_f32_e32 v72, v76, v72
	v_cvt_pk_bf16_f32 v72, v72, v72
	v_mul_f32_e32 v76, 0xbfb8aa3b, v73
	v_exp_f32_e32 v76, v76
	v_mad_i64_i32 v[80:81], s[14:15], v84, s33, v[120:121]
	v_lshl_add_u64 v[80:81], v[80:81], 0, v[122:123]
	global_store_short_d16_hi v[80:81], v72, off
	v_add_f32_e32 v72, 1.0, v76
	v_rcp_f32_e32 v80, v72
	v_or_b32_e32 v81, 49, v124
	v_mov_b32_e32 v82, v81
	v_mul_f32_e32 v72, v73, v80
	v_mul_f32_e32 v72, v77, v72
	v_cvt_pk_bf16_f32 v76, v72, v72
	v_mul_f32_e32 v72, 0xbfb8aa3b, v74
	v_exp_f32_e32 v77, v72
	v_mad_i64_i32 v[72:73], s[14:15], v82, s33, v[120:121]
	v_lshl_add_u64 v[72:73], v[72:73], 0, v[122:123]
	global_store_short_d16_hi v[72:73], v76, off
	v_add_f32_e32 v72, 1.0, v77
	v_rcp_f32_e32 v76, v72
	v_or_b32_e32 v77, 50, v124
	v_mov_b32_e32 v80, v77
	v_mul_f32_e32 v72, v74, v76
	v_mul_f32_e32 v72, v78, v72
	v_cvt_pk_bf16_f32 v74, v72, v72
	v_mul_f32_e32 v72, 0xbfb8aa3b, v75
	v_exp_f32_e32 v76, v72
	v_mad_i64_i32 v[72:73], s[14:15], v80, s33, v[120:121]
	v_lshl_add_u64 v[72:73], v[72:73], 0, v[122:123]
	global_store_short_d16_hi v[72:73], v74, off
	v_add_f32_e32 v72, 1.0, v76
	v_rcp_f32_e32 v74, v72
	v_or_b32_e32 v76, 51, v124
	v_mov_b32_e32 v78, v76
	v_mul_f32_e32 v72, v75, v74
	v_mul_f32_e32 v74, 0xbfb8aa3b, v64
	v_exp_f32_e32 v74, v74
	v_mul_f32_e32 v72, v79, v72
	v_add_f32_e32 v74, 1.0, v74
	v_cvt_pk_bf16_f32 v75, v72, v72
	v_mad_i64_i32 v[72:73], s[14:15], v78, s33, v[120:121]
	v_rcp_f32_e32 v79, v74
	v_lshl_add_u64 v[72:73], v[72:73], 0, v[122:123]
	global_store_short_d16_hi v[72:73], v75, off
	v_mul_f32_e32 v64, v64, v79
	v_mul_f32_e32 v72, 0xbfb8aa3b, v65
	v_exp_f32_e32 v74, v72
	v_mul_f32_e32 v64, v68, v64
	v_cvt_pk_bf16_f32 v64, v64, v64
	v_add_f32_e32 v68, 1.0, v74
	v_rcp_f32_e32 v75, v68
	v_mad_i64_i32 v[72:73], s[14:15], v83, s33, v[120:121]
	v_lshl_add_u64 v[72:73], v[72:73], 0, v[122:123]
	global_store_short_d16_hi v[72:73], v64, off offset:32
	v_mul_f32_e32 v64, v65, v75
	v_mul_f32_e32 v68, 0xbfb8aa3b, v66
	v_exp_f32_e32 v68, v68
	v_mul_f32_e32 v64, v69, v64
	v_add_f32_e32 v68, 1.0, v68
	v_rcp_f32_e32 v73, v68
	v_cvt_pk_bf16_f32 v69, v64, v64
	v_mad_i64_i32 v[64:65], s[14:15], v81, s33, v[120:121]
	v_lshl_add_u64 v[64:65], v[64:65], 0, v[122:123]
	global_store_short_d16_hi v[64:65], v69, off offset:32
	v_mul_f32_e32 v64, v66, v73
	v_mul_f32_e32 v66, 0xbfb8aa3b, v67
	v_exp_f32_e32 v66, v66
	v_mul_f32_e32 v64, v70, v64
	v_add_f32_e32 v66, 1.0, v66
	v_rcp_f32_e32 v70, v66
	v_cvt_pk_bf16_f32 v68, v64, v64
	v_mad_i64_i32 v[64:65], s[14:15], v77, s33, v[120:121]
	v_lshl_add_u64 v[64:65], v[64:65], 0, v[122:123]
	global_store_short_d16_hi v[64:65], v68, off offset:32
	v_mul_f32_e32 v64, v67, v70
	v_mul_f32_e32 v64, v71, v64
	v_cvt_pk_bf16_f32 v66, v64, v64
	v_mad_i64_i32 v[64:65], s[14:15], v76, s33, v[120:121]
	v_lshl_add_u64 v[64:65], v[64:65], 0, v[122:123]
	global_store_short_d16_hi v[64:65], v66, off offset:32
	v_readlane_b32 s41, v241, 22
	v_readlane_b32 s42, v241, 23
	v_readlane_b32 s43, v241, 24
	v_mul_f32_e32 v64, 0xbfb8aa3b, v56
	v_exp_f32_e32 v64, v64
	v_or_b32_e32 v66, 64, v124
	v_mov_b32_e32 v65, v66
	v_add_f32_e32 v64, 1.0, v64
	v_rcp_f32_e32 v68, v64
	s_add_i32 s2, s2, s3
	v_mul_f32_e32 v56, v56, v68
	v_mul_f32_e32 v56, v60, v56
	v_cvt_pk_bf16_f32 v56, v56, v56
	v_mul_f32_e32 v60, 0xbfb8aa3b, v57
	v_exp_f32_e32 v60, v60
	v_mad_i64_i32 v[64:65], s[14:15], v65, s33, v[120:121]
	v_lshl_add_u64 v[64:65], v[64:65], 0, v[122:123]
	global_store_short_d16_hi v[64:65], v56, off
	v_add_f32_e32 v56, 1.0, v60
	v_rcp_f32_e32 v64, v56
	v_or_b32_e32 v65, 0x41, v124
	v_mov_b32_e32 v67, v65
	v_mul_f32_e32 v56, v57, v64
	v_mul_f32_e32 v56, v61, v56
	v_cvt_pk_bf16_f32 v60, v56, v56
	v_mul_f32_e32 v56, 0xbfb8aa3b, v58
	v_exp_f32_e32 v61, v56
	v_mad_i64_i32 v[56:57], s[14:15], v67, s33, v[120:121]
	v_lshl_add_u64 v[56:57], v[56:57], 0, v[122:123]
	global_store_short_d16_hi v[56:57], v60, off
	v_add_f32_e32 v56, 1.0, v61
	v_rcp_f32_e32 v60, v56
	v_or_b32_e32 v61, 0x42, v124
	v_mov_b32_e32 v64, v61
	v_mul_f32_e32 v56, v58, v60
	v_mul_f32_e32 v56, v62, v56
	v_cvt_pk_bf16_f32 v58, v56, v56
	v_mul_f32_e32 v56, 0xbfb8aa3b, v59
	v_exp_f32_e32 v60, v56
	v_mad_i64_i32 v[56:57], s[14:15], v64, s33, v[120:121]
	v_lshl_add_u64 v[56:57], v[56:57], 0, v[122:123]
	global_store_short_d16_hi v[56:57], v58, off
	v_add_f32_e32 v56, 1.0, v60
	v_rcp_f32_e32 v58, v56
	v_or_b32_e32 v60, 0x43, v124
	v_mov_b32_e32 v62, v60
	v_mul_f32_e32 v56, v59, v58
	v_mul_f32_e32 v58, 0xbfb8aa3b, v48
	v_exp_f32_e32 v58, v58
	v_mul_f32_e32 v56, v63, v56
	v_add_f32_e32 v58, 1.0, v58
	v_cvt_pk_bf16_f32 v59, v56, v56
	v_mad_i64_i32 v[56:57], s[14:15], v62, s33, v[120:121]
	v_rcp_f32_e32 v63, v58
	v_lshl_add_u64 v[56:57], v[56:57], 0, v[122:123]
	global_store_short_d16_hi v[56:57], v59, off
	v_mul_f32_e32 v48, v48, v63
	v_mul_f32_e32 v56, 0xbfb8aa3b, v49
	v_exp_f32_e32 v58, v56
	v_mul_f32_e32 v48, v52, v48
	v_cvt_pk_bf16_f32 v48, v48, v48
	v_add_f32_e32 v52, 1.0, v58
	v_rcp_f32_e32 v59, v52
	v_mad_i64_i32 v[56:57], s[14:15], v66, s33, v[120:121]
	v_lshl_add_u64 v[56:57], v[56:57], 0, v[122:123]
	global_store_short_d16_hi v[56:57], v48, off offset:32
	v_mul_f32_e32 v48, v49, v59
	v_mul_f32_e32 v52, 0xbfb8aa3b, v50
	v_exp_f32_e32 v52, v52
	v_mul_f32_e32 v48, v53, v48
	v_add_f32_e32 v52, 1.0, v52
	v_rcp_f32_e32 v57, v52
	v_cvt_pk_bf16_f32 v53, v48, v48
	v_mad_i64_i32 v[48:49], s[14:15], v65, s33, v[120:121]
	v_lshl_add_u64 v[48:49], v[48:49], 0, v[122:123]
	global_store_short_d16_hi v[48:49], v53, off offset:32
	v_mul_f32_e32 v48, v50, v57
	v_mul_f32_e32 v50, 0xbfb8aa3b, v51
	v_exp_f32_e32 v50, v50
	v_mul_f32_e32 v48, v54, v48
	v_add_f32_e32 v50, 1.0, v50
	v_rcp_f32_e32 v54, v50
	v_cvt_pk_bf16_f32 v52, v48, v48
	v_mad_i64_i32 v[48:49], s[14:15], v61, s33, v[120:121]
	v_lshl_add_u64 v[48:49], v[48:49], 0, v[122:123]
	global_store_short_d16_hi v[48:49], v52, off offset:32
	v_mul_f32_e32 v48, v51, v54
	v_mul_f32_e32 v48, v55, v48
	v_cvt_pk_bf16_f32 v50, v48, v48
	v_mul_f32_e32 v48, 0xbfb8aa3b, v40
	v_exp_f32_e32 v51, v48
	s_add_i32 s19, s19, s20
	v_mad_i64_i32 v[48:49], s[14:15], v60, s33, v[120:121]
	v_lshl_add_u64 v[48:49], v[48:49], 0, v[122:123]
	global_store_short_d16_hi v[48:49], v50, off offset:32
	v_add_f32_e32 v48, 1.0, v51
	v_rcp_f32_e32 v50, v48
	v_or_b32_e32 v51, 0x50, v124
	v_mov_b32_e32 v52, v51
	v_mul_f32_e32 v40, v40, v50
	v_mul_f32_e32 v40, v44, v40
	v_cvt_pk_bf16_f32 v40, v40, v40
	v_mul_f32_e32 v44, 0xbfb8aa3b, v41
	v_exp_f32_e32 v44, v44
	v_mad_i64_i32 v[48:49], s[14:15], v52, s33, v[120:121]
	v_lshl_add_u64 v[48:49], v[48:49], 0, v[122:123]
	global_store_short_d16_hi v[48:49], v40, off
	v_add_f32_e32 v40, 1.0, v44
	v_rcp_f32_e32 v48, v40
	v_or_b32_e32 v49, 0x51, v124
	v_mov_b32_e32 v50, v49
	v_mul_f32_e32 v40, v41, v48
	v_mul_f32_e32 v40, v45, v40
	v_cvt_pk_bf16_f32 v44, v40, v40
	v_mul_f32_e32 v40, 0xbfb8aa3b, v42
	v_exp_f32_e32 v45, v40
	v_mad_i64_i32 v[40:41], s[14:15], v50, s33, v[120:121]
	v_lshl_add_u64 v[40:41], v[40:41], 0, v[122:123]
	global_store_short_d16_hi v[40:41], v44, off
	v_add_f32_e32 v40, 1.0, v45
	v_rcp_f32_e32 v44, v40
	v_or_b32_e32 v45, 0x52, v124
	v_mov_b32_e32 v48, v45
	v_mul_f32_e32 v40, v42, v44
	v_mul_f32_e32 v40, v46, v40
	v_cvt_pk_bf16_f32 v42, v40, v40
	v_mul_f32_e32 v40, 0xbfb8aa3b, v43
	v_exp_f32_e32 v44, v40
	v_mad_i64_i32 v[40:41], s[14:15], v48, s33, v[120:121]
	v_lshl_add_u64 v[40:41], v[40:41], 0, v[122:123]
	global_store_short_d16_hi v[40:41], v42, off
	v_add_f32_e32 v40, 1.0, v44
	v_rcp_f32_e32 v42, v40
	v_or_b32_e32 v44, 0x53, v124
	v_mov_b32_e32 v46, v44
	v_mul_f32_e32 v40, v43, v42
	v_mul_f32_e32 v42, 0xbfb8aa3b, v32
	v_exp_f32_e32 v42, v42
	v_mul_f32_e32 v40, v47, v40
	v_add_f32_e32 v42, 1.0, v42
	v_cvt_pk_bf16_f32 v43, v40, v40
	v_mad_i64_i32 v[40:41], s[14:15], v46, s33, v[120:121]
	v_rcp_f32_e32 v47, v42
	v_lshl_add_u64 v[40:41], v[40:41], 0, v[122:123]
	global_store_short_d16_hi v[40:41], v43, off
	v_mul_f32_e32 v32, v32, v47
	v_mul_f32_e32 v40, 0xbfb8aa3b, v33
	v_exp_f32_e32 v42, v40
	v_mul_f32_e32 v32, v36, v32
	v_cvt_pk_bf16_f32 v32, v32, v32
	v_add_f32_e32 v36, 1.0, v42
	v_rcp_f32_e32 v43, v36
	v_mad_i64_i32 v[40:41], s[14:15], v51, s33, v[120:121]
	v_lshl_add_u64 v[40:41], v[40:41], 0, v[122:123]
	global_store_short_d16_hi v[40:41], v32, off offset:32
	v_mul_f32_e32 v32, v33, v43
	v_mul_f32_e32 v36, 0xbfb8aa3b, v34
	v_exp_f32_e32 v36, v36
	v_mul_f32_e32 v32, v37, v32
	v_add_f32_e32 v36, 1.0, v36
	v_rcp_f32_e32 v41, v36
	v_cvt_pk_bf16_f32 v37, v32, v32
	v_mad_i64_i32 v[32:33], s[14:15], v49, s33, v[120:121]
	v_lshl_add_u64 v[32:33], v[32:33], 0, v[122:123]
	global_store_short_d16_hi v[32:33], v37, off offset:32
	v_mul_f32_e32 v32, v34, v41
	v_mul_f32_e32 v34, 0xbfb8aa3b, v35
	v_exp_f32_e32 v34, v34
	v_mul_f32_e32 v32, v38, v32
	v_add_f32_e32 v34, 1.0, v34
	v_rcp_f32_e32 v38, v34
	v_cvt_pk_bf16_f32 v36, v32, v32
	v_mad_i64_i32 v[32:33], s[14:15], v45, s33, v[120:121]
	v_lshl_add_u64 v[32:33], v[32:33], 0, v[122:123]
	global_store_short_d16_hi v[32:33], v36, off offset:32
	v_mul_f32_e32 v32, v35, v38
	v_mul_f32_e32 v32, v39, v32
	v_cvt_pk_bf16_f32 v34, v32, v32
	v_mul_f32_e32 v32, 0xbfb8aa3b, v24
	v_exp_f32_e32 v35, v32
	s_xor_b64 s[0:1], s[0:1], s[4:5]
	v_mad_i64_i32 v[32:33], s[14:15], v44, s33, v[120:121]
	v_lshl_add_u64 v[32:33], v[32:33], 0, v[122:123]
	global_store_short_d16_hi v[32:33], v34, off offset:32
	v_add_f32_e32 v32, 1.0, v35
	v_rcp_f32_e32 v34, v32
	v_or_b32_e32 v35, 0x60, v124
	v_mov_b32_e32 v36, v35
	v_mul_f32_e32 v24, v24, v34
	v_mul_f32_e32 v24, v28, v24
	v_cvt_pk_bf16_f32 v24, v24, v24
	v_mul_f32_e32 v28, 0xbfb8aa3b, v25
	v_exp_f32_e32 v28, v28
	v_mad_i64_i32 v[32:33], s[14:15], v36, s33, v[120:121]
	v_lshl_add_u64 v[32:33], v[32:33], 0, v[122:123]
	global_store_short_d16_hi v[32:33], v24, off
	v_add_f32_e32 v24, 1.0, v28
	v_rcp_f32_e32 v32, v24
	v_or_b32_e32 v33, 0x61, v124
	v_mov_b32_e32 v34, v33
	v_mul_f32_e32 v24, v25, v32
	v_mul_f32_e32 v24, v29, v24
	v_cvt_pk_bf16_f32 v28, v24, v24
	v_mul_f32_e32 v24, 0xbfb8aa3b, v26
	v_exp_f32_e32 v29, v24
	v_mad_i64_i32 v[24:25], s[14:15], v34, s33, v[120:121]
	v_lshl_add_u64 v[24:25], v[24:25], 0, v[122:123]
	global_store_short_d16_hi v[24:25], v28, off
	v_add_f32_e32 v24, 1.0, v29
	v_rcp_f32_e32 v28, v24
	v_or_b32_e32 v29, 0x62, v124
	v_mov_b32_e32 v32, v29
	v_mul_f32_e32 v24, v26, v28
	v_mul_f32_e32 v24, v30, v24
	v_cvt_pk_bf16_f32 v26, v24, v24
	v_mul_f32_e32 v24, 0xbfb8aa3b, v27
	v_exp_f32_e32 v28, v24
	v_mad_i64_i32 v[24:25], s[14:15], v32, s33, v[120:121]
	v_lshl_add_u64 v[24:25], v[24:25], 0, v[122:123]
	global_store_short_d16_hi v[24:25], v26, off
	v_add_f32_e32 v24, 1.0, v28
	v_rcp_f32_e32 v26, v24
	v_or_b32_e32 v28, 0x63, v124
	v_mov_b32_e32 v30, v28
	v_mul_f32_e32 v24, v27, v26
	v_mul_f32_e32 v26, 0xbfb8aa3b, v16
	v_exp_f32_e32 v26, v26
	v_mul_f32_e32 v24, v31, v24
	v_add_f32_e32 v26, 1.0, v26
	v_cvt_pk_bf16_f32 v27, v24, v24
	v_mad_i64_i32 v[24:25], s[14:15], v30, s33, v[120:121]
	v_rcp_f32_e32 v31, v26
	v_lshl_add_u64 v[24:25], v[24:25], 0, v[122:123]
	global_store_short_d16_hi v[24:25], v27, off
	v_mul_f32_e32 v16, v16, v31
	v_mul_f32_e32 v24, 0xbfb8aa3b, v17
	v_exp_f32_e32 v26, v24
	v_mul_f32_e32 v16, v20, v16
	v_cvt_pk_bf16_f32 v16, v16, v16
	v_add_f32_e32 v20, 1.0, v26
	v_rcp_f32_e32 v27, v20
	v_mad_i64_i32 v[24:25], s[14:15], v35, s33, v[120:121]
	v_lshl_add_u64 v[24:25], v[24:25], 0, v[122:123]
	global_store_short_d16_hi v[24:25], v16, off offset:32
	v_mul_f32_e32 v16, v17, v27
	v_mul_f32_e32 v20, 0xbfb8aa3b, v18
	v_exp_f32_e32 v20, v20
	v_mul_f32_e32 v16, v21, v16
	v_add_f32_e32 v20, 1.0, v20
	v_rcp_f32_e32 v25, v20
	v_cvt_pk_bf16_f32 v21, v16, v16
	v_mad_i64_i32 v[16:17], s[14:15], v33, s33, v[120:121]
	v_lshl_add_u64 v[16:17], v[16:17], 0, v[122:123]
	global_store_short_d16_hi v[16:17], v21, off offset:32
	v_mul_f32_e32 v16, v18, v25
	v_mul_f32_e32 v18, 0xbfb8aa3b, v19
	v_exp_f32_e32 v18, v18
	v_mul_f32_e32 v16, v22, v16
	v_add_f32_e32 v18, 1.0, v18
	v_rcp_f32_e32 v22, v18
	v_cvt_pk_bf16_f32 v20, v16, v16
	v_mad_i64_i32 v[16:17], s[14:15], v29, s33, v[120:121]
	v_lshl_add_u64 v[16:17], v[16:17], 0, v[122:123]
	global_store_short_d16_hi v[16:17], v20, off offset:32
	v_mul_f32_e32 v16, v19, v22
	v_mul_f32_e32 v16, v23, v16
	v_cvt_pk_bf16_f32 v18, v16, v16
	v_mul_f32_e32 v16, 0xbfb8aa3b, v8
	v_exp_f32_e32 v19, v16
	s_cmpk_gt_i32 s2, 0x1b7
	v_mad_i64_i32 v[16:17], s[14:15], v28, s33, v[120:121]
	v_lshl_add_u64 v[16:17], v[16:17], 0, v[122:123]
	global_store_short_d16_hi v[16:17], v18, off offset:32
	v_add_f32_e32 v16, 1.0, v19
	v_rcp_f32_e32 v18, v16
	v_or_b32_e32 v19, 0x70, v124
	v_mov_b32_e32 v20, v19
	v_mul_f32_e32 v8, v8, v18
	v_mul_f32_e32 v8, v12, v8
	v_cvt_pk_bf16_f32 v8, v8, v8
	v_mul_f32_e32 v12, 0xbfb8aa3b, v9
	v_exp_f32_e32 v12, v12
	v_mad_i64_i32 v[16:17], s[14:15], v20, s33, v[120:121]
	v_lshl_add_u64 v[16:17], v[16:17], 0, v[122:123]
	global_store_short_d16_hi v[16:17], v8, off
	v_add_f32_e32 v8, 1.0, v12
	v_rcp_f32_e32 v16, v8
	v_or_b32_e32 v17, 0x71, v124
	v_mov_b32_e32 v18, v17
	v_mul_f32_e32 v8, v9, v16
	v_mul_f32_e32 v8, v13, v8
	v_cvt_pk_bf16_f32 v12, v8, v8
	v_mul_f32_e32 v8, 0xbfb8aa3b, v10
	v_exp_f32_e32 v13, v8
	v_mad_i64_i32 v[8:9], s[14:15], v18, s33, v[120:121]
	v_lshl_add_u64 v[8:9], v[8:9], 0, v[122:123]
	global_store_short_d16_hi v[8:9], v12, off
	v_add_f32_e32 v8, 1.0, v13
	v_rcp_f32_e32 v12, v8
	v_or_b32_e32 v13, 0x72, v124
	v_mov_b32_e32 v16, v13
	v_mul_f32_e32 v8, v10, v12
	v_mul_f32_e32 v8, v14, v8
	v_cvt_pk_bf16_f32 v10, v8, v8
	v_mul_f32_e32 v8, 0xbfb8aa3b, v11
	v_exp_f32_e32 v12, v8
	v_mad_i64_i32 v[8:9], s[14:15], v16, s33, v[120:121]
	v_lshl_add_u64 v[8:9], v[8:9], 0, v[122:123]
	global_store_short_d16_hi v[8:9], v10, off
	v_add_f32_e32 v8, 1.0, v12
	v_rcp_f32_e32 v10, v8
	v_or_b32_e32 v12, 0x73, v124
	v_mov_b32_e32 v14, v12
	v_mul_f32_e32 v8, v11, v10
	v_mul_f32_e32 v10, 0xbfb8aa3b, v0
	v_exp_f32_e32 v10, v10
	v_mul_f32_e32 v8, v15, v8
	v_add_f32_e32 v10, 1.0, v10
	v_cvt_pk_bf16_f32 v11, v8, v8
	v_mad_i64_i32 v[8:9], s[14:15], v14, s33, v[120:121]
	v_rcp_f32_e32 v15, v10
	v_lshl_add_u64 v[8:9], v[8:9], 0, v[122:123]
	global_store_short_d16_hi v[8:9], v11, off
	v_mul_f32_e32 v0, v0, v15
	v_mul_f32_e32 v8, 0xbfb8aa3b, v1
	v_exp_f32_e32 v10, v8
	v_mul_f32_e32 v0, v4, v0
	v_cvt_pk_bf16_f32 v0, v0, v0
	v_add_f32_e32 v4, 1.0, v10
	v_rcp_f32_e32 v11, v4
	v_mad_i64_i32 v[8:9], s[14:15], v19, s33, v[120:121]
	v_lshl_add_u64 v[8:9], v[8:9], 0, v[122:123]
	global_store_short_d16_hi v[8:9], v0, off offset:32
	v_mul_f32_e32 v0, v1, v11
	v_mul_f32_e32 v4, 0xbfb8aa3b, v2
	v_exp_f32_e32 v4, v4
	v_mul_f32_e32 v0, v5, v0
	v_add_f32_e32 v4, 1.0, v4
	v_rcp_f32_e32 v9, v4
	v_cvt_pk_bf16_f32 v5, v0, v0
	v_mad_i64_i32 v[0:1], s[14:15], v17, s33, v[120:121]
	v_lshl_add_u64 v[0:1], v[0:1], 0, v[122:123]
	global_store_short_d16_hi v[0:1], v5, off offset:32
	v_mul_f32_e32 v0, v2, v9
	v_mul_f32_e32 v2, 0xbfb8aa3b, v3
	v_exp_f32_e32 v2, v2
	v_mul_f32_e32 v0, v6, v0
	v_add_f32_e32 v2, 1.0, v2
	v_rcp_f32_e32 v6, v2
	v_cvt_pk_bf16_f32 v4, v0, v0
	v_mad_i64_i32 v[0:1], s[14:15], v13, s33, v[120:121]
	v_lshl_add_u64 v[0:1], v[0:1], 0, v[122:123]
	global_store_short_d16_hi v[0:1], v4, off offset:32
	v_mul_f32_e32 v0, v3, v6
	v_mul_f32_e32 v0, v7, v0
	v_cvt_pk_bf16_f32 v2, v0, v0
	v_mad_i64_i32 v[0:1], s[14:15], v12, s33, v[120:121]
	v_lshl_add_u64 v[0:1], v[0:1], 0, v[122:123]
	global_store_short_d16_hi v[0:1], v2, off offset:32
	s_cbranch_scc0 .LBB0_1519

.LBB0_1576:
	s_ashr_i32 s16, s2, 31
	s_lshr_b32 s16, s16, 27
	s_add_i32 s16, s2, s16
	s_ashr_i32 s16, s16, 5
	s_lshl_b32 s17, s16, 2
	s_and_b32 s31, s2, 3
	s_add_i32 s34, s17, s18
	s_or_b32 s17, s34, s31
	s_lshl_b32 s31, s17, 7
	s_lshl_b32 s35, s16, 10
	s_lshl_b32 s16, s2, 5
	v_add_u32_e32 v2, s31, v83
	s_sub_i32 s16, s16, s35
	s_mov_b32 m0, s19
	s_and_b32 s33, s16, 0xffffff80
	v_mad_i64_i32 v[2:3], s[16:17], v2, s22, v[72:73]
	v_add_u32_e32 v0, s33, v83
	s_setprio 2
	global_load_lds_dwordx4 v[2:3], off
	v_lshl_add_u64 v[4:5], v[2:3], 0, s[0:1]
	s_mov_b32 m0, s23
	v_mad_i64_i32 v[0:1], s[16:17], v0, s22, v[70:71]
	global_load_lds_dwordx4 v[4:5], off
	s_mov_b32 m0, s24
	v_lshl_add_u64 v[4:5], v[0:1], 0, s[0:1]
	global_load_lds_dwordx4 v[0:1], off
	s_mov_b32 m0, s25
	s_sub_i32 s16, s20, s35
	global_load_lds_dwordx4 v[4:5], off
	v_lshl_add_u64 v[4:5], v[2:3], 0, 64
	s_mov_b32 m0, s26
	v_lshl_add_u64 v[2:3], v[2:3], 0, s[4:5]
	global_load_lds_dwordx4 v[4:5], off
	s_mov_b32 m0, s27
	s_and_b32 s36, s15, 3
	global_load_lds_dwordx4 v[2:3], off
	v_lshl_add_u64 v[2:3], v[0:1], 0, 64
	s_mov_b32 m0, s28
	v_lshl_add_u64 v[0:1], v[0:1], 0, s[4:5]
	global_load_lds_dwordx4 v[2:3], off
	s_mov_b32 m0, s29
	s_and_b32 s16, s16, 0xffffff80
	global_load_lds_dwordx4 v[0:1], off
	v_add_u32_e32 v0, s16, v83
	s_add_i32 s34, s34, s36
	v_mad_i64_i32 v[64:65], s[16:17], v0, s22, v[70:71]
	v_lshl_add_u32 v0, s34, 7, v83
	v_mad_i64_i32 v[66:67], s[16:17], v0, s22, v[72:73]
	s_mov_b64 s[16:17], 0
	s_mov_b32 s35, 2
	s_mov_b32 s34, 0
	v_mov_b32_e32 v0, 0
	v_mov_b32_e32 v1, v69
	v_mov_b32_e32 v2, v69
	v_mov_b32_e32 v3, v69
	v_mov_b32_e32 v4, 0
	v_mov_b32_e32 v5, v69
	v_mov_b32_e32 v6, v69
	v_mov_b32_e32 v7, v69
	v_mov_b32_e32 v8, 0
	v_mov_b32_e32 v9, v69
	v_mov_b32_e32 v10, v69
	v_mov_b32_e32 v11, v69
	v_mov_b32_e32 v12, 0
	v_mov_b32_e32 v13, v69
	v_mov_b32_e32 v14, v69
	v_mov_b32_e32 v15, v69
	v_mov_b32_e32 v16, 0
	v_mov_b32_e32 v17, v69
	v_mov_b32_e32 v18, v69
	v_mov_b32_e32 v19, v69
	v_mov_b32_e32 v20, 0
	v_mov_b32_e32 v21, v69
	v_mov_b32_e32 v22, v69
	v_mov_b32_e32 v23, v69
	v_mov_b32_e32 v24, 0
	v_mov_b32_e32 v25, v69
	v_mov_b32_e32 v26, v69
	v_mov_b32_e32 v27, v69
	v_mov_b32_e32 v28, 0
	v_mov_b32_e32 v29, v69
	v_mov_b32_e32 v30, v69
	v_mov_b32_e32 v31, v69
	v_mov_b32_e32 v32, 0
	v_mov_b32_e32 v33, v69
	v_mov_b32_e32 v34, v69
	v_mov_b32_e32 v35, v69
	v_mov_b32_e32 v36, 0
	v_mov_b32_e32 v37, v69
	v_mov_b32_e32 v38, v69
	v_mov_b32_e32 v39, v69
	v_mov_b32_e32 v40, 0
	v_mov_b32_e32 v41, v69
	v_mov_b32_e32 v42, v69
	v_mov_b32_e32 v43, v69
	v_mov_b32_e32 v44, 0
	v_mov_b32_e32 v45, v69
	v_mov_b32_e32 v46, v69
	v_mov_b32_e32 v47, v69
	v_mov_b32_e32 v48, 0
	v_mov_b32_e32 v49, v69
	v_mov_b32_e32 v50, v69
	v_mov_b32_e32 v51, v69
	v_mov_b32_e32 v52, 0
	v_mov_b32_e32 v53, v69
	v_mov_b32_e32 v54, v69
	v_mov_b32_e32 v55, v69
	v_mov_b32_e32 v56, 0
	v_mov_b32_e32 v57, v69
	v_mov_b32_e32 v58, v69
	v_mov_b32_e32 v59, v69
	v_mov_b32_e32 v60, 0
	v_mov_b32_e32 v61, v69
	v_mov_b32_e32 v62, v69
	v_mov_b32_e32 v63, v69
.LBB0_1577:
	s_lshl_b32 s36, s35, 14
	s_waitcnt vmcnt(0)
	v_lshl_add_u64 v[80:81], v[66:67], 0, s[16:17]
	s_add_i32 s36, s19, s36
	s_waitcnt lgkmcnt(0)
	s_barrier
	s_lshl_b32 s98, s34, 14
	v_add_u32_e32 v120, s98, v86
	v_or_b32_e32 v121, s98, v87
	ds_read_b128 v[76:79], v120
	ds_read_b128 v[90:93], v120 offset:1024
	ds_read_b128 v[94:97], v120 offset:2048
	ds_read_b128 v[98:101], v120 offset:3072
	ds_read_b128 v[102:105], v121
	ds_read_b128 v[106:109], v121 offset:1024
	ds_read_b128 v[110:113], v121 offset:2048
	ds_read_b128 v[114:117], v121 offset:3072
	v_lshl_add_u64 v[126:127], v[80:81], 0, s[6:7]
	s_mov_b32 m0, s36
	v_lshl_add_u64 v[118:119], v[64:65], 0, s[16:17]
	global_load_lds_dwordx4 v[126:127], off
	v_lshl_add_u64 v[126:127], v[80:81], 0, s[8:9]
	s_add_i32 m0, s36, 0x400
	s_nop 0
	global_load_lds_dwordx4 v[126:127], off
	s_add_i32 m0, s36, 0x2000
	v_lshl_add_u64 v[126:127], v[118:119], 0, s[6:7]
	global_load_lds_dwordx4 v[126:127], off
	s_add_i32 m0, s36, 0x2400
	s_lshl_b32 s36, s34, 14
	s_add_i32 s36, s34, 1
	s_cmp_lg_u32 s34, 3
	s_cselect_b32 s34, s36, 0
	s_add_i32 s36, s35, 1
	v_lshl_add_u64 v[126:127], v[118:119], 0, s[8:9]
	s_cmp_lg_u32 s35, 3
	global_load_lds_dwordx4 v[126:127], off
	s_cselect_b32 s35, s36, 0
	s_waitcnt lgkmcnt(0)
	s_lshl_b32 s36, s35, 14
	s_add_i32 s36, s19, s36
	v_mfma_f32_16x16x32_bf16 v[60:63], v[102:105], v[76:79], v[60:63]
	v_mfma_f32_16x16x32_bf16 v[56:59], v[106:109], v[76:79], v[56:59]
	s_mov_b32 m0, s36
	v_mfma_f32_16x16x32_bf16 v[52:55], v[110:113], v[76:79], v[52:55]
	v_mfma_f32_16x16x32_bf16 v[48:51], v[114:117], v[76:79], v[48:51]
	v_lshl_add_u64 v[76:77], v[80:81], 0, s[10:11]
	global_load_lds_dwordx4 v[76:77], off
	v_lshl_add_u64 v[76:77], v[80:81], 0, s[12:13]
	s_add_i32 m0, s36, 0x400
	v_mfma_f32_16x16x32_bf16 v[44:47], v[102:105], v[90:93], v[44:47]
	global_load_lds_dwordx4 v[76:77], off
	s_add_i32 m0, s36, 0x2000
	v_lshl_add_u64 v[76:77], v[118:119], 0, s[10:11]
	global_load_lds_dwordx4 v[76:77], off
	v_lshl_add_u64 v[76:77], v[118:119], 0, s[12:13]
	s_add_i32 m0, s36, 0x2400
	v_mfma_f32_16x16x32_bf16 v[40:43], v[106:109], v[90:93], v[40:43]
	global_load_lds_dwordx4 v[76:77], off
	s_lshl_b32 s36, s34, 14
	v_mfma_f32_16x16x32_bf16 v[36:39], v[110:113], v[90:93], v[36:39]
	v_add_u32_e32 v80, s36, v86
	v_or_b32_e32 v81, s36, v87
	s_add_i32 s36, s34, 1
	v_mfma_f32_16x16x32_bf16 v[32:35], v[114:117], v[90:93], v[32:35]
	s_cmp_lg_u32 s34, 3
	s_cselect_b32 s34, s36, 0
	s_add_i32 s36, s35, 1
	v_mfma_f32_16x16x32_bf16 v[28:31], v[102:105], v[94:97], v[28:31]
	s_cmp_lg_u32 s35, 3
	s_cselect_b32 s35, s36, 0
	s_add_u32 s16, s16, 0x80
	v_mfma_f32_16x16x32_bf16 v[24:27], v[106:109], v[94:97], v[24:27]
	s_addc_u32 s17, s17, 0
	s_cmpk_eq_i32 s16, 0x1580
	v_mfma_f32_16x16x32_bf16 v[20:23], v[110:113], v[94:97], v[20:23]
	v_mfma_f32_16x16x32_bf16 v[16:19], v[114:117], v[94:97], v[16:19]
	v_mfma_f32_16x16x32_bf16 v[12:15], v[102:105], v[98:101], v[12:15]
	v_mfma_f32_16x16x32_bf16 v[8:11], v[106:109], v[98:101], v[8:11]
	v_mfma_f32_16x16x32_bf16 v[4:7], v[110:113], v[98:101], v[4:7]
	v_mfma_f32_16x16x32_bf16 v[0:3], v[114:117], v[98:101], v[0:3]
	ds_read_b128 v[76:79], v80
	ds_read_b128 v[90:93], v80 offset:1024
	ds_read_b128 v[94:97], v80 offset:2048
	ds_read_b128 v[98:101], v80 offset:3072
	ds_read_b128 v[102:105], v81
	ds_read_b128 v[106:109], v81 offset:1024
	ds_read_b128 v[110:113], v81 offset:2048
	ds_read_b128 v[114:117], v81 offset:3072
	s_waitcnt lgkmcnt(0)
	s_nop 0
	v_mfma_f32_16x16x32_bf16 v[60:63], v[102:105], v[76:79], v[60:63]
	v_mfma_f32_16x16x32_bf16 v[56:59], v[106:109], v[76:79], v[56:59]
	v_mfma_f32_16x16x32_bf16 v[52:55], v[110:113], v[76:79], v[52:55]
	v_mfma_f32_16x16x32_bf16 v[48:51], v[114:117], v[76:79], v[48:51]
	v_mfma_f32_16x16x32_bf16 v[44:47], v[102:105], v[90:93], v[44:47]
	v_mfma_f32_16x16x32_bf16 v[40:43], v[106:109], v[90:93], v[40:43]
	v_mfma_f32_16x16x32_bf16 v[36:39], v[110:113], v[90:93], v[36:39]
	v_mfma_f32_16x16x32_bf16 v[32:35], v[114:117], v[90:93], v[32:35]
	v_mfma_f32_16x16x32_bf16 v[28:31], v[102:105], v[94:97], v[28:31]
	v_mfma_f32_16x16x32_bf16 v[24:27], v[106:109], v[94:97], v[24:27]
	v_mfma_f32_16x16x32_bf16 v[20:23], v[110:113], v[94:97], v[20:23]
	v_mfma_f32_16x16x32_bf16 v[16:19], v[114:117], v[94:97], v[16:19]
	v_mfma_f32_16x16x32_bf16 v[12:15], v[102:105], v[98:101], v[12:15]
	v_mfma_f32_16x16x32_bf16 v[8:11], v[106:109], v[98:101], v[8:11]
	v_mfma_f32_16x16x32_bf16 v[4:7], v[110:113], v[98:101], v[4:7]
	v_mfma_f32_16x16x32_bf16 v[0:3], v[114:117], v[98:101], v[0:3]
	s_cbranch_scc0 .LBB0_1577
	s_waitcnt vmcnt(4)
	s_waitcnt lgkmcnt(0)
	s_barrier
	ds_read_b128 v[64:67], v86 offset:32768
	ds_read_b128 v[76:79], v86 offset:33792
	ds_read_b128 v[90:93], v86 offset:34816
	ds_read_b128 v[94:97], v86 offset:35840
	ds_read_b128 v[98:101], v87 offset:32768
	ds_read_b128 v[102:105], v87 offset:33792
	ds_read_b128 v[106:109], v87 offset:34816
	ds_read_b128 v[110:113], v87 offset:35840
	s_waitcnt lgkmcnt(0)
	s_waitcnt vmcnt(0)
	s_waitcnt lgkmcnt(0)
	s_barrier
	v_mfma_f32_16x16x32_bf16 v[56:59], v[102:105], v[64:67], v[56:59]
	s_movk_i32 s16, 0xfff
	v_readlane_b32 s36, v241, 1
	v_mfma_f32_16x16x32_bf16 v[40:43], v[102:105], v[76:79], v[40:43]
	v_readlane_b32 s44, v241, 9
	v_readlane_b32 s45, v241, 10
	s_add_i32 s2, s2, s3
	v_mfma_f32_16x16x32_bf16 v[24:27], v[102:105], v[90:93], v[24:27]
	s_add_i32 s20, s20, s21
	v_readlane_b32 s37, v241, 2
	v_readlane_b32 s38, v241, 3
	v_mfma_f32_16x16x32_bf16 v[52:55], v[106:109], v[64:67], v[52:55]
	v_readlane_b32 s39, v241, 4
	v_readlane_b32 s40, v241, 5
	v_readlane_b32 s41, v241, 6
	v_mfma_f32_16x16x32_bf16 v[36:39], v[106:109], v[76:79], v[36:39]
	v_readlane_b32 s42, v241, 7
	v_readlane_b32 s43, v241, 8
	v_readlane_b32 s46, v241, 11
	v_mfma_f32_16x16x32_bf16 v[20:23], v[106:109], v[90:93], v[20:23]
	v_readlane_b32 s47, v241, 12
	v_readlane_b32 s48, v241, 13
	v_readlane_b32 s49, v241, 14
	v_mfma_f32_16x16x32_bf16 v[60:63], v[98:101], v[64:67], v[60:63]
	v_readlane_b32 s50, v241, 15
	v_readlane_b32 s51, v241, 16
	v_mfma_f32_16x16x32_bf16 v[48:51], v[110:113], v[64:67], v[48:51]
	v_mfma_f32_16x16x32_bf16 v[44:47], v[98:101], v[76:79], v[44:47]
	v_mfma_f32_16x16x32_bf16 v[32:35], v[110:113], v[76:79], v[32:35]
	v_mfma_f32_16x16x32_bf16 v[28:31], v[98:101], v[90:93], v[28:31]
	v_mfma_f32_16x16x32_bf16 v[16:19], v[110:113], v[90:93], v[16:19]
	v_mfma_f32_16x16x32_bf16 v[12:15], v[98:101], v[94:97], v[12:15]
	v_mfma_f32_16x16x32_bf16 v[8:11], v[102:105], v[94:97], v[8:11]
	v_mfma_f32_16x16x32_bf16 v[4:7], v[106:109], v[94:97], v[4:7]
	v_mfma_f32_16x16x32_bf16 v[0:3], v[110:113], v[94:97], v[0:3]
	ds_read_b128 v[64:67], v86 offset:49152
	ds_read_b128 v[76:79], v86 offset:50176
	ds_read_b128 v[90:93], v86 offset:51200
	ds_read_b128 v[94:97], v86 offset:52224
	ds_read_b128 v[98:101], v87 offset:49152
	ds_read_b128 v[102:105], v87 offset:50176
	ds_read_b128 v[106:109], v87 offset:51200
	ds_read_b128 v[110:113], v87 offset:52224
	s_waitcnt lgkmcnt(0)
	s_waitcnt lgkmcnt(0)
	s_barrier
	v_mfma_f32_16x16x32_bf16 v[118:121], v[102:105], v[64:67], v[56:59]
	v_mfma_f32_16x16x32_bf16 v[56:59], v[102:105], v[76:79], v[40:43]
	v_mfma_f32_16x16x32_bf16 v[40:43], v[102:105], v[90:93], v[24:27]
	s_nop 2
	v_add_u32_e32 v24, s31, v84
	v_mfma_f32_16x16x32_bf16 v[122:125], v[106:109], v[64:67], v[52:55]
	v_cmp_lt_i32_e32 vcc, s16, v24
	s_movk_i32 s16, 0x6000
	v_mfma_f32_16x16x32_bf16 v[52:55], v[106:109], v[76:79], v[36:39]
	v_mfma_f32_16x16x32_bf16 v[36:39], v[106:109], v[90:93], v[20:23]
	s_nop 2
	v_add_u32_e32 v21, 0xfffff000, v24
	v_lshrrev_b32_e32 v21, 12, v21
	v_add_u32_e32 v21, 1, v21
	v_or_b32_e32 v20, s33, v85
	v_cndmask_b32_e32 v21, 0, v21, vcc
	v_mad_u64_u32 v[22:23], s[16:17], v21, s16, v[74:75]
	v_ashrrev_i32_e32 v21, 31, v20
	v_mfma_f32_16x16x32_bf16 v[114:117], v[98:101], v[64:67], v[60:63]
	s_mov_b64 s[16:17], 0x5000
	v_mfma_f32_16x16x32_bf16 v[64:67], v[110:113], v[64:67], v[48:51]
	v_mfma_f32_16x16x32_bf16 v[60:63], v[98:101], v[76:79], v[44:47]
	v_mfma_f32_16x16x32_bf16 v[48:51], v[110:113], v[76:79], v[32:35]
	v_lshlrev_b64 v[76:77], 2, v[20:21]
	v_lshl_add_u64 v[20:21], v[22:23], 0, v[76:77]
	v_lshl_add_u64 v[20:21], v[20:21], 0, v[68:69]
	v_lshl_add_u64 v[22:23], v[20:21], 0, s[16:17]
	s_movk_i32 s16, 0x5000
	v_add_co_u32_e32 v20, vcc, s16, v20
	v_mfma_f32_16x16x32_bf16 v[44:47], v[98:101], v[90:93], v[28:31]
	s_nop 0
	v_addc_co_u32_e32 v21, vcc, 0, v21, vcc
	v_mfma_f32_16x16x32_bf16 v[16:19], v[110:113], v[90:93], v[16:19]
	v_or_b32_e32 v90, v24, v82
	v_or_b32_e32 v80, 32, v90
	v_or_b32_e32 v78, 48, v90
	v_mfma_f32_16x16x32_bf16 v[12:15], v[98:101], v[94:97], v[12:15]
	global_load_dwordx4 v[32:35], v[20:21], off
	global_load_dwordx4 v[28:31], v[22:23], off offset:64
	global_load_dwordx4 v[24:27], v[22:23], off offset:128
	s_nop 0
	global_load_dwordx4 v[20:23], v[22:23], off offset:192
	v_mfma_f32_16x16x32_bf16 v[8:11], v[102:105], v[94:97], v[8:11]
	v_mfma_f32_16x16x32_bf16 v[4:7], v[106:109], v[94:97], v[4:7]
	v_mfma_f32_16x16x32_bf16 v[0:3], v[110:113], v[94:97], v[0:3]
	s_setprio 0
	v_or_b32_e32 v94, 16, v90
	s_nop 0
	v_mov_b32_e32 v192, v90
	v_ashrrev_i32_e32 v193, 31, v90
	v_lshlrev_b64 v[192:193], 12, v[192:193]
	v_lshl_add_u64 v[192:193], s[44:45], 0, v[192:193]
	v_lshl_add_u64 v[192:193], v[192:193], 0, v[76:77]
	v_lshl_add_u64 v[192:193], v[192:193], 0, v[68:69]
	v_mov_b32_e32 v194, v94
	v_ashrrev_i32_e32 v195, 31, v94
	v_lshlrev_b64 v[194:195], 12, v[194:195]
	v_lshl_add_u64 v[194:195], s[44:45], 0, v[194:195]
	v_lshl_add_u64 v[194:195], v[194:195], 0, v[76:77]
	v_lshl_add_u64 v[194:195], v[194:195], 0, v[68:69]
	v_mov_b32_e32 v196, v80
	v_ashrrev_i32_e32 v197, 31, v80
	v_lshlrev_b64 v[196:197], 12, v[196:197]
	v_lshl_add_u64 v[196:197], s[44:45], 0, v[196:197]
	v_lshl_add_u64 v[196:197], v[196:197], 0, v[76:77]
	v_lshl_add_u64 v[196:197], v[196:197], 0, v[68:69]
	v_mov_b32_e32 v198, v78
	v_ashrrev_i32_e32 v199, 31, v78
	v_lshlrev_b64 v[198:199], 12, v[198:199]
	v_lshl_add_u64 v[198:199], s[44:45], 0, v[198:199]
	v_lshl_add_u64 v[198:199], v[198:199], 0, v[76:77]
	v_lshl_add_u64 v[198:199], v[198:199], 0, v[68:69]
	global_load_dwordx4 v[128:131], v[192:193], off
	global_load_dwordx4 v[132:135], v[192:193], off offset:64
	global_load_dwordx4 v[136:139], v[192:193], off offset:128
	global_load_dwordx4 v[140:143], v[192:193], off offset:192
	global_load_dwordx4 v[144:147], v[194:195], off
	global_load_dwordx4 v[148:151], v[194:195], off offset:64
	global_load_dwordx4 v[152:155], v[194:195], off offset:128
	global_load_dwordx4 v[156:159], v[194:195], off offset:192
	global_load_dwordx4 v[160:163], v[196:197], off
	global_load_dwordx4 v[164:167], v[196:197], off offset:64
	global_load_dwordx4 v[168:171], v[196:197], off offset:128
	global_load_dwordx4 v[172:175], v[196:197], off offset:192
	global_load_dwordx4 v[176:179], v[198:199], off
	global_load_dwordx4 v[180:183], v[198:199], off offset:64
	global_load_dwordx4 v[184:187], v[198:199], off offset:128
	global_load_dwordx4 v[188:191], v[198:199], off offset:192
	s_waitcnt vmcnt(15)
	v_pk_mul_f32 v[128:129], v[128:129], s[14:15] op_sel_hi:[1,0]
	v_pk_mul_f32 v[130:131], v[130:131], s[14:15] op_sel_hi:[1,0]
	v_pk_fma_f32 v[128:129], v[114:115], v[32:33], v[128:129]
	v_pk_fma_f32 v[130:131], v[116:117], v[34:35], v[130:131]
	global_store_dwordx4 v[192:193], v[128:131], off
	s_waitcnt vmcnt(15)
	v_pk_mul_f32 v[132:133], v[132:133], s[14:15] op_sel_hi:[1,0]
	v_pk_mul_f32 v[134:135], v[134:135], s[14:15] op_sel_hi:[1,0]
	v_pk_fma_f32 v[132:133], v[118:119], v[28:29], v[132:133]
	v_pk_fma_f32 v[134:135], v[120:121], v[30:31], v[134:135]
	global_store_dwordx4 v[192:193], v[132:135], off offset:64
	s_waitcnt vmcnt(15)
	v_pk_mul_f32 v[136:137], v[136:137], s[14:15] op_sel_hi:[1,0]
	v_pk_mul_f32 v[138:139], v[138:139], s[14:15] op_sel_hi:[1,0]
	v_pk_fma_f32 v[136:137], v[122:123], v[24:25], v[136:137]
	v_pk_fma_f32 v[138:139], v[124:125], v[26:27], v[138:139]
	global_store_dwordx4 v[192:193], v[136:139], off offset:128
	s_waitcnt vmcnt(15)
	v_pk_mul_f32 v[140:141], v[140:141], s[14:15] op_sel_hi:[1,0]
	v_pk_fma_f32 v[64:65], v[64:65], v[20:21], v[140:141]
	v_pk_mul_f32 v[140:141], v[142:143], s[14:15] op_sel_hi:[1,0]
	v_pk_fma_f32 v[66:67], v[66:67], v[22:23], v[140:141]
	global_store_dwordx4 v[192:193], v[64:67], off offset:192
	s_waitcnt vmcnt(15)
	v_pk_mul_f32 v[144:145], v[144:145], s[14:15] op_sel_hi:[1,0]
	v_pk_fma_f32 v[60:61], v[60:61], v[32:33], v[144:145]
	v_pk_mul_f32 v[144:145], v[146:147], s[14:15] op_sel_hi:[1,0]
	v_pk_fma_f32 v[62:63], v[62:63], v[34:35], v[144:145]
	global_store_dwordx4 v[194:195], v[60:63], off
	s_waitcnt vmcnt(15)
	v_pk_mul_f32 v[148:149], v[148:149], s[14:15] op_sel_hi:[1,0]
	v_pk_fma_f32 v[56:57], v[56:57], v[28:29], v[148:149]
	v_pk_mul_f32 v[148:149], v[150:151], s[14:15] op_sel_hi:[1,0]
	v_pk_fma_f32 v[58:59], v[58:59], v[30:31], v[148:149]
	global_store_dwordx4 v[194:195], v[56:59], off offset:64
	s_waitcnt vmcnt(15)
	v_pk_mul_f32 v[152:153], v[152:153], s[14:15] op_sel_hi:[1,0]
	v_pk_fma_f32 v[52:53], v[52:53], v[24:25], v[152:153]
	v_pk_mul_f32 v[152:153], v[154:155], s[14:15] op_sel_hi:[1,0]
	v_pk_fma_f32 v[54:55], v[54:55], v[26:27], v[152:153]
	global_store_dwordx4 v[194:195], v[52:55], off offset:128
	s_waitcnt vmcnt(15)
	v_pk_mul_f32 v[156:157], v[156:157], s[14:15] op_sel_hi:[1,0]
	v_pk_fma_f32 v[48:49], v[48:49], v[20:21], v[156:157]
	v_pk_mul_f32 v[156:157], v[158:159], s[14:15] op_sel_hi:[1,0]
	v_pk_fma_f32 v[50:51], v[50:51], v[22:23], v[156:157]
	global_store_dwordx4 v[194:195], v[48:51], off offset:192
	s_waitcnt vmcnt(15)
	v_pk_mul_f32 v[160:161], v[160:161], s[14:15] op_sel_hi:[1,0]
	v_pk_fma_f32 v[44:45], v[44:45], v[32:33], v[160:161]
	v_pk_mul_f32 v[160:161], v[162:163], s[14:15] op_sel_hi:[1,0]
	v_pk_fma_f32 v[46:47], v[46:47], v[34:35], v[160:161]
	global_store_dwordx4 v[196:197], v[44:47], off
	s_waitcnt vmcnt(15)
	v_pk_mul_f32 v[164:165], v[164:165], s[14:15] op_sel_hi:[1,0]
	v_pk_fma_f32 v[40:41], v[40:41], v[28:29], v[164:165]
	v_pk_mul_f32 v[164:165], v[166:167], s[14:15] op_sel_hi:[1,0]
	v_pk_fma_f32 v[42:43], v[42:43], v[30:31], v[164:165]
	global_store_dwordx4 v[196:197], v[40:43], off offset:64
	s_waitcnt vmcnt(15)
	v_pk_mul_f32 v[168:169], v[168:169], s[14:15] op_sel_hi:[1,0]
	v_pk_fma_f32 v[36:37], v[36:37], v[24:25], v[168:169]
	v_pk_mul_f32 v[168:169], v[170:171], s[14:15] op_sel_hi:[1,0]
	v_pk_fma_f32 v[38:39], v[38:39], v[26:27], v[168:169]
	global_store_dwordx4 v[196:197], v[36:39], off offset:128
	s_waitcnt vmcnt(15)
	v_pk_mul_f32 v[172:173], v[172:173], s[14:15] op_sel_hi:[1,0]
	v_pk_fma_f32 v[16:17], v[16:17], v[20:21], v[172:173]
	v_pk_mul_f32 v[172:173], v[174:175], s[14:15] op_sel_hi:[1,0]
	v_pk_fma_f32 v[18:19], v[18:19], v[22:23], v[172:173]
	global_store_dwordx4 v[196:197], v[16:19], off offset:192
	s_waitcnt vmcnt(15)
	v_pk_mul_f32 v[176:177], v[176:177], s[14:15] op_sel_hi:[1,0]
	v_pk_fma_f32 v[12:13], v[12:13], v[32:33], v[176:177]
	v_pk_mul_f32 v[176:177], v[178:179], s[14:15] op_sel_hi:[1,0]
	v_pk_fma_f32 v[14:15], v[14:15], v[34:35], v[176:177]
	global_store_dwordx4 v[198:199], v[12:15], off
	s_waitcnt vmcnt(15)
	v_pk_mul_f32 v[180:181], v[180:181], s[14:15] op_sel_hi:[1,0]
	v_pk_fma_f32 v[8:9], v[8:9], v[28:29], v[180:181]
	v_pk_mul_f32 v[180:181], v[182:183], s[14:15] op_sel_hi:[1,0]
	v_pk_fma_f32 v[10:11], v[10:11], v[30:31], v[180:181]
	global_store_dwordx4 v[198:199], v[8:11], off offset:64
	s_waitcnt vmcnt(15)
	v_pk_mul_f32 v[184:185], v[184:185], s[14:15] op_sel_hi:[1,0]
	v_pk_fma_f32 v[4:5], v[4:5], v[24:25], v[184:185]
	v_pk_mul_f32 v[184:185], v[186:187], s[14:15] op_sel_hi:[1,0]
	v_pk_fma_f32 v[6:7], v[6:7], v[26:27], v[184:185]
	global_store_dwordx4 v[198:199], v[4:7], off offset:128
	s_waitcnt vmcnt(15)
	v_pk_mul_f32 v[188:189], v[188:189], s[14:15] op_sel_hi:[1,0]
	v_pk_fma_f32 v[0:1], v[0:1], v[20:21], v[188:189]
	v_pk_mul_f32 v[188:189], v[190:191], s[14:15] op_sel_hi:[1,0]
	s_add_i32 s15, s15, s30
	v_pk_fma_f32 v[2:3], v[2:3], v[22:23], v[188:189]
	s_cmpk_gt_i32 s2, 0x9f
	global_store_dwordx4 v[198:199], v[0:3], off offset:192
	s_cbranch_scc0 .LBB0_1576

.LBB0_1691:
	s_mul_hi_i32 s0, s2, 0x2e8ba2e9
	s_lshr_b32 s1, s0, 31
	s_ashr_i32 s0, s0, 3
	s_add_i32 s6, s0, s1
	s_lshl_b32 s4, s6, 1
	s_and_b32 s1, s2, 1
	s_add_i32 s7, s4, s22
	s_or_b32 s1, s7, s1
	s_lshl_b32 s4, s1, 8
	s_mul_i32 s0, s6, 0xffffffd4
	v_add_u32_e32 v0, s4, v147
	s_add_i32 s0, s0, s2
	v_ashrrev_i32_e32 v1, 31, v0
	v_lshlrev_b64 v[0:1], 11, v[0:1]
	s_lshl_b32 s44, s0, 6
	s_mov_b32 m0, s23
	v_lshl_add_u64 v[0:1], v[132:133], 0, v[0:1]
	s_and_b32 s5, s44, 0xffffff80
	v_add_u32_e32 v2, s5, v148
	s_setprio 2
	global_load_lds_dwordx4 v[0:1], off
	v_lshl_add_u64 v[4:5], v[0:1], 0, s[16:17]
	s_mov_b32 m0, s27
	s_mov_b64 s[0:1], 0x10000
	v_ashrrev_i32_e32 v3, 31, v2
	global_load_lds_dwordx4 v[4:5], off
	v_lshl_add_u64 v[4:5], v[0:1], 0, s[0:1]
	s_mov_b32 m0, s28
	s_mov_b64 s[0:1], 0x18000
	v_lshlrev_b64 v[2:3], 11, v[2:3]
	global_load_lds_dwordx4 v[4:5], off
	v_lshl_add_u64 v[4:5], v[0:1], 0, s[0:1]
	s_mov_b32 m0, s29
	v_lshl_add_u64 v[2:3], v[136:137], 0, v[2:3]
	global_load_lds_dwordx4 v[4:5], off
	s_mov_b32 m0, s30
	v_lshl_add_u64 v[4:5], v[2:3], 0, s[16:17]
	global_load_lds_dwordx4 v[2:3], off
	s_mov_b32 m0, s31
	s_mov_b64 s[0:1], 0x10040
	global_load_lds_dwordx4 v[4:5], off
	v_lshl_add_u64 v[4:5], v[0:1], 0, 64
	s_mov_b32 m0, s33
	s_mulk_i32 s6, 0xb00
	global_load_lds_dwordx4 v[4:5], off
	v_lshl_add_u64 v[4:5], v[0:1], 0, s[18:19]
	s_mov_b32 m0, s34
	v_cndmask_b32_e64 v6, 0, 1, s[12:13]
	global_load_lds_dwordx4 v[4:5], off
	v_lshl_add_u64 v[4:5], v[0:1], 0, s[0:1]
	s_mov_b32 m0, s35
	s_mov_b64 s[0:1], 0x18040
	global_load_lds_dwordx4 v[4:5], off
	v_lshl_add_u64 v[0:1], v[0:1], 0, s[0:1]
	s_mov_b32 m0, s36
	s_sub_i32 s0, s25, s6
	global_load_lds_dwordx4 v[0:1], off
	v_lshl_add_u64 v[0:1], v[2:3], 0, 64
	s_mov_b32 m0, s37
	s_and_b32 s0, s0, 0xffffff80
	global_load_lds_dwordx4 v[0:1], off
	v_lshl_add_u64 v[0:1], v[2:3], 0, s[18:19]
	s_mov_b32 m0, s38
	s_mov_b32 s6, 2
	global_load_lds_dwordx4 v[0:1], off
	v_add_u32_e32 v0, s0, v148
	v_ashrrev_i32_e32 v1, 31, v0
	v_lshlrev_b64 v[0:1], 11, v[0:1]
	v_lshl_add_u64 v[140:141], v[134:135], 0, v[0:1]
	v_add_u32_e32 v0, s7, v6
	v_lshl_add_u32 v0, v0, 8, v147
	v_ashrrev_i32_e32 v1, 31, v0
	v_lshlrev_b64 v[0:1], 11, v[0:1]
	v_lshl_add_u64 v[142:143], v[132:133], 0, v[0:1]
	s_mov_b64 s[0:1], 0
	s_mov_b32 s7, 0
	v_mov_b32_e32 v0, 0
	v_mov_b32_e32 v1, v131
	v_mov_b32_e32 v2, v131
	v_mov_b32_e32 v3, v131
	v_mov_b32_e32 v4, 0
	v_mov_b32_e32 v5, v131
	v_mov_b32_e32 v6, v131
	v_mov_b32_e32 v7, v131
	v_mov_b32_e32 v8, 0
	v_mov_b32_e32 v9, v131
	v_mov_b32_e32 v10, v131
	v_mov_b32_e32 v11, v131
	v_mov_b32_e32 v12, 0
	v_mov_b32_e32 v13, v131
	v_mov_b32_e32 v14, v131
	v_mov_b32_e32 v15, v131
	v_mov_b32_e32 v16, 0
	v_mov_b32_e32 v17, v131
	v_mov_b32_e32 v18, v131
	v_mov_b32_e32 v19, v131
	v_mov_b32_e32 v20, 0
	v_mov_b32_e32 v21, v131
	v_mov_b32_e32 v22, v131
	v_mov_b32_e32 v23, v131
	v_mov_b32_e32 v24, 0
	v_mov_b32_e32 v25, v131
	v_mov_b32_e32 v26, v131
	v_mov_b32_e32 v27, v131
	v_mov_b32_e32 v28, 0
	v_mov_b32_e32 v29, v131
	v_mov_b32_e32 v30, v131
	v_mov_b32_e32 v31, v131
	v_mov_b32_e32 v32, 0
	v_mov_b32_e32 v33, v131
	v_mov_b32_e32 v34, v131
	v_mov_b32_e32 v35, v131
	v_mov_b32_e32 v36, 0
	v_mov_b32_e32 v37, v131
	v_mov_b32_e32 v38, v131
	v_mov_b32_e32 v39, v131
	v_mov_b32_e32 v44, 0
	v_mov_b32_e32 v45, v131
	v_mov_b32_e32 v46, v131
	v_mov_b32_e32 v47, v131
	v_mov_b32_e32 v52, 0
	v_mov_b32_e32 v53, v131
	v_mov_b32_e32 v54, v131
	v_mov_b32_e32 v55, v131
	v_mov_b32_e32 v60, 0
	v_mov_b32_e32 v61, v131
	v_mov_b32_e32 v62, v131
	v_mov_b32_e32 v63, v131
	v_mov_b32_e32 v68, 0
	v_mov_b32_e32 v69, v131
	v_mov_b32_e32 v70, v131
	v_mov_b32_e32 v71, v131
	v_mov_b32_e32 v76, 0
	v_mov_b32_e32 v77, v131
	v_mov_b32_e32 v78, v131
	v_mov_b32_e32 v79, v131
	v_mov_b32_e32 v84, 0
	v_mov_b32_e32 v85, v131
	v_mov_b32_e32 v86, v131
	v_mov_b32_e32 v87, v131
	v_mov_b32_e32 v40, 0
	v_mov_b32_e32 v41, v131
	v_mov_b32_e32 v42, v131
	v_mov_b32_e32 v43, v131
	v_mov_b32_e32 v48, 0
	v_mov_b32_e32 v49, v131
	v_mov_b32_e32 v50, v131
	v_mov_b32_e32 v51, v131
	v_mov_b32_e32 v56, 0
	v_mov_b32_e32 v57, v131
	v_mov_b32_e32 v58, v131
	v_mov_b32_e32 v59, v131
	v_mov_b32_e32 v64, 0
	v_mov_b32_e32 v65, v131
	v_mov_b32_e32 v66, v131
	v_mov_b32_e32 v67, v131
	v_mov_b32_e32 v72, 0
	v_mov_b32_e32 v73, v131
	v_mov_b32_e32 v74, v131
	v_mov_b32_e32 v75, v131
	v_mov_b32_e32 v80, 0
	v_mov_b32_e32 v81, v131
	v_mov_b32_e32 v82, v131
	v_mov_b32_e32 v83, v131
	v_mov_b32_e32 v88, 0
	v_mov_b32_e32 v89, v131
	v_mov_b32_e32 v90, v131
	v_mov_b32_e32 v91, v131
	v_mov_b32_e32 v92, 0
	v_mov_b32_e32 v93, v131
	v_mov_b32_e32 v94, v131
	v_mov_b32_e32 v95, v131
	v_mov_b32_e32 v96, 0
	v_mov_b32_e32 v97, v131
	v_mov_b32_e32 v98, v131
	v_mov_b32_e32 v99, v131
	v_mov_b32_e32 v100, 0
	v_mov_b32_e32 v101, v131
	v_mov_b32_e32 v102, v131
	v_mov_b32_e32 v103, v131
	v_mov_b32_e32 v104, 0
	v_mov_b32_e32 v105, v131
	v_mov_b32_e32 v106, v131
	v_mov_b32_e32 v107, v131
	v_mov_b32_e32 v108, 0
	v_mov_b32_e32 v109, v131
	v_mov_b32_e32 v110, v131
	v_mov_b32_e32 v111, v131
	v_mov_b32_e32 v112, 0
	v_mov_b32_e32 v113, v131
	v_mov_b32_e32 v114, v131
	v_mov_b32_e32 v115, v131
	v_mov_b32_e32 v116, 0
	v_mov_b32_e32 v117, v131
	v_mov_b32_e32 v118, v131
	v_mov_b32_e32 v119, v131
	v_mov_b32_e32 v120, 0
	v_mov_b32_e32 v121, v131
	v_mov_b32_e32 v122, v131
	v_mov_b32_e32 v123, v131
	v_mov_b32_e32 v124, 0
	v_mov_b32_e32 v125, v131
	v_mov_b32_e32 v126, v131
	v_mov_b32_e32 v127, v131
.LBB0_1692:
	s_mul_i32 s8, s6, 0x6000
	s_waitcnt vmcnt(6)
	s_add_i32 s10, s23, s8
	s_mul_i32 s98, s7, 0x6000
	v_lshl_add_u64 v[186:187], v[142:143], 0, s[0:1]
	v_lshl_add_u64 v[204:205], v[140:141], 0, s[0:1]
	s_add_i32 s99, s10, s24
	s_waitcnt lgkmcnt(0)
	s_barrier
	v_add_u32_e32 v184, s98, v144
	v_add_u32_e32 v185, s98, v146
	ds_read_b128 v[168:171], v185
	ds_read_b128 v[152:155], v184
	ds_read_b128 v[172:175], v185 offset:1024
	ds_read_b128 v[176:179], v185 offset:2048
	ds_read_b128 v[180:183], v185 offset:3072
	ds_read_b128 v[156:159], v184 offset:1024
	ds_read_b128 v[160:163], v184 offset:2048
	ds_read_b128 v[164:167], v184 offset:3072
	ds_read_b128 v[188:191], v184 offset:4096
	ds_read_b128 v[192:195], v184 offset:5120
	ds_read_b128 v[196:199], v184 offset:6144
	ds_read_b128 v[200:203], v184 offset:7168
	s_mov_b64 s[100:101], 0x80
	v_lshl_add_u64 v[206:207], v[186:187], 0, s[100:101]
	s_mov_b32 m0, s10
	s_waitcnt lgkmcnt(10)
	v_mfma_f32_16x16x32_bf16 v[84:87], v[152:155], v[168:171], v[84:87]
	global_load_lds_dwordx4 v[206:207], off
	s_waitcnt lgkmcnt(9)
	v_mfma_f32_16x16x32_bf16 v[76:79], v[152:155], v[172:175], v[76:79]
	s_mov_b64 s[100:101], 0x8080
	v_lshl_add_u64 v[206:207], v[186:187], 0, s[100:101]
	s_add_i32 m0, s10, 0x400
	s_waitcnt lgkmcnt(8)
	v_mfma_f32_16x16x32_bf16 v[68:71], v[152:155], v[176:179], v[68:71]
	global_load_lds_dwordx4 v[206:207], off
	s_waitcnt lgkmcnt(7)
	v_mfma_f32_16x16x32_bf16 v[60:63], v[152:155], v[180:183], v[60:63]
	s_mov_b64 s[100:101], 0x10080
	v_lshl_add_u64 v[206:207], v[186:187], 0, s[100:101]
	s_add_i32 m0, s10, 0x800
	s_waitcnt lgkmcnt(6)
	v_mfma_f32_16x16x32_bf16 v[52:55], v[156:159], v[168:171], v[52:55]
	global_load_lds_dwordx4 v[206:207], off
	v_mfma_f32_16x16x32_bf16 v[44:47], v[156:159], v[172:175], v[44:47]
	v_mfma_f32_16x16x32_bf16 v[36:39], v[156:159], v[176:179], v[36:39]
	s_mov_b64 s[100:101], 0x18080
	v_lshl_add_u64 v[206:207], v[186:187], 0, s[100:101]
	s_add_i32 m0, s10, 0xc00
	v_mfma_f32_16x16x32_bf16 v[32:35], v[156:159], v[180:183], v[32:35]
	global_load_lds_dwordx4 v[206:207], off
	s_waitcnt lgkmcnt(5)
	v_mfma_f32_16x16x32_bf16 v[28:31], v[160:163], v[168:171], v[28:31]
	s_mov_b64 s[100:101], 0x580080
	v_lshl_add_u64 v[206:207], v[204:205], 0, s[100:101]
	s_add_i32 m0, s99, 0x4000
	v_mfma_f32_16x16x32_bf16 v[24:27], v[160:163], v[172:175], v[24:27]
	global_load_lds_dwordx4 v[206:207], off
	v_mfma_f32_16x16x32_bf16 v[20:23], v[160:163], v[176:179], v[20:23]
	s_mov_b64 s[100:101], 0x588080
	v_lshl_add_u64 v[206:207], v[204:205], 0, s[100:101]
	s_add_i32 m0, s99, 0x4400
	v_mfma_f32_16x16x32_bf16 v[16:19], v[160:163], v[180:183], v[16:19]
	global_load_lds_dwordx4 v[206:207], off
	s_waitcnt lgkmcnt(4)
	v_mfma_f32_16x16x32_bf16 v[12:15], v[164:167], v[168:171], v[12:15]
	v_mfma_f32_16x16x32_bf16 v[8:11], v[164:167], v[172:175], v[8:11]
	v_mfma_f32_16x16x32_bf16 v[4:7], v[164:167], v[176:179], v[4:7]
	v_mfma_f32_16x16x32_bf16 v[0:3], v[164:167], v[180:183], v[0:3]
	s_waitcnt lgkmcnt(3)
	v_mfma_f32_16x16x32_bf16 v[124:127], v[188:191], v[168:171], v[124:127]
	v_mfma_f32_16x16x32_bf16 v[120:123], v[188:191], v[172:175], v[120:123]
	v_mfma_f32_16x16x32_bf16 v[116:119], v[188:191], v[176:179], v[116:119]
	v_mfma_f32_16x16x32_bf16 v[112:115], v[188:191], v[180:183], v[112:115]
	s_waitcnt lgkmcnt(2)
	v_mfma_f32_16x16x32_bf16 v[108:111], v[192:195], v[168:171], v[108:111]
	v_mfma_f32_16x16x32_bf16 v[104:107], v[192:195], v[172:175], v[104:107]
	v_mfma_f32_16x16x32_bf16 v[100:103], v[192:195], v[176:179], v[100:103]
	v_mfma_f32_16x16x32_bf16 v[96:99], v[192:195], v[180:183], v[96:99]
	s_waitcnt lgkmcnt(1)
	v_mfma_f32_16x16x32_bf16 v[92:95], v[196:199], v[168:171], v[92:95]
	v_mfma_f32_16x16x32_bf16 v[88:91], v[196:199], v[172:175], v[88:91]
	v_mfma_f32_16x16x32_bf16 v[80:83], v[196:199], v[176:179], v[80:83]
	v_mfma_f32_16x16x32_bf16 v[72:75], v[196:199], v[180:183], v[72:75]
	s_waitcnt lgkmcnt(0)
	v_mfma_f32_16x16x32_bf16 v[64:67], v[200:203], v[168:171], v[64:67]
	v_mfma_f32_16x16x32_bf16 v[56:59], v[200:203], v[172:175], v[56:59]
	v_mfma_f32_16x16x32_bf16 v[48:51], v[200:203], v[176:179], v[48:51]
	v_mfma_f32_16x16x32_bf16 v[40:43], v[200:203], v[180:183], v[40:43]
	s_add_i32 s8, s7, 1
	s_cmp_lg_u32 s7, 2
	s_cselect_b32 s7, s8, 0
	s_add_i32 s8, s6, 1
	s_cmp_lg_u32 s6, 2
	s_cselect_b32 s6, s8, 0
	s_add_u32 s0, s0, 64
	s_addc_u32 s1, s1, 0
	s_cmpk_eq_i32 s0, 0x780
	s_cbranch_scc0 .LBB0_1692
	s_waitcnt vmcnt(6)
	s_waitcnt lgkmcnt(0)
	s_barrier
	ds_read_b128 v[140:143], v144
	ds_read_b128 v[152:155], v144 offset:1024
	ds_read_b128 v[156:159], v144 offset:2048
	ds_read_b128 v[160:163], v144 offset:3072
	ds_read_b128 v[164:167], v146
	ds_read_b128 v[168:171], v146 offset:1024
	ds_read_b128 v[172:175], v146 offset:2048
	ds_read_b128 v[176:179], v146 offset:3072
	s_waitcnt lgkmcnt(0)
	s_nop 0
	v_mfma_f32_16x16x32_bf16 v[84:87], v[140:143], v[164:167], v[84:87]
	v_mfma_f32_16x16x32_bf16 v[76:79], v[140:143], v[168:171], v[76:79]
	v_mfma_f32_16x16x32_bf16 v[68:71], v[140:143], v[172:175], v[68:71]
	v_mfma_f32_16x16x32_bf16 v[60:63], v[140:143], v[176:179], v[60:63]
	v_mfma_f32_16x16x32_bf16 v[52:55], v[152:155], v[164:167], v[52:55]
	v_mfma_f32_16x16x32_bf16 v[44:47], v[152:155], v[168:171], v[44:47]
	v_mfma_f32_16x16x32_bf16 v[36:39], v[152:155], v[172:175], v[36:39]
	v_mfma_f32_16x16x32_bf16 v[32:35], v[152:155], v[176:179], v[32:35]
	v_mfma_f32_16x16x32_bf16 v[28:31], v[156:159], v[164:167], v[28:31]
	v_mfma_f32_16x16x32_bf16 v[24:27], v[156:159], v[168:171], v[24:27]
	v_mfma_f32_16x16x32_bf16 v[20:23], v[156:159], v[172:175], v[20:23]
	v_mfma_f32_16x16x32_bf16 v[16:19], v[156:159], v[176:179], v[16:19]
	v_mfma_f32_16x16x32_bf16 v[12:15], v[160:163], v[164:167], v[12:15]
	v_mfma_f32_16x16x32_bf16 v[8:11], v[160:163], v[168:171], v[8:11]
	v_mfma_f32_16x16x32_bf16 v[4:7], v[160:163], v[172:175], v[4:7]
	v_mfma_f32_16x16x32_bf16 v[0:3], v[160:163], v[176:179], v[0:3]
	ds_read_b128 v[140:143], v144 offset:4096
	ds_read_b128 v[152:155], v144 offset:5120
	ds_read_b128 v[156:159], v144 offset:6144
	ds_read_b128 v[160:163], v144 offset:7168
	s_waitcnt lgkmcnt(0)
	s_nop 0
	v_mfma_f32_16x16x32_bf16 v[180:183], v[140:143], v[164:167], v[124:127]
	v_mfma_f32_16x16x32_bf16 v[184:187], v[140:143], v[168:171], v[120:123]
	v_mfma_f32_16x16x32_bf16 v[188:191], v[140:143], v[172:175], v[116:119]
	v_mfma_f32_16x16x32_bf16 v[140:143], v[140:143], v[176:179], v[112:115]
	v_mfma_f32_16x16x32_bf16 v[192:195], v[152:155], v[164:167], v[108:111]
	v_mfma_f32_16x16x32_bf16 v[196:199], v[152:155], v[168:171], v[104:107]
	v_mfma_f32_16x16x32_bf16 v[200:203], v[152:155], v[172:175], v[100:103]
	v_mfma_f32_16x16x32_bf16 v[152:155], v[152:155], v[176:179], v[96:99]
	v_mfma_f32_16x16x32_bf16 v[204:207], v[156:159], v[164:167], v[92:95]
	v_mfma_f32_16x16x32_bf16 v[208:211], v[156:159], v[168:171], v[88:91]
	v_mfma_f32_16x16x32_bf16 v[212:215], v[156:159], v[172:175], v[80:83]
	v_mfma_f32_16x16x32_bf16 v[156:159], v[156:159], v[176:179], v[72:75]
	v_mfma_f32_16x16x32_bf16 v[164:167], v[160:163], v[164:167], v[64:67]
	v_mfma_f32_16x16x32_bf16 v[168:171], v[160:163], v[168:171], v[56:59]
	v_mfma_f32_16x16x32_bf16 v[172:175], v[160:163], v[172:175], v[48:51]
	v_mfma_f32_16x16x32_bf16 v[160:163], v[160:163], v[176:179], v[40:43]
	s_waitcnt vmcnt(0)
	s_waitcnt lgkmcnt(0)
	s_barrier
	ds_read_b128 v[40:43], v150
	ds_read_b128 v[48:51], v150 offset:1024
	ds_read_b128 v[56:59], v150 offset:2048
	ds_read_b128 v[176:179], v150 offset:3072
	ds_read_b128 v[216:219], v151
	ds_read_b128 v[220:223], v151 offset:1024
	ds_read_b128 v[228:231], v151 offset:2048
	ds_read_b128 v[232:235], v151 offset:3072
	s_waitcnt lgkmcnt(0)
	s_nop 0
	v_mfma_f32_16x16x32_bf16 v[116:119], v[40:43], v[220:223], v[76:79]
	v_mfma_f32_16x16x32_bf16 v[120:123], v[40:43], v[228:231], v[68:71]
	v_mfma_f32_16x16x32_bf16 v[64:67], v[176:179], v[216:219], v[12:15]
	v_mfma_f32_16x16x32_bf16 v[68:71], v[176:179], v[220:223], v[8:11]
	v_mfma_f32_16x16x32_bf16 v[72:75], v[176:179], v[228:231], v[4:7]
	v_mfma_f32_16x16x32_bf16 v[76:79], v[176:179], v[232:235], v[0:3]
	ds_read_b128 v[0:3], v150 offset:4096
	ds_read_b128 v[4:7], v150 offset:5120
	ds_read_b128 v[8:11], v150 offset:6144
	ds_read_b128 v[12:15], v150 offset:7168
	s_waitcnt lgkmcnt(0)
	v_mfma_f32_16x16x32_bf16 v[112:115], v[40:43], v[216:219], v[84:87]
	v_mfma_f32_16x16x32_bf16 v[124:127], v[40:43], v[232:235], v[60:63]
	v_mfma_f32_16x16x32_bf16 v[96:99], v[48:51], v[216:219], v[52:55]
	v_mfma_f32_16x16x32_bf16 v[100:103], v[48:51], v[220:223], v[44:47]
	v_mfma_f32_16x16x32_bf16 v[104:107], v[48:51], v[228:231], v[36:39]
	v_mfma_f32_16x16x32_bf16 v[108:111], v[48:51], v[232:235], v[32:35]
	v_mfma_f32_16x16x32_bf16 v[80:83], v[56:59], v[216:219], v[28:31]
	v_mfma_f32_16x16x32_bf16 v[84:87], v[56:59], v[220:223], v[24:27]
	v_mfma_f32_16x16x32_bf16 v[88:91], v[56:59], v[228:231], v[20:23]
	v_mfma_f32_16x16x32_bf16 v[92:95], v[56:59], v[232:235], v[16:19]
	v_mfma_f32_16x16x32_bf16 v[48:51], v[0:3], v[216:219], v[180:183]
	v_mfma_f32_16x16x32_bf16 v[52:55], v[0:3], v[220:223], v[184:187]
	v_mfma_f32_16x16x32_bf16 v[56:59], v[0:3], v[228:231], v[188:191]
	v_mfma_f32_16x16x32_bf16 v[60:63], v[0:3], v[232:235], v[140:143]
	v_mfma_f32_16x16x32_bf16 v[32:35], v[4:7], v[216:219], v[192:195]
	v_mfma_f32_16x16x32_bf16 v[36:39], v[4:7], v[220:223], v[196:199]
	v_mfma_f32_16x16x32_bf16 v[40:43], v[4:7], v[228:231], v[200:203]
	v_mfma_f32_16x16x32_bf16 v[44:47], v[4:7], v[232:235], v[152:155]
	v_mfma_f32_16x16x32_bf16 v[16:19], v[8:11], v[216:219], v[204:207]
	v_mfma_f32_16x16x32_bf16 v[20:23], v[8:11], v[220:223], v[208:211]
	v_mfma_f32_16x16x32_bf16 v[24:27], v[8:11], v[228:231], v[212:215]
	v_mfma_f32_16x16x32_bf16 v[28:31], v[8:11], v[232:235], v[156:159]
	v_mfma_f32_16x16x32_bf16 v[0:3], v[12:15], v[216:219], v[164:167]
	v_mfma_f32_16x16x32_bf16 v[4:7], v[12:15], v[220:223], v[168:171]
	v_mfma_f32_16x16x32_bf16 v[8:11], v[12:15], v[228:231], v[172:175]
	v_mfma_f32_16x16x32_bf16 v[12:15], v[12:15], v[232:235], v[160:163]
	s_setprio 0
	v_add_u32_e32 v152, s4, v129
	v_or_b32_e32 v153, v152, v149
	v_or_b32_e32 v140, s5, v145
	v_mov_b32_e32 v155, v153
	v_mov_b64_e32 v[142:143], s[94:95]
	s_waitcnt lgkmcnt(0)
	s_barrier
	v_ashrrev_i32_e32 v141, 31, v140
	v_or_b32_e32 v154, v140, v128
	v_mad_i64_i32 v[142:143], s[0:1], v155, s39, v[142:143]
	v_lshl_add_u64 v[142:143], v[140:141], 1, v[142:143]
	v_lshl_add_u64 v[142:143], v[142:143], 0, v[130:131]
	v_cmp_gt_i32_e32 vcc, s40, v154
	s_and_saveexec_b64 s[0:1], vcc
	s_cbranch_execz .LBB0_1695
	v_cvt_pk_bf16_f32 v155, v112, v112
	global_store_short_d16_hi v[142:143], v155, off

.LBB0_2119:
	s_mul_hi_i32 s30, s2, 0x66666667
	s_lshr_b32 s31, s30, 31
	s_ashr_i32 s30, s30, 4
	s_add_i32 s30, s30, s31
	s_lshl_b32 s34, s30, 2
	s_and_b32 s31, s2, 3
	s_add_i32 s34, s34, s33
	s_or_b32 s31, s34, s31
	s_lshl_b32 s54, s31, 7
	s_mulk_i32 s30, 0xfb00
	v_add_u32_e32 v0, s54, v80
	s_add_i32 s53, s37, s30
	v_ashrrev_i32_e32 v1, 31, v0
	s_and_b32 s30, s53, 0xffffff80
	v_add_u32_e32 v2, s30, v80
	v_lshlrev_b64 v[0:1], 9, v[0:1]
	s_mov_b32 m0, s36
	v_ashrrev_i32_e32 v3, 31, v2
	v_lshl_add_u64 v[78:79], v[74:75], 0, v[0:1]
	v_lshlrev_b64 v[2:3], 9, v[2:3]
	s_setprio 2
	global_load_lds_dwordx4 v[78:79], off
	v_lshl_add_u64 v[0:1], v[78:79], 0, s[0:1]
	s_mov_b32 m0, s39
	v_lshl_add_u64 v[68:69], v[72:73], 0, v[2:3]
	global_load_lds_dwordx4 v[0:1], off
	s_mov_b32 m0, s40
	v_lshl_add_u64 v[0:1], v[68:69], 0, s[0:1]
	global_load_lds_dwordx4 v[68:69], off
	s_mov_b32 m0, s41
	v_lshl_add_u64 v[4:5], v[78:79], 0, s[8:9]
	global_load_lds_dwordx4 v[0:1], off
	v_lshl_add_u64 v[0:1], v[78:79], 0, 64
	s_mov_b32 m0, s42
	v_lshl_add_u64 v[6:7], v[78:79], 0, s[6:7]
	global_load_lds_dwordx4 v[0:1], off
	v_lshl_add_u64 v[0:1], v[78:79], 0, s[4:5]
	s_mov_b32 m0, s43
	v_lshl_add_u64 v[2:3], v[68:69], 0, s[8:9]
	global_load_lds_dwordx4 v[0:1], off
	v_lshl_add_u64 v[0:1], v[68:69], 0, 64
	s_mov_b32 m0, s44
	v_lshl_add_u64 v[90:91], v[78:79], 0, s[12:13]
	global_load_lds_dwordx4 v[0:1], off
	v_lshl_add_u64 v[0:1], v[68:69], 0, s[4:5]
	s_mov_b32 m0, s45
	v_lshl_add_u64 v[92:93], v[78:79], 0, s[10:11]
	global_load_lds_dwordx4 v[0:1], off
	s_waitcnt vmcnt(4)
	s_waitcnt lgkmcnt(0)
	s_barrier
	s_mov_b32 m0, s46
	v_lshl_add_u64 v[0:1], v[68:69], 0, s[6:7]
	global_load_lds_dwordx4 v[4:5], off
	s_mov_b32 m0, s47
	s_nop 0
	global_load_lds_dwordx4 v[6:7], off
	s_mov_b32 m0, s48
	s_nop 0
	global_load_lds_dwordx4 v[2:3], off
	s_mov_b32 m0, s49
	s_nop 0
	global_load_lds_dwordx4 v[0:1], off
	ds_read_b128 v[0:3], v82
	ds_read_b128 v[4:7], v82 offset:1024
	ds_read_b128 v[8:11], v82 offset:2048
	ds_read_b128 v[12:15], v82 offset:3072
	ds_read_b128 v[16:19], v83
	ds_read_b128 v[20:23], v83 offset:1024
	ds_read_b128 v[24:27], v83 offset:2048
	ds_read_b128 v[28:31], v83 offset:3072
	s_waitcnt lgkmcnt(0)
	s_waitcnt vmcnt(4)
	s_waitcnt lgkmcnt(0)
	s_barrier
	s_mov_b32 m0, s36
	v_mfma_f32_16x16x32_bf16 v[32:35], v[16:19], v[0:3], 0
	global_load_lds_dwordx4 v[90:91], off
	s_mov_b32 m0, s39
	v_mfma_f32_16x16x32_bf16 v[36:39], v[20:23], v[0:3], 0
	global_load_lds_dwordx4 v[92:93], off
	s_mov_b32 m0, s40
	v_mfma_f32_16x16x32_bf16 v[40:43], v[24:27], v[0:3], 0
	v_mfma_f32_16x16x32_bf16 v[0:3], v[28:31], v[0:3], 0
	v_mfma_f32_16x16x32_bf16 v[44:47], v[16:19], v[4:7], 0
	v_mfma_f32_16x16x32_bf16 v[48:51], v[20:23], v[4:7], 0
	v_mfma_f32_16x16x32_bf16 v[52:55], v[24:27], v[4:7], 0
	v_mfma_f32_16x16x32_bf16 v[4:7], v[28:31], v[4:7], 0
	v_mfma_f32_16x16x32_bf16 v[56:59], v[16:19], v[8:11], 0
	v_mfma_f32_16x16x32_bf16 v[60:63], v[20:23], v[8:11], 0
	v_mfma_f32_16x16x32_bf16 v[64:67], v[24:27], v[8:11], 0
	v_mfma_f32_16x16x32_bf16 v[8:11], v[28:31], v[8:11], 0
	v_mfma_f32_16x16x32_bf16 v[16:19], v[16:19], v[12:15], 0
	v_mfma_f32_16x16x32_bf16 v[20:23], v[20:23], v[12:15], 0
	v_mfma_f32_16x16x32_bf16 v[24:27], v[24:27], v[12:15], 0
	v_mfma_f32_16x16x32_bf16 v[12:15], v[28:31], v[12:15], 0
	v_lshl_add_u64 v[30:31], v[68:69], 0, s[12:13]
	v_lshl_add_u64 v[28:29], v[68:69], 0, s[10:11]
	global_load_lds_dwordx4 v[30:31], off
	s_mov_b32 m0, s41
	s_nop 0
	global_load_lds_dwordx4 v[28:29], off
	ds_read_b128 v[28:31], v85
	ds_read_b128 v[90:93], v85 offset:1024
	ds_read_b128 v[94:97], v85 offset:2048
	ds_read_b128 v[98:101], v85 offset:3072
	ds_read_b128 v[102:105], v86
	ds_read_b128 v[106:109], v86 offset:1024
	ds_read_b128 v[110:113], v86 offset:2048
	ds_read_b128 v[114:117], v86 offset:3072
	s_waitcnt lgkmcnt(0)
	s_waitcnt vmcnt(4)
	s_waitcnt lgkmcnt(0)
	s_barrier
	v_mfma_f32_16x16x32_bf16 v[32:35], v[102:105], v[28:31], v[32:35]
	s_mov_b32 m0, s42
	v_mfma_f32_16x16x32_bf16 v[36:39], v[106:109], v[28:31], v[36:39]
	v_mfma_f32_16x16x32_bf16 v[40:43], v[110:113], v[28:31], v[40:43]
	v_mfma_f32_16x16x32_bf16 v[0:3], v[114:117], v[28:31], v[0:3]
	v_mfma_f32_16x16x32_bf16 v[28:31], v[102:105], v[90:93], v[44:47]
	v_mfma_f32_16x16x32_bf16 v[44:47], v[106:109], v[90:93], v[48:51]
	v_mfma_f32_16x16x32_bf16 v[48:51], v[110:113], v[90:93], v[52:55]
	v_mfma_f32_16x16x32_bf16 v[4:7], v[114:117], v[90:93], v[4:7]
	v_lshl_add_u64 v[90:91], v[78:79], 0, s[16:17]
	v_lshl_add_u64 v[92:93], v[78:79], 0, s[14:15]
	global_load_lds_dwordx4 v[90:91], off
	s_mov_b32 m0, s43
	v_mfma_f32_16x16x32_bf16 v[52:55], v[102:105], v[94:97], v[56:59]
	global_load_lds_dwordx4 v[92:93], off
	s_mov_b32 m0, s44
	v_mfma_f32_16x16x32_bf16 v[56:59], v[106:109], v[94:97], v[60:63]
	v_mfma_f32_16x16x32_bf16 v[60:63], v[110:113], v[94:97], v[64:67]
	s_nop 2
	v_lshl_add_u64 v[66:67], v[68:69], 0, s[16:17]
	v_lshl_add_u64 v[64:65], v[68:69], 0, s[14:15]
	global_load_lds_dwordx4 v[66:67], off
	s_mov_b32 m0, s45
	v_mfma_f32_16x16x32_bf16 v[8:11], v[114:117], v[94:97], v[8:11]
	global_load_lds_dwordx4 v[64:65], off
	s_mov_b32 m0, s46
	v_mfma_f32_16x16x32_bf16 v[16:19], v[102:105], v[98:101], v[16:19]
	v_mfma_f32_16x16x32_bf16 v[20:23], v[106:109], v[98:101], v[20:23]
	v_mfma_f32_16x16x32_bf16 v[24:27], v[110:113], v[98:101], v[24:27]
	v_mfma_f32_16x16x32_bf16 v[12:15], v[114:117], v[98:101], v[12:15]
	ds_read_b128 v[64:67], v87
	ds_read_b128 v[90:93], v87 offset:1024
	ds_read_b128 v[94:97], v87 offset:2048
	ds_read_b128 v[98:101], v87 offset:3072
	ds_read_b128 v[102:105], v88
	ds_read_b128 v[106:109], v88 offset:1024
	ds_read_b128 v[110:113], v88 offset:2048
	ds_read_b128 v[114:117], v88 offset:3072
	s_waitcnt lgkmcnt(0)
	s_waitcnt vmcnt(4)
	s_waitcnt lgkmcnt(0)
	s_barrier
	v_mfma_f32_16x16x32_bf16 v[28:31], v[102:105], v[90:93], v[28:31]
	v_mfma_f32_16x16x32_bf16 v[44:47], v[106:109], v[90:93], v[44:47]
	v_mfma_f32_16x16x32_bf16 v[48:51], v[110:113], v[90:93], v[48:51]
	v_mfma_f32_16x16x32_bf16 v[4:7], v[114:117], v[90:93], v[4:7]
	v_lshl_add_u64 v[90:91], v[78:79], 0, s[20:21]
	v_lshl_add_u64 v[92:93], v[78:79], 0, s[18:19]
	global_load_lds_dwordx4 v[90:91], off
	s_mov_b32 m0, s47
	v_mfma_f32_16x16x32_bf16 v[32:35], v[102:105], v[64:67], v[32:35]
	global_load_lds_dwordx4 v[92:93], off
	s_mov_b32 m0, s48
	v_mfma_f32_16x16x32_bf16 v[36:39], v[106:109], v[64:67], v[36:39]
	v_mfma_f32_16x16x32_bf16 v[40:43], v[110:113], v[64:67], v[40:43]
	v_mfma_f32_16x16x32_bf16 v[0:3], v[114:117], v[64:67], v[0:3]
	v_lshl_add_u64 v[66:67], v[68:69], 0, s[20:21]
	v_lshl_add_u64 v[64:65], v[68:69], 0, s[18:19]
	global_load_lds_dwordx4 v[66:67], off
	s_mov_b32 m0, s49
	v_mfma_f32_16x16x32_bf16 v[52:55], v[102:105], v[94:97], v[52:55]
	global_load_lds_dwordx4 v[64:65], off
	s_mov_b32 m0, s36
	v_mfma_f32_16x16x32_bf16 v[56:59], v[106:109], v[94:97], v[56:59]
	v_mfma_f32_16x16x32_bf16 v[60:63], v[110:113], v[94:97], v[60:63]
	v_mfma_f32_16x16x32_bf16 v[8:11], v[114:117], v[94:97], v[8:11]
	v_mfma_f32_16x16x32_bf16 v[16:19], v[102:105], v[98:101], v[16:19]
	v_mfma_f32_16x16x32_bf16 v[20:23], v[106:109], v[98:101], v[20:23]
	v_mfma_f32_16x16x32_bf16 v[24:27], v[110:113], v[98:101], v[24:27]
	v_mfma_f32_16x16x32_bf16 v[12:15], v[114:117], v[98:101], v[12:15]
	ds_read_b128 v[64:67], v82
	ds_read_b128 v[90:93], v82 offset:1024
	ds_read_b128 v[94:97], v82 offset:2048
	ds_read_b128 v[98:101], v82 offset:3072
	ds_read_b128 v[102:105], v83
	ds_read_b128 v[106:109], v83 offset:1024
	ds_read_b128 v[110:113], v83 offset:2048
	ds_read_b128 v[114:117], v83 offset:3072
	s_waitcnt lgkmcnt(0)
	s_waitcnt vmcnt(4)
	s_waitcnt lgkmcnt(0)
	s_barrier
	v_mfma_f32_16x16x32_bf16 v[28:31], v[102:105], v[90:93], v[28:31]
	v_mfma_f32_16x16x32_bf16 v[44:47], v[106:109], v[90:93], v[44:47]
	v_mfma_f32_16x16x32_bf16 v[48:51], v[110:113], v[90:93], v[48:51]
	v_mfma_f32_16x16x32_bf16 v[4:7], v[114:117], v[90:93], v[4:7]
	v_lshl_add_u64 v[90:91], v[78:79], 0, s[24:25]
	v_lshl_add_u64 v[92:93], v[78:79], 0, s[22:23]
	global_load_lds_dwordx4 v[90:91], off
	s_mov_b32 m0, s39
	v_mfma_f32_16x16x32_bf16 v[32:35], v[102:105], v[64:67], v[32:35]
	global_load_lds_dwordx4 v[92:93], off
	s_mov_b32 m0, s40
	v_mfma_f32_16x16x32_bf16 v[36:39], v[106:109], v[64:67], v[36:39]
	v_mfma_f32_16x16x32_bf16 v[40:43], v[110:113], v[64:67], v[40:43]
	v_mfma_f32_16x16x32_bf16 v[0:3], v[114:117], v[64:67], v[0:3]
	v_lshl_add_u64 v[66:67], v[68:69], 0, s[24:25]
	v_lshl_add_u64 v[64:65], v[68:69], 0, s[22:23]
	global_load_lds_dwordx4 v[66:67], off
	s_mov_b32 m0, s41
	v_mfma_f32_16x16x32_bf16 v[52:55], v[102:105], v[94:97], v[52:55]
	global_load_lds_dwordx4 v[64:65], off
	s_mov_b32 m0, s42
	v_mfma_f32_16x16x32_bf16 v[56:59], v[106:109], v[94:97], v[56:59]
	v_mfma_f32_16x16x32_bf16 v[60:63], v[110:113], v[94:97], v[60:63]
	v_mfma_f32_16x16x32_bf16 v[8:11], v[114:117], v[94:97], v[8:11]
	v_mfma_f32_16x16x32_bf16 v[16:19], v[102:105], v[98:101], v[16:19]
	v_mfma_f32_16x16x32_bf16 v[20:23], v[106:109], v[98:101], v[20:23]
	v_mfma_f32_16x16x32_bf16 v[24:27], v[110:113], v[98:101], v[24:27]
	v_mfma_f32_16x16x32_bf16 v[12:15], v[114:117], v[98:101], v[12:15]
	ds_read_b128 v[64:67], v85
	ds_read_b128 v[90:93], v85 offset:1024
	ds_read_b128 v[94:97], v85 offset:2048
	ds_read_b128 v[98:101], v85 offset:3072
	ds_read_b128 v[102:105], v86
	ds_read_b128 v[106:109], v86 offset:1024
	ds_read_b128 v[110:113], v86 offset:2048
	ds_read_b128 v[114:117], v86 offset:3072
	s_waitcnt lgkmcnt(0)
	s_waitcnt vmcnt(4)
	s_waitcnt lgkmcnt(0)
	s_barrier
	v_mfma_f32_16x16x32_bf16 v[32:35], v[102:105], v[64:67], v[32:35]
	v_mfma_f32_16x16x32_bf16 v[36:39], v[106:109], v[64:67], v[36:39]
	v_mfma_f32_16x16x32_bf16 v[40:43], v[110:113], v[64:67], v[40:43]
	v_mfma_f32_16x16x32_bf16 v[0:3], v[114:117], v[64:67], v[0:3]
	v_lshl_add_u64 v[64:65], v[68:69], 0, s[26:27]
	v_lshl_add_u64 v[66:67], v[68:69], 0, s[28:29]
	v_lshl_add_u64 v[68:69], v[78:79], 0, s[28:29]
	v_lshl_add_u64 v[78:79], v[78:79], 0, s[26:27]
	global_load_lds_dwordx4 v[68:69], off
	s_mov_b32 m0, s43
	v_mfma_f32_16x16x32_bf16 v[28:31], v[102:105], v[90:93], v[28:31]
	global_load_lds_dwordx4 v[78:79], off
	s_mov_b32 m0, s44
	v_mfma_f32_16x16x32_bf16 v[44:47], v[106:109], v[90:93], v[44:47]
	global_load_lds_dwordx4 v[66:67], off
	s_mov_b32 m0, s45
	v_mfma_f32_16x16x32_bf16 v[48:51], v[110:113], v[90:93], v[48:51]
	global_load_lds_dwordx4 v[64:65], off
	v_or_b32_e32 v78, s30, v84
	v_mfma_f32_16x16x32_bf16 v[4:7], v[114:117], v[90:93], v[4:7]
	v_cmp_lt_i32_e32 vcc, s50, v78
	v_mfma_f32_16x16x32_bf16 v[52:55], v[102:105], v[94:97], v[52:55]
	v_mfma_f32_16x16x32_bf16 v[56:59], v[106:109], v[94:97], v[56:59]
	v_mfma_f32_16x16x32_bf16 v[60:63], v[110:113], v[94:97], v[60:63]
	v_mfma_f32_16x16x32_bf16 v[8:11], v[114:117], v[94:97], v[8:11]
	v_mfma_f32_16x16x32_bf16 v[16:19], v[102:105], v[98:101], v[16:19]
	v_mfma_f32_16x16x32_bf16 v[20:23], v[106:109], v[98:101], v[20:23]
	v_mfma_f32_16x16x32_bf16 v[24:27], v[110:113], v[98:101], v[24:27]
	v_mfma_f32_16x16x32_bf16 v[12:15], v[114:117], v[98:101], v[12:15]
	ds_read_b128 v[64:67], v87
	ds_read_b128 v[90:93], v87 offset:1024
	ds_read_b128 v[94:97], v87 offset:2048
	ds_read_b128 v[98:101], v87 offset:3072
	ds_read_b128 v[102:105], v88
	ds_read_b128 v[106:109], v88 offset:1024
	ds_read_b128 v[110:113], v88 offset:2048
	ds_read_b128 v[114:117], v88 offset:3072
	s_waitcnt lgkmcnt(0)
	s_waitcnt vmcnt(4)
	s_waitcnt lgkmcnt(0)
	s_barrier
	v_mfma_f32_16x16x32_bf16 v[32:35], v[102:105], v[64:67], v[32:35]
	v_mfma_f32_16x16x32_bf16 v[36:39], v[106:109], v[64:67], v[36:39]
	v_mfma_f32_16x16x32_bf16 v[40:43], v[110:113], v[64:67], v[40:43]
	v_mfma_f32_16x16x32_bf16 v[0:3], v[114:117], v[64:67], v[0:3]
	v_mfma_f32_16x16x32_bf16 v[28:31], v[102:105], v[90:93], v[28:31]
	v_mfma_f32_16x16x32_bf16 v[44:47], v[106:109], v[90:93], v[44:47]
	v_mfma_f32_16x16x32_bf16 v[48:51], v[110:113], v[90:93], v[48:51]
	v_mfma_f32_16x16x32_bf16 v[4:7], v[114:117], v[90:93], v[4:7]
	v_mfma_f32_16x16x32_bf16 v[52:55], v[102:105], v[94:97], v[52:55]
	v_mfma_f32_16x16x32_bf16 v[56:59], v[106:109], v[94:97], v[56:59]
	v_mfma_f32_16x16x32_bf16 v[60:63], v[110:113], v[94:97], v[60:63]
	v_mfma_f32_16x16x32_bf16 v[8:11], v[114:117], v[94:97], v[8:11]
	v_mfma_f32_16x16x32_bf16 v[16:19], v[102:105], v[98:101], v[16:19]
	v_mfma_f32_16x16x32_bf16 v[20:23], v[106:109], v[98:101], v[20:23]
	v_mfma_f32_16x16x32_bf16 v[24:27], v[110:113], v[98:101], v[24:27]
	v_mfma_f32_16x16x32_bf16 v[12:15], v[114:117], v[98:101], v[12:15]
	ds_read_b128 v[64:67], v82
	ds_read_b128 v[90:93], v82 offset:1024
	ds_read_b128 v[94:97], v82 offset:2048
	ds_read_b128 v[98:101], v82 offset:3072
	ds_read_b128 v[102:105], v83
	ds_read_b128 v[106:109], v83 offset:1024
	ds_read_b128 v[110:113], v83 offset:2048
	ds_read_b128 v[114:117], v83 offset:3072
	s_waitcnt lgkmcnt(0)
	s_waitcnt vmcnt(0)
	s_waitcnt lgkmcnt(0)
	s_barrier
	v_mfma_f32_16x16x32_bf16 v[32:35], v[102:105], v[64:67], v[32:35]
	v_mfma_f32_16x16x32_bf16 v[36:39], v[106:109], v[64:67], v[36:39]
	v_mfma_f32_16x16x32_bf16 v[40:43], v[110:113], v[64:67], v[40:43]
	v_mfma_f32_16x16x32_bf16 v[0:3], v[114:117], v[64:67], v[0:3]
	v_mfma_f32_16x16x32_bf16 v[118:121], v[102:105], v[90:93], v[28:31]
	v_mfma_f32_16x16x32_bf16 v[122:125], v[106:109], v[90:93], v[44:47]
	v_mfma_f32_16x16x32_bf16 v[48:51], v[110:113], v[90:93], v[48:51]
	v_mfma_f32_16x16x32_bf16 v[4:7], v[114:117], v[90:93], v[4:7]
	v_mfma_f32_16x16x32_bf16 v[52:55], v[102:105], v[94:97], v[52:55]
	v_mfma_f32_16x16x32_bf16 v[90:93], v[106:109], v[94:97], v[56:59]
	v_mfma_f32_16x16x32_bf16 v[126:129], v[110:113], v[94:97], v[60:63]
	v_mfma_f32_16x16x32_bf16 v[94:97], v[114:117], v[94:97], v[8:11]
	v_mfma_f32_16x16x32_bf16 v[16:19], v[102:105], v[98:101], v[16:19]
	v_mfma_f32_16x16x32_bf16 v[102:105], v[106:109], v[98:101], v[20:23]
	v_mfma_f32_16x16x32_bf16 v[106:109], v[110:113], v[98:101], v[24:27]
	v_mfma_f32_16x16x32_bf16 v[98:101], v[114:117], v[98:101], v[12:15]
	ds_read_b128 v[8:11], v85
	ds_read_b128 v[20:23], v85 offset:1024
	ds_read_b128 v[110:113], v85 offset:2048
	ds_read_b128 v[114:117], v85 offset:3072
	ds_read_b128 v[130:133], v86
	ds_read_b128 v[134:137], v86 offset:1024
	ds_read_b128 v[138:141], v86 offset:2048
	ds_read_b128 v[142:145], v86 offset:3072
	s_waitcnt lgkmcnt(0)
	s_waitcnt lgkmcnt(0)
	s_barrier
	v_mfma_f32_16x16x32_bf16 v[66:69], v[130:133], v[8:11], v[32:35]
	v_mfma_f32_16x16x32_bf16 v[44:47], v[134:137], v[8:11], v[36:39]
	v_mfma_f32_16x16x32_bf16 v[28:31], v[138:141], v[8:11], v[40:43]
	v_mfma_f32_16x16x32_bf16 v[12:15], v[142:145], v[8:11], v[0:3]
	v_mfma_f32_16x16x32_bf16 v[62:65], v[130:133], v[20:23], v[118:121]
	v_mfma_f32_16x16x32_bf16 v[40:43], v[134:137], v[20:23], v[122:125]
	v_mfma_f32_16x16x32_bf16 v[24:27], v[138:141], v[20:23], v[48:51]
	v_mfma_f32_16x16x32_bf16 v[8:11], v[142:145], v[20:23], v[4:7]
	v_mfma_f32_16x16x32_bf16 v[58:61], v[130:133], v[110:113], v[52:55]
	v_mfma_f32_16x16x32_bf16 v[36:39], v[134:137], v[110:113], v[90:93]
	v_mfma_f32_16x16x32_bf16 v[20:23], v[138:141], v[110:113], v[126:129]
	v_mfma_f32_16x16x32_bf16 v[4:7], v[142:145], v[110:113], v[94:97]
	v_mfma_f32_16x16x32_bf16 v[48:51], v[130:133], v[114:117], v[16:19]
	v_mfma_f32_16x16x32_bf16 v[32:35], v[134:137], v[114:117], v[102:105]
	v_mfma_f32_16x16x32_bf16 v[16:19], v[138:141], v[114:117], v[106:109]
	v_mfma_f32_16x16x32_bf16 v[0:3], v[142:145], v[114:117], v[98:101]
	s_setprio 0
	s_and_saveexec_b64 s[34:35], vcc
	s_xor_b64 s[34:35], exec, s[34:35]
	s_cbranch_execz .LBB0_2122
	s_cmpk_gt_u32 s53, 0x3ff
	s_cbranch_scc1 .LBB0_2135
	v_readlane_b32 s56, v241, 57
	v_mov_b32_e32 v79, v71
	v_readlane_b32 s68, v240, 5
	v_readlane_b32 s69, v240, 6
	v_readlane_b32 s57, v241, 58
	v_readlane_b32 s58, v241, 59
	v_lshl_add_u64 v[52:53], v[78:79], 2, s[68:69]
	global_load_dwordx4 v[54:57], v[52:53], off
	v_readlane_b32 s59, v241, 60
	v_readlane_b32 s60, v241, 61
	v_readlane_b32 s61, v241, 62
	v_readlane_b32 s62, v241, 63
	v_readlane_b32 s63, v240, 0
	v_readlane_b32 s64, v240, 1
	v_readlane_b32 s65, v240, 2
	v_readlane_b32 s66, v240, 3
	v_readlane_b32 s67, v240, 4
	v_readlane_b32 s70, v240, 7
	v_readlane_b32 s71, v240, 8
	s_mov_b64 s[30:31], -1
	s_waitcnt vmcnt(0)
	v_mov_b32_e32 v53, v56
	v_mov_b32_e32 v52, v54
	v_mov_b32_e32 v56, v55

.LBB0_2891:
	s_ashr_i32 s10, s2, 31
	s_lshr_b32 s10, s10, 27
	s_add_i32 s10, s2, s10
	s_ashr_i32 s10, s10, 5
	s_lshl_b32 s24, s10, 2
	s_and_b32 s25, s2, 3
	s_add_i32 s24, s24, s23
	s_or_b32 s24, s24, s25
	s_lshl_b32 s44, s24, 7
	s_lshl_b32 s10, s10, 10
	s_lshl_b32 s24, s2, 5
	s_sub_i32 s24, s24, s10
	s_and_b32 s45, s24, 0xffffff80
	v_add_u32_e32 v64, s44, v83
	v_add_u32_e32 v0, s45, v83
	s_mov_b32 m0, s28
	v_ashrrev_i32_e32 v1, 31, v0
	v_mad_i64_i32 v[2:3], s[24:25], v64, s34, v[72:73]
	v_lshlrev_b64 v[0:1], 11, v[0:1]
	s_setprio 2
	global_load_lds_dwordx4 v[2:3], off
	v_lshl_add_u64 v[4:5], v[2:3], 0, s[0:1]
	s_mov_b32 m0, s35
	v_lshl_add_u64 v[0:1], v[70:71], 0, v[0:1]
	global_load_lds_dwordx4 v[4:5], off
	s_mov_b32 m0, s36
	v_lshl_add_u64 v[4:5], v[0:1], 0, s[4:5]
	global_load_lds_dwordx4 v[0:1], off
	s_mov_b32 m0, s37
	s_sub_i32 s10, s31, s10
	global_load_lds_dwordx4 v[4:5], off
	v_lshl_add_u64 v[4:5], v[2:3], 0, 64
	s_mov_b32 m0, s38
	v_lshl_add_u64 v[2:3], v[2:3], 0, s[6:7]
	global_load_lds_dwordx4 v[4:5], off
	s_mov_b32 m0, s39
	s_and_b32 s10, s10, 0xffffff80
	global_load_lds_dwordx4 v[2:3], off
	v_lshl_add_u64 v[2:3], v[0:1], 0, 64
	s_mov_b32 m0, s40
	v_lshl_add_u64 v[0:1], v[0:1], 0, s[8:9]
	global_load_lds_dwordx4 v[2:3], off
	s_mov_b32 m0, s41
	v_readlane_b32 s52, v241, 17
	global_load_lds_dwordx4 v[0:1], off
	v_add_u32_e32 v0, s10, v83
	v_ashrrev_i32_e32 v1, 31, v0
	v_lshlrev_b64 v[0:1], 11, v[0:1]
	v_lshl_add_u64 v[66:67], v[70:71], 0, v[0:1]
	s_mov_b64 s[24:25], 0
	s_mov_b64 s[26:27], 0
	s_mov_b32 s46, s11
	s_mov_b32 s47, 2
	s_mov_b32 s48, s11
	v_mov_b32_e32 v24, 0
	v_mov_b32_e32 v25, v69
	v_mov_b32_e32 v26, v69
	v_mov_b32_e32 v27, v69
	v_mov_b32_e32 v0, 0
	v_mov_b32_e32 v1, v69
	v_mov_b32_e32 v2, v69
	v_mov_b32_e32 v3, v69
	v_mov_b32_e32 v4, 0
	v_mov_b32_e32 v5, v69
	v_mov_b32_e32 v6, v69
	v_mov_b32_e32 v7, v69
	v_mov_b32_e32 v8, 0
	v_mov_b32_e32 v9, v69
	v_mov_b32_e32 v10, v69
	v_mov_b32_e32 v11, v69
	v_mov_b32_e32 v12, 0
	v_mov_b32_e32 v13, v69
	v_mov_b32_e32 v14, v69
	v_mov_b32_e32 v15, v69
	v_mov_b32_e32 v16, 0
	v_mov_b32_e32 v17, v69
	v_mov_b32_e32 v18, v69
	v_mov_b32_e32 v19, v69
	v_mov_b32_e32 v20, 0
	v_mov_b32_e32 v21, v69
	v_mov_b32_e32 v22, v69
	v_mov_b32_e32 v23, v69
	v_mov_b32_e32 v28, 0
	v_mov_b32_e32 v29, v69
	v_mov_b32_e32 v30, v69
	v_mov_b32_e32 v31, v69
	v_mov_b32_e32 v32, 0
	v_mov_b32_e32 v33, v69
	v_mov_b32_e32 v34, v69
	v_mov_b32_e32 v35, v69
	v_mov_b32_e32 v36, 0
	v_mov_b32_e32 v37, v69
	v_mov_b32_e32 v38, v69
	v_mov_b32_e32 v39, v69
	v_mov_b32_e32 v40, 0
	v_mov_b32_e32 v41, v69
	v_mov_b32_e32 v42, v69
	v_mov_b32_e32 v43, v69
	v_mov_b32_e32 v44, 0
	v_mov_b32_e32 v45, v69
	v_mov_b32_e32 v46, v69
	v_mov_b32_e32 v47, v69
	v_mov_b32_e32 v48, 0
	v_mov_b32_e32 v49, v69
	v_mov_b32_e32 v50, v69
	v_mov_b32_e32 v51, v69
	v_mov_b32_e32 v52, 0
	v_mov_b32_e32 v53, v69
	v_mov_b32_e32 v54, v69
	v_mov_b32_e32 v55, v69
	v_mov_b32_e32 v56, 0
	v_mov_b32_e32 v57, v69
	v_mov_b32_e32 v58, v69
	v_mov_b32_e32 v59, v69
	v_mov_b32_e32 v60, 0
	v_mov_b32_e32 v61, v69
	v_mov_b32_e32 v62, v69
	v_mov_b32_e32 v63, v69
	v_readlane_b32 s56, v241, 21
	v_readlane_b32 s57, v241, 22
	v_readlane_b32 s58, v241, 23
	v_readlane_b32 s59, v241, 24
	v_readlane_b32 s53, v241, 18
	v_readlane_b32 s54, v241, 19
	v_readlane_b32 s55, v241, 20
.LBB0_2892:
	s_cmp_lt_u32 s46, 10
	s_cselect_b32 s52, s42, 0x500
	s_cselect_b32 s10, s57, s59
	s_cselect_b32 s49, s56, s58
	s_cselect_b32 s54, 0, 0xfffffe80
	v_mad_i64_i32 v[92:93], s[50:51], s52, v64, 0
	s_cselect_b32 s53, 0, -1
	v_mov_b32_e32 v90, s49
	v_mov_b32_e32 v91, s10
	s_add_u32 s50, s24, s54
	v_lshl_add_u64 v[90:91], v[92:93], 1, v[90:91]
	s_addc_u32 s51, s25, s53
	s_lshl_b32 s49, s47, 14
	v_lshl_add_u64 v[90:91], s[50:51], 1, v[90:91]
	s_waitcnt vmcnt(0)
	s_lshl_b32 s10, s52, 5
	s_add_i32 s49, s28, s49
	v_lshl_add_u64 v[120:121], v[90:91], 0, v[68:69]
	s_waitcnt lgkmcnt(0)
	s_barrier
	v_lshl_add_u64 v[90:91], v[120:121], 0, s[12:13]
	v_lshl_add_u64 v[122:123], v[120:121], 0, s[10:11]
	s_mov_b32 m0, s49
	v_lshl_add_u64 v[118:119], v[66:67], 0, s[26:27]
	global_load_lds_dwordx4 v[90:91], off
	v_lshl_add_u64 v[90:91], v[122:123], 0, s[12:13]
	s_add_i32 m0, s49, 0x400
	v_lshl_add_u64 v[78:79], v[118:119], 0, s[12:13]
	global_load_lds_dwordx4 v[90:91], off
	s_add_i32 m0, s49, 0x2000
	s_lshl_b32 s52, s48, 14
	global_load_lds_dwordx4 v[78:79], off
	s_add_i32 m0, s49, 0x2400
	s_add_i32 s10, s48, 1
	s_cmp_lg_u32 s48, 3
	s_cselect_b32 s10, s10, 0
	s_add_i32 s48, s47, 1
	v_lshl_add_u64 v[80:81], v[118:119], 0, s[14:15]
	s_cmp_lg_u32 s47, 3
	global_load_lds_dwordx4 v[80:81], off
	s_cselect_b32 s47, s48, 0
	v_add_u32_e32 v65, s52, v86
	v_or_b32_e32 v124, s52, v87
	ds_read_b128 v[78:81], v65
	ds_read_b128 v[90:93], v65 offset:1024
	ds_read_b128 v[94:97], v65 offset:2048
	ds_read_b128 v[98:101], v65 offset:3072
	ds_read_b128 v[102:105], v124
	ds_read_b128 v[106:109], v124 offset:1024
	ds_read_b128 v[110:113], v124 offset:2048
	ds_read_b128 v[114:117], v124 offset:3072
	s_waitcnt lgkmcnt(0)
	s_lshl_b32 s48, s47, 14
	s_add_i32 s48, s28, s48
	v_mfma_f32_16x16x32_bf16 v[44:47], v[102:105], v[90:93], v[44:47]
	v_mfma_f32_16x16x32_bf16 v[40:43], v[106:109], v[90:93], v[40:43]
	s_mov_b32 m0, s48
	s_add_i32 s46, s46, 2
	v_mfma_f32_16x16x32_bf16 v[36:39], v[110:113], v[90:93], v[36:39]
	v_mfma_f32_16x16x32_bf16 v[32:35], v[114:117], v[90:93], v[32:35]
	v_lshl_add_u64 v[90:91], v[120:121], 0, s[16:17]
	v_lshl_add_u64 v[92:93], v[122:123], 0, s[16:17]
	global_load_lds_dwordx4 v[90:91], off
	s_add_i32 m0, s48, 0x400
	v_mfma_f32_16x16x32_bf16 v[60:63], v[102:105], v[78:81], v[60:63]
	global_load_lds_dwordx4 v[92:93], off
	s_add_i32 m0, s48, 0x2000
	v_mfma_f32_16x16x32_bf16 v[56:59], v[106:109], v[78:81], v[56:59]
	v_mfma_f32_16x16x32_bf16 v[52:55], v[110:113], v[78:81], v[52:55]
	v_mfma_f32_16x16x32_bf16 v[48:51], v[114:117], v[78:81], v[48:51]
	v_lshl_add_u64 v[78:79], v[118:119], 0, s[16:17]
	v_lshl_add_u64 v[80:81], v[118:119], 0, s[18:19]
	global_load_lds_dwordx4 v[78:79], off
	s_add_i32 m0, s48, 0x2400
	s_lshl_b32 s48, s10, 14
	global_load_lds_dwordx4 v[80:81], off
	v_add_u32_e32 v65, s48, v86
	v_or_b32_e32 v118, s48, v87
	s_add_i32 s48, s10, 1
	v_mfma_f32_16x16x32_bf16 v[28:31], v[102:105], v[94:97], v[28:31]
	s_cmp_lg_u32 s10, 3
	s_cselect_b32 s48, s48, 0
	s_add_i32 s10, s47, 1
	v_mfma_f32_16x16x32_bf16 v[20:23], v[106:109], v[94:97], v[20:23]
	s_cmp_lg_u32 s47, 3
	s_cselect_b32 s47, s10, 0
	s_add_u32 s26, s26, 0x80
	v_mfma_f32_16x16x32_bf16 v[16:19], v[110:113], v[94:97], v[16:19]
	s_addc_u32 s27, s27, 0
	s_add_u32 s24, s24, 64
	s_addc_u32 s25, s25, 0
	v_mfma_f32_16x16x32_bf16 v[12:15], v[114:117], v[94:97], v[12:15]
	s_cmpk_eq_i32 s26, 0x780
	v_mfma_f32_16x16x32_bf16 v[8:11], v[102:105], v[98:101], v[8:11]
	v_mfma_f32_16x16x32_bf16 v[4:7], v[106:109], v[98:101], v[4:7]
	v_mfma_f32_16x16x32_bf16 v[0:3], v[110:113], v[98:101], v[0:3]
	v_mfma_f32_16x16x32_bf16 v[24:27], v[114:117], v[98:101], v[24:27]
	ds_read_b128 v[78:81], v65
	ds_read_b128 v[90:93], v65 offset:1024
	ds_read_b128 v[94:97], v65 offset:2048
	ds_read_b128 v[98:101], v65 offset:3072
	ds_read_b128 v[102:105], v118
	ds_read_b128 v[106:109], v118 offset:1024
	ds_read_b128 v[110:113], v118 offset:2048
	ds_read_b128 v[114:117], v118 offset:3072
	s_waitcnt lgkmcnt(0)
	s_nop 0
	v_mfma_f32_16x16x32_bf16 v[60:63], v[102:105], v[78:81], v[60:63]
	v_mfma_f32_16x16x32_bf16 v[56:59], v[106:109], v[78:81], v[56:59]
	v_mfma_f32_16x16x32_bf16 v[52:55], v[110:113], v[78:81], v[52:55]
	v_mfma_f32_16x16x32_bf16 v[48:51], v[114:117], v[78:81], v[48:51]
	v_mfma_f32_16x16x32_bf16 v[44:47], v[102:105], v[90:93], v[44:47]
	v_mfma_f32_16x16x32_bf16 v[40:43], v[106:109], v[90:93], v[40:43]
	v_mfma_f32_16x16x32_bf16 v[36:39], v[110:113], v[90:93], v[36:39]
	v_mfma_f32_16x16x32_bf16 v[32:35], v[114:117], v[90:93], v[32:35]
	v_mfma_f32_16x16x32_bf16 v[28:31], v[102:105], v[94:97], v[28:31]
	v_mfma_f32_16x16x32_bf16 v[20:23], v[106:109], v[94:97], v[20:23]
	v_mfma_f32_16x16x32_bf16 v[16:19], v[110:113], v[94:97], v[16:19]
	v_mfma_f32_16x16x32_bf16 v[12:15], v[114:117], v[94:97], v[12:15]
	v_mfma_f32_16x16x32_bf16 v[8:11], v[102:105], v[98:101], v[8:11]
	v_mfma_f32_16x16x32_bf16 v[4:7], v[106:109], v[98:101], v[4:7]
	v_mfma_f32_16x16x32_bf16 v[0:3], v[110:113], v[98:101], v[0:3]
	v_mfma_f32_16x16x32_bf16 v[24:27], v[114:117], v[98:101], v[24:27]
	s_cbranch_scc0 .LBB0_2892
	s_waitcnt vmcnt(4)
	s_waitcnt lgkmcnt(0)
	s_barrier
	ds_read_b128 v[64:67], v86 offset:32768
	ds_read_b128 v[78:81], v86 offset:33792
	ds_read_b128 v[90:93], v86 offset:34816
	ds_read_b128 v[94:97], v86 offset:35840
	ds_read_b128 v[98:101], v87 offset:32768
	ds_read_b128 v[102:105], v87 offset:33792
	ds_read_b128 v[106:109], v87 offset:34816
	ds_read_b128 v[110:113], v87 offset:35840
	s_waitcnt lgkmcnt(0)
	s_waitcnt vmcnt(0)
	s_waitcnt lgkmcnt(0)
	s_barrier
	v_mfma_f32_16x16x32_bf16 v[158:161], v[102:105], v[90:93], v[20:23]
	s_add_i32 s2, s2, s3
	s_add_i32 s31, s31, s33
	v_mfma_f32_16x16x32_bf16 v[114:117], v[98:101], v[64:67], v[60:63]
	v_add_u32_e32 v22, s44, v84
	v_or_b32_e32 v20, s45, v85
	v_cmp_lt_i32_e32 vcc, s43, v22
	v_mfma_f32_16x16x32_bf16 v[118:121], v[102:105], v[64:67], v[56:59]
	v_ashrrev_i32_e32 v21, 31, v20
	v_readlane_b32 s44, v241, 1
	v_readlane_b32 s52, v241, 9
	v_mfma_f32_16x16x32_bf16 v[122:125], v[106:109], v[64:67], v[52:55]
	v_readlane_b32 s53, v241, 10
	s_cmpk_gt_i32 s2, 0x9f
	v_readlane_b32 s45, v241, 2
	v_mfma_f32_16x16x32_bf16 v[126:129], v[110:113], v[64:67], v[48:51]
	v_readlane_b32 s46, v241, 3
	v_readlane_b32 s47, v241, 4
	v_readlane_b32 s48, v241, 5
	v_mfma_f32_16x16x32_bf16 v[64:67], v[106:109], v[90:93], v[16:19]
	v_readlane_b32 s49, v241, 6
	v_readlane_b32 s50, v241, 7
	v_readlane_b32 s51, v241, 8
	v_add_u32_e32 v16, 0xfffff000, v22
	v_lshrrev_b32_e32 v16, 12, v16
	v_add_u32_e32 v16, 6, v16
	v_mfma_f32_16x16x32_bf16 v[60:63], v[110:113], v[90:93], v[12:15]
	v_readlane_b32 s54, v241, 11
	v_readlane_b32 s55, v241, 12
	v_readlane_b32 s56, v241, 13
	v_cndmask_b32_e32 v12, 5, v16, vcc
	v_mfma_f32_16x16x32_bf16 v[130:133], v[98:101], v[78:81], v[44:47]
	v_mad_u64_u32 v[12:13], s[24:25], v12, s30, v[74:75]
	v_readlane_b32 s57, v241, 14
	v_mfma_f32_16x16x32_bf16 v[134:137], v[102:105], v[78:81], v[40:43]
	v_readlane_b32 s58, v241, 15
	v_readlane_b32 s59, v241, 16
	v_mfma_f32_16x16x32_bf16 v[138:141], v[106:109], v[78:81], v[36:39]
	v_mfma_f32_16x16x32_bf16 v[142:145], v[110:113], v[78:81], v[32:35]
	v_lshlrev_b64 v[78:79], 2, v[20:21]
	v_mfma_f32_16x16x32_bf16 v[52:55], v[98:101], v[94:97], v[8:11]
	s_nop 2
	v_lshl_add_u64 v[8:9], v[12:13], 0, v[78:79]
	v_lshl_add_u64 v[8:9], v[8:9], 0, v[76:77]
	v_mfma_f32_16x16x32_bf16 v[146:149], v[98:101], v[90:93], v[28:31]
	ds_read_b128 v[150:153], v86 offset:49152
	ds_read_b128 v[154:157], v86 offset:50176
	ds_read_b128 v[56:59], v86 offset:51200
	ds_read_b128 v[28:31], v86 offset:52224
	ds_read_b128 v[44:47], v87 offset:49152
	ds_read_b128 v[40:43], v87 offset:50176
	ds_read_b128 v[36:39], v87 offset:51200
	ds_read_b128 v[32:35], v87 offset:52224
	s_waitcnt lgkmcnt(0)
	v_add_co_u32_e32 v14, vcc, s29, v8
	s_waitcnt lgkmcnt(0)
	s_barrier
	v_lshl_add_u64 v[12:13], v[8:9], 0, s[20:21]
	v_or_b32_e32 v98, v22, v82
	v_addc_co_u32_e32 v15, vcc, 0, v9, vcc
	v_mfma_f32_16x16x32_bf16 v[20:23], v[106:109], v[94:97], v[0:3]
	v_or_b32_e32 v162, 16, v98
	v_or_b32_e32 v164, 32, v98
	v_or_b32_e32 v80, 48, v98
	global_load_dwordx4 v[0:3], v[12:13], off offset:64
	global_load_dwordx4 v[8:11], v[12:13], off offset:128
	global_load_dwordx4 v[16:19], v[14:15], off
	s_nop 0
	global_load_dwordx4 v[12:15], v[12:13], off offset:192
	v_mfma_f32_16x16x32_bf16 v[48:51], v[102:105], v[94:97], v[4:7]
	v_mov_b32_e32 v236, v98
	v_ashrrev_i32_e32 v237, 31, v98
	v_lshlrev_b64 v[236:237], 12, v[236:237]
	v_lshl_add_u64 v[236:237], s[52:53], 0, v[236:237]
	v_lshl_add_u64 v[236:237], v[236:237], 0, v[78:79]
	v_lshl_add_u64 v[236:237], v[236:237], 0, v[76:77]
	v_mov_b32_e32 v238, v162
	v_ashrrev_i32_e32 v239, 31, v162
	v_lshlrev_b64 v[238:239], 12, v[238:239]
	v_lshl_add_u64 v[238:239], s[52:53], 0, v[238:239]
	v_lshl_add_u64 v[238:239], v[238:239], 0, v[78:79]
	v_lshl_add_u64 v[238:239], v[238:239], 0, v[76:77]
	v_mov_b32_e32 v242, v164
	v_ashrrev_i32_e32 v243, 31, v164
	v_lshlrev_b64 v[242:243], 12, v[242:243]
	v_lshl_add_u64 v[242:243], s[52:53], 0, v[242:243]
	v_lshl_add_u64 v[242:243], v[242:243], 0, v[78:79]
	v_lshl_add_u64 v[242:243], v[242:243], 0, v[76:77]
	v_mov_b32_e32 v244, v80
	v_ashrrev_i32_e32 v245, 31, v80
	v_lshlrev_b64 v[244:245], 12, v[244:245]
	v_lshl_add_u64 v[244:245], s[52:53], 0, v[244:245]
	v_lshl_add_u64 v[244:245], v[244:245], 0, v[78:79]
	v_lshl_add_u64 v[244:245], v[244:245], 0, v[76:77]
	global_load_dwordx4 v[168:171], v[236:237], off
	global_load_dwordx4 v[172:175], v[236:237], off offset:64
	global_load_dwordx4 v[176:179], v[236:237], off offset:128
	global_load_dwordx4 v[180:183], v[236:237], off offset:192
	global_load_dwordx4 v[184:187], v[238:239], off
	global_load_dwordx4 v[188:191], v[238:239], off offset:64
	global_load_dwordx4 v[192:195], v[238:239], off offset:128
	global_load_dwordx4 v[196:199], v[238:239], off offset:192
	global_load_dwordx4 v[200:203], v[242:243], off
	global_load_dwordx4 v[204:207], v[242:243], off offset:64
	global_load_dwordx4 v[208:211], v[242:243], off offset:128
	global_load_dwordx4 v[212:215], v[242:243], off offset:192
	global_load_dwordx4 v[216:219], v[244:245], off
	global_load_dwordx4 v[220:223], v[244:245], off offset:64
	global_load_dwordx4 v[228:231], v[244:245], off offset:128
	global_load_dwordx4 v[232:235], v[244:245], off offset:192
	v_mfma_f32_16x16x32_bf16 v[4:7], v[110:113], v[94:97], v[24:27]
	v_mfma_f32_16x16x32_bf16 v[90:93], v[40:43], v[150:153], v[118:121]
	s_waitcnt vmcnt(15)
	v_pk_mul_f32 v[168:169], v[168:169], s[22:23] op_sel_hi:[1,0]
	v_mfma_f32_16x16x32_bf16 v[24:27], v[44:47], v[150:153], v[114:117]
	v_mul_f32_e64 v170, v170, s22
	v_mul_f32_e64 v171, v171, s22
	s_waitcnt vmcnt(14)
	v_pk_mul_f32 v[172:173], v[172:173], s[22:23] op_sel_hi:[1,0]
	v_pk_mul_f32 v[174:175], v[174:175], s[22:23] op_sel_hi:[1,0]
	v_mfma_f32_16x16x32_bf16 v[94:97], v[36:39], v[150:153], v[122:125]
	s_waitcnt vmcnt(13)
	v_mul_f32_e64 v176, v176, s22
	v_mul_f32_e64 v177, v177, s22
	v_pk_mul_f32 v[178:179], v[178:179], s[22:23] op_sel_hi:[1,0]
	v_pk_fma_f32 v[24:25], v[24:25], v[16:17], v[168:169]
	v_mfma_f32_16x16x32_bf16 v[102:105], v[32:35], v[150:153], v[126:129]
	v_fma_f32 v26, v26, v18, v170
	v_fma_f32 v27, v27, v19, v171
	v_pk_fma_f32 v[90:91], v[90:91], v[0:1], v[172:173]
	v_pk_fma_f32 v[92:93], v[92:93], v[2:3], v[174:175]
	v_pk_fma_f32 v[94:95], v[94:95], v[8:9], v[176:177]
	v_pk_fma_f32 v[96:97], v[96:97], v[10:11], v[178:179]
	v_mfma_f32_16x16x32_bf16 v[114:117], v[44:47], v[154:157], v[130:133]
	s_waitcnt vmcnt(12)
	v_pk_mul_f32 v[180:181], v[180:181], s[22:23] op_sel_hi:[1,0]
	v_pk_mul_f32 v[182:183], v[182:183], s[22:23] op_sel_hi:[1,0]
	v_pk_fma_f32 v[168:169], v[102:103], v[12:13], v[180:181]
	v_pk_fma_f32 v[170:171], v[104:105], v[14:15], v[182:183]
	global_store_dwordx4 v[236:237], v[24:27], off
	global_store_dwordx4 v[236:237], v[90:93], off offset:64
	global_store_dwordx4 v[236:237], v[94:97], off offset:128
	global_store_dwordx4 v[236:237], v[168:171], off offset:192
	v_mfma_f32_16x16x32_bf16 v[122:125], v[40:43], v[154:157], v[134:137]
	v_mfma_f32_16x16x32_bf16 v[90:93], v[36:39], v[154:157], v[138:141]
	s_waitcnt vmcnt(15)
	v_pk_mul_f32 v[184:185], v[184:185], s[22:23] op_sel_hi:[1,0]
	v_mfma_f32_16x16x32_bf16 v[102:105], v[32:35], v[154:157], v[142:145]
	v_mul_f32_e64 v186, v186, s22
	v_mul_f32_e64 v187, v187, s22
	s_waitcnt vmcnt(14)
	v_pk_mul_f32 v[188:189], v[188:189], s[22:23] op_sel_hi:[1,0]
	v_pk_mul_f32 v[190:191], v[190:191], s[22:23] op_sel_hi:[1,0]
	s_waitcnt vmcnt(13)
	v_pk_mul_f32 v[192:193], v[192:193], s[22:23] op_sel_hi:[1,0]
	v_pk_mul_f32 v[194:195], v[194:195], s[22:23] op_sel_hi:[1,0]
	s_waitcnt vmcnt(12)
	v_pk_mul_f32 v[196:197], v[196:197], s[22:23] op_sel_hi:[1,0]
	v_pk_mul_f32 v[198:199], v[198:199], s[22:23] op_sel_hi:[1,0]
	v_pk_fma_f32 v[184:185], v[114:115], v[16:17], v[184:185]
	v_pk_fma_f32 v[186:187], v[116:117], v[18:19], v[186:187]
	v_pk_fma_f32 v[188:189], v[122:123], v[0:1], v[188:189]
	v_pk_fma_f32 v[190:191], v[124:125], v[2:3], v[190:191]
	v_pk_fma_f32 v[90:91], v[90:91], v[8:9], v[192:193]
	v_pk_fma_f32 v[92:93], v[92:93], v[10:11], v[194:195]
	v_pk_fma_f32 v[192:193], v[102:103], v[12:13], v[196:197]
	v_pk_fma_f32 v[194:195], v[104:105], v[14:15], v[198:199]
	global_store_dwordx4 v[238:239], v[184:187], off
	global_store_dwordx4 v[238:239], v[188:191], off offset:64
	global_store_dwordx4 v[238:239], v[90:93], off offset:128
	global_store_dwordx4 v[238:239], v[192:195], off offset:192
	v_mfma_f32_16x16x32_bf16 v[176:179], v[44:47], v[56:59], v[146:149]
	v_mfma_f32_16x16x32_bf16 v[90:93], v[40:43], v[56:59], v[158:161]
	s_waitcnt vmcnt(15)
	v_pk_mul_f32 v[200:201], v[200:201], s[22:23] op_sel_hi:[1,0]
	v_mfma_f32_16x16x32_bf16 v[64:67], v[36:39], v[56:59], v[64:67]
	v_mul_f32_e64 v202, v202, s22
	v_mul_f32_e64 v203, v203, s22
	s_nop 1
	v_pk_fma_f32 v[200:201], v[176:177], v[16:17], v[200:201]
	s_nop 0
	v_pk_fma_f32 v[202:203], v[178:179], v[18:19], v[202:203]
	v_mfma_f32_16x16x32_bf16 v[56:59], v[32:35], v[56:59], v[60:63]
	s_waitcnt vmcnt(14)
	v_mul_f32_e64 v60, v204, s22
	v_mul_f32_e64 v61, v205, s22
	v_pk_mul_f32 v[62:63], v[206:207], s[22:23] op_sel_hi:[1,0]
	s_waitcnt vmcnt(13)
	v_pk_mul_f32 v[204:205], v[208:209], s[22:23] op_sel_hi:[1,0]
	v_pk_mul_f32 v[206:207], v[210:211], s[22:23] op_sel_hi:[1,0]
	s_waitcnt vmcnt(12)
	v_pk_mul_f32 v[208:209], v[212:213], s[22:23] op_sel_hi:[1,0]
	v_pk_mul_f32 v[210:211], v[214:215], s[22:23] op_sel_hi:[1,0]
	v_pk_fma_f32 v[60:61], v[90:91], v[0:1], v[60:61]
	v_pk_fma_f32 v[62:63], v[92:93], v[2:3], v[62:63]
	v_pk_fma_f32 v[64:65], v[64:65], v[8:9], v[204:205]
	v_pk_fma_f32 v[66:67], v[66:67], v[10:11], v[206:207]
	v_pk_fma_f32 v[56:57], v[56:57], v[12:13], v[208:209]
	v_pk_fma_f32 v[58:59], v[58:59], v[14:15], v[210:211]
	global_store_dwordx4 v[242:243], v[200:203], off
	global_store_dwordx4 v[242:243], v[60:63], off offset:64
	global_store_dwordx4 v[242:243], v[64:67], off offset:128
	global_store_dwordx4 v[242:243], v[56:59], off offset:192
	v_mfma_f32_16x16x32_bf16 v[44:47], v[44:47], v[28:31], v[52:55]
	v_mfma_f32_16x16x32_bf16 v[40:43], v[40:43], v[28:31], v[48:51]
	s_waitcnt vmcnt(15)
	v_pk_mul_f32 v[216:217], v[216:217], s[22:23] op_sel_hi:[1,0]
	v_mfma_f32_16x16x32_bf16 v[20:23], v[36:39], v[28:31], v[20:23]
	v_mul_f32_e64 v218, v218, s22
	v_mul_f32_e64 v219, v219, s22
	s_nop 1
	v_pk_fma_f32 v[16:17], v[44:45], v[16:17], v[216:217]
	s_nop 0
	v_pk_fma_f32 v[18:19], v[46:47], v[18:19], v[218:219]
	v_mfma_f32_16x16x32_bf16 v[4:7], v[32:35], v[28:31], v[4:7]
	s_setprio 0
	s_waitcnt vmcnt(14)
	v_mul_f32_e64 v28, v220, s22
	v_mul_f32_e64 v29, v221, s22
	v_pk_mul_f32 v[30:31], v[222:223], s[22:23] op_sel_hi:[1,0]
	s_waitcnt vmcnt(13)
	v_pk_mul_f32 v[32:33], v[228:229], s[22:23] op_sel_hi:[1,0]
	v_pk_mul_f32 v[34:35], v[230:231], s[22:23] op_sel_hi:[1,0]
	v_pk_fma_f32 v[0:1], v[40:41], v[0:1], v[28:29]
	v_pk_fma_f32 v[2:3], v[42:43], v[2:3], v[30:31]
	v_pk_fma_f32 v[8:9], v[20:21], v[8:9], v[32:33]
	v_pk_fma_f32 v[10:11], v[22:23], v[10:11], v[34:35]
	s_waitcnt vmcnt(12)
	v_pk_mul_f32 v[36:37], v[232:233], s[22:23] op_sel_hi:[1,0]
	v_pk_mul_f32 v[38:39], v[234:235], s[22:23] op_sel_hi:[1,0]
	v_pk_fma_f32 v[4:5], v[4:5], v[12:13], v[36:37]
	v_pk_fma_f32 v[6:7], v[6:7], v[14:15], v[38:39]
	global_store_dwordx4 v[244:245], v[16:19], off
	global_store_dwordx4 v[244:245], v[0:3], off offset:64
	global_store_dwordx4 v[244:245], v[8:11], off offset:128
	global_store_dwordx4 v[244:245], v[4:7], off offset:192
	s_cbranch_scc0 .LBB0_2891

.LBB0_3005:
	s_mul_hi_i32 s26, s2, 0x2e8ba2e9
	s_lshr_b32 s27, s26, 31
	s_ashr_i32 s26, s26, 4
	s_add_i32 s26, s26, s27
	s_lshl_b32 s48, s26, 1
	s_and_b32 s47, s2, 1
	s_add_i32 s49, s48, s28
	s_or_b32 s47, s49, s47
	s_lshl_b32 s47, s47, 8
	s_mul_i32 s27, s26, 0xffffffa8
	v_add_u32_e32 v0, s47, v142
	s_add_i32 s27, s27, s2
	v_ashrrev_i32_e32 v1, 31, v0
	v_lshlrev_b64 v[0:1], 11, v[0:1]
	s_lshl_b32 s27, s27, 6
	s_mov_b32 m0, s29
	v_lshl_add_u64 v[0:1], v[130:131], 0, v[0:1]
	s_and_b32 s48, s27, 0xffffff80
	v_add_u32_e32 v2, s48, v143
	s_setprio 2
	global_load_lds_dwordx4 v[0:1], off
	v_lshl_add_u64 v[4:5], v[0:1], 0, s[6:7]
	s_mov_b32 m0, s34
	v_ashrrev_i32_e32 v3, 31, v2
	global_load_lds_dwordx4 v[4:5], off
	v_lshl_add_u64 v[4:5], v[0:1], 0, s[8:9]
	s_mov_b32 m0, s35
	v_lshlrev_b64 v[2:3], 11, v[2:3]
	global_load_lds_dwordx4 v[4:5], off
	v_lshl_add_u64 v[4:5], v[0:1], 0, s[10:11]
	s_mov_b32 m0, s36
	v_lshl_add_u64 v[2:3], v[132:133], 0, v[2:3]
	global_load_lds_dwordx4 v[4:5], off
	s_mov_b32 m0, s37
	v_lshl_add_u64 v[4:5], v[2:3], 0, s[6:7]
	global_load_lds_dwordx4 v[2:3], off
	s_mov_b32 m0, s38
	s_mulk_i32 s26, 0x1600
	global_load_lds_dwordx4 v[4:5], off
	v_lshl_add_u64 v[4:5], v[0:1], 0, 64
	s_mov_b32 m0, s39
	s_sub_i32 s26, s31, s26
	global_load_lds_dwordx4 v[4:5], off
	v_lshl_add_u64 v[4:5], v[0:1], 0, s[12:13]
	s_mov_b32 m0, s40
	s_and_b32 s26, s26, 0xffffff80
	global_load_lds_dwordx4 v[4:5], off
	v_lshl_add_u64 v[4:5], v[0:1], 0, s[14:15]
	s_mov_b32 m0, s41
	v_lshl_add_u64 v[0:1], v[0:1], 0, s[16:17]
	global_load_lds_dwordx4 v[4:5], off
	s_mov_b32 m0, s42
	v_cndmask_b32_e64 v6, 0, 1, s[0:1]
	global_load_lds_dwordx4 v[0:1], off
	v_lshl_add_u64 v[0:1], v[2:3], 0, 64
	s_mov_b32 m0, s43
	s_mov_b32 s50, 0
	global_load_lds_dwordx4 v[0:1], off
	v_lshl_add_u64 v[0:1], v[2:3], 0, s[12:13]
	s_mov_b32 m0, s44
	v_mov_b32_e32 v2, v129
	global_load_lds_dwordx4 v[0:1], off
	v_add_u32_e32 v0, s26, v143
	v_ashrrev_i32_e32 v1, 31, v0
	v_lshlrev_b64 v[0:1], 11, v[0:1]
	v_lshl_add_u64 v[134:135], v[132:133], 0, v[0:1]
	v_add_u32_e32 v0, s49, v6
	v_lshl_add_u32 v0, v0, 8, v142
	v_ashrrev_i32_e32 v1, 31, v0
	v_lshlrev_b64 v[0:1], 11, v[0:1]
	v_lshl_add_u64 v[136:137], v[130:131], 0, v[0:1]
	s_mov_b64 s[26:27], 0
	s_mov_b32 s49, 2
	v_mov_b32_e32 v0, 0
	v_mov_b32_e32 v1, v129
	v_mov_b32_e32 v3, v129
	v_mov_b32_e32 v4, 0
	v_mov_b32_e32 v5, v129
	v_mov_b32_e32 v6, v129
	v_mov_b32_e32 v7, v129
	v_mov_b32_e32 v8, 0
	v_mov_b32_e32 v9, v129
	v_mov_b32_e32 v10, v129
	v_mov_b32_e32 v11, v129
	v_mov_b32_e32 v12, 0
	v_mov_b32_e32 v13, v129
	v_mov_b32_e32 v14, v129
	v_mov_b32_e32 v15, v129
	v_mov_b32_e32 v16, 0
	v_mov_b32_e32 v17, v129
	v_mov_b32_e32 v18, v129
	v_mov_b32_e32 v19, v129
	v_mov_b32_e32 v20, 0
	v_mov_b32_e32 v21, v129
	v_mov_b32_e32 v22, v129
	v_mov_b32_e32 v23, v129
	v_mov_b32_e32 v24, 0
	v_mov_b32_e32 v25, v129
	v_mov_b32_e32 v26, v129
	v_mov_b32_e32 v27, v129
	v_mov_b32_e32 v28, 0
	v_mov_b32_e32 v29, v129
	v_mov_b32_e32 v30, v129
	v_mov_b32_e32 v31, v129
	v_mov_b32_e32 v32, 0
	v_mov_b32_e32 v33, v129
	v_mov_b32_e32 v34, v129
	v_mov_b32_e32 v35, v129
	v_mov_b32_e32 v36, 0
	v_mov_b32_e32 v37, v129
	v_mov_b32_e32 v38, v129
	v_mov_b32_e32 v39, v129
	v_mov_b32_e32 v44, 0
	v_mov_b32_e32 v45, v129
	v_mov_b32_e32 v46, v129
	v_mov_b32_e32 v47, v129
	v_mov_b32_e32 v52, 0
	v_mov_b32_e32 v53, v129
	v_mov_b32_e32 v54, v129
	v_mov_b32_e32 v55, v129
	v_mov_b32_e32 v60, 0
	v_mov_b32_e32 v61, v129
	v_mov_b32_e32 v62, v129
	v_mov_b32_e32 v63, v129
	v_mov_b32_e32 v68, 0
	v_mov_b32_e32 v69, v129
	v_mov_b32_e32 v70, v129
	v_mov_b32_e32 v71, v129
	v_mov_b32_e32 v76, 0
	v_mov_b32_e32 v77, v129
	v_mov_b32_e32 v78, v129
	v_mov_b32_e32 v79, v129
	v_mov_b32_e32 v84, 0
	v_mov_b32_e32 v85, v129
	v_mov_b32_e32 v86, v129
	v_mov_b32_e32 v87, v129
	v_mov_b32_e32 v40, 0
	v_mov_b32_e32 v41, v129
	v_mov_b32_e32 v42, v129
	v_mov_b32_e32 v43, v129
	v_mov_b32_e32 v48, 0
	v_mov_b32_e32 v49, v129
	v_mov_b32_e32 v50, v129
	v_mov_b32_e32 v51, v129
	v_mov_b32_e32 v56, 0
	v_mov_b32_e32 v57, v129
	v_mov_b32_e32 v58, v129
	v_mov_b32_e32 v59, v129
	v_mov_b32_e32 v64, 0
	v_mov_b32_e32 v65, v129
	v_mov_b32_e32 v66, v129
	v_mov_b32_e32 v67, v129
	v_mov_b32_e32 v72, 0
	v_mov_b32_e32 v73, v129
	v_mov_b32_e32 v74, v129
	v_mov_b32_e32 v75, v129
	v_mov_b32_e32 v80, 0
	v_mov_b32_e32 v81, v129
	v_mov_b32_e32 v82, v129
	v_mov_b32_e32 v83, v129
	v_mov_b32_e32 v88, 0
	v_mov_b32_e32 v89, v129
	v_mov_b32_e32 v90, v129
	v_mov_b32_e32 v91, v129
	v_mov_b32_e32 v92, 0
	v_mov_b32_e32 v93, v129
	v_mov_b32_e32 v94, v129
	v_mov_b32_e32 v95, v129
	v_mov_b32_e32 v96, 0
	v_mov_b32_e32 v97, v129
	v_mov_b32_e32 v98, v129
	v_mov_b32_e32 v99, v129
	v_mov_b32_e32 v100, 0
	v_mov_b32_e32 v101, v129
	v_mov_b32_e32 v102, v129
	v_mov_b32_e32 v103, v129
	v_mov_b32_e32 v104, 0
	v_mov_b32_e32 v105, v129
	v_mov_b32_e32 v106, v129
	v_mov_b32_e32 v107, v129
	v_mov_b32_e32 v108, 0
	v_mov_b32_e32 v109, v129
	v_mov_b32_e32 v110, v129
	v_mov_b32_e32 v111, v129
	v_mov_b32_e32 v112, 0
	v_mov_b32_e32 v113, v129
	v_mov_b32_e32 v114, v129
	v_mov_b32_e32 v115, v129
	v_mov_b32_e32 v116, 0
	v_mov_b32_e32 v117, v129
	v_mov_b32_e32 v118, v129
	v_mov_b32_e32 v119, v129
	v_mov_b32_e32 v120, 0
	v_mov_b32_e32 v121, v129
	v_mov_b32_e32 v122, v129
	v_mov_b32_e32 v123, v129
	v_mov_b32_e32 v124, 0
	v_mov_b32_e32 v125, v129
	v_mov_b32_e32 v126, v129
	v_mov_b32_e32 v127, v129
.LBB0_3006:
	s_mul_i32 s51, s49, 0x6000
	s_waitcnt vmcnt(6)
	s_add_i32 s51, s29, s51
	s_mul_i32 s98, s50, 0x6000
	v_lshl_add_u64 v[196:197], v[136:137], 0, s[26:27]
	v_lshl_add_u64 v[198:199], v[134:135], 0, s[26:27]
	s_add_i32 s99, s51, s30
	s_waitcnt lgkmcnt(0)
	s_barrier
	v_add_u32_e32 v178, s98, v139
	v_add_u32_e32 v179, s98, v141
	ds_read_b128 v[162:165], v179
	ds_read_b128 v[146:149], v178
	ds_read_b128 v[166:169], v179 offset:1024
	ds_read_b128 v[170:173], v179 offset:2048
	ds_read_b128 v[174:177], v179 offset:3072
	ds_read_b128 v[150:153], v178 offset:1024
	ds_read_b128 v[154:157], v178 offset:2048
	ds_read_b128 v[158:161], v178 offset:3072
	ds_read_b128 v[180:183], v178 offset:4096
	ds_read_b128 v[184:187], v178 offset:5120
	ds_read_b128 v[188:191], v178 offset:6144
	ds_read_b128 v[192:195], v178 offset:7168
	v_lshl_add_u64 v[200:201], v[196:197], 0, s[18:19]
	s_mov_b32 m0, s51
	s_waitcnt lgkmcnt(10)
	v_mfma_f32_16x16x32_bf16 v[84:87], v[146:149], v[162:165], v[84:87]
	global_load_lds_dwordx4 v[200:201], off
	s_waitcnt lgkmcnt(9)
	v_mfma_f32_16x16x32_bf16 v[76:79], v[146:149], v[166:169], v[76:79]
	v_lshl_add_u64 v[200:201], v[196:197], 0, s[20:21]
	s_add_i32 m0, s51, 0x400
	s_waitcnt lgkmcnt(8)
	v_mfma_f32_16x16x32_bf16 v[68:71], v[146:149], v[170:173], v[68:71]
	global_load_lds_dwordx4 v[200:201], off
	s_waitcnt lgkmcnt(7)
	v_mfma_f32_16x16x32_bf16 v[60:63], v[146:149], v[174:177], v[60:63]
	v_lshl_add_u64 v[200:201], v[196:197], 0, s[22:23]
	s_add_i32 m0, s51, 0x800
	s_waitcnt lgkmcnt(6)
	v_mfma_f32_16x16x32_bf16 v[52:55], v[150:153], v[162:165], v[52:55]
	global_load_lds_dwordx4 v[200:201], off
	v_mfma_f32_16x16x32_bf16 v[44:47], v[150:153], v[166:169], v[44:47]
	v_mfma_f32_16x16x32_bf16 v[36:39], v[150:153], v[170:173], v[36:39]
	v_lshl_add_u64 v[200:201], v[196:197], 0, s[24:25]
	s_add_i32 m0, s51, 0xc00
	v_mfma_f32_16x16x32_bf16 v[32:35], v[150:153], v[174:177], v[32:35]
	global_load_lds_dwordx4 v[200:201], off
	s_waitcnt lgkmcnt(5)
	v_mfma_f32_16x16x32_bf16 v[28:31], v[154:157], v[162:165], v[28:31]
	v_lshl_add_u64 v[200:201], v[198:199], 0, s[18:19]
	s_add_i32 m0, s99, 0x4000
	v_mfma_f32_16x16x32_bf16 v[24:27], v[154:157], v[166:169], v[24:27]
	global_load_lds_dwordx4 v[200:201], off
	v_mfma_f32_16x16x32_bf16 v[20:23], v[154:157], v[170:173], v[20:23]
	v_lshl_add_u64 v[200:201], v[198:199], 0, s[20:21]
	s_add_i32 m0, s99, 0x4400
	v_mfma_f32_16x16x32_bf16 v[16:19], v[154:157], v[174:177], v[16:19]
	global_load_lds_dwordx4 v[200:201], off
	s_waitcnt lgkmcnt(4)
	v_mfma_f32_16x16x32_bf16 v[12:15], v[158:161], v[162:165], v[12:15]
	v_mfma_f32_16x16x32_bf16 v[8:11], v[158:161], v[166:169], v[8:11]
	v_mfma_f32_16x16x32_bf16 v[4:7], v[158:161], v[170:173], v[4:7]
	v_mfma_f32_16x16x32_bf16 v[0:3], v[158:161], v[174:177], v[0:3]
	s_waitcnt lgkmcnt(3)
	v_mfma_f32_16x16x32_bf16 v[124:127], v[180:183], v[162:165], v[124:127]
	v_mfma_f32_16x16x32_bf16 v[120:123], v[180:183], v[166:169], v[120:123]
	v_mfma_f32_16x16x32_bf16 v[116:119], v[180:183], v[170:173], v[116:119]
	v_mfma_f32_16x16x32_bf16 v[112:115], v[180:183], v[174:177], v[112:115]
	s_waitcnt lgkmcnt(2)
	v_mfma_f32_16x16x32_bf16 v[108:111], v[184:187], v[162:165], v[108:111]
	v_mfma_f32_16x16x32_bf16 v[104:107], v[184:187], v[166:169], v[104:107]
	v_mfma_f32_16x16x32_bf16 v[100:103], v[184:187], v[170:173], v[100:103]
	v_mfma_f32_16x16x32_bf16 v[96:99], v[184:187], v[174:177], v[96:99]
	s_waitcnt lgkmcnt(1)
	v_mfma_f32_16x16x32_bf16 v[92:95], v[188:191], v[162:165], v[92:95]
	v_mfma_f32_16x16x32_bf16 v[88:91], v[188:191], v[166:169], v[88:91]
	v_mfma_f32_16x16x32_bf16 v[80:83], v[188:191], v[170:173], v[80:83]
	v_mfma_f32_16x16x32_bf16 v[72:75], v[188:191], v[174:177], v[72:75]
	s_waitcnt lgkmcnt(0)
	v_mfma_f32_16x16x32_bf16 v[64:67], v[192:195], v[162:165], v[64:67]
	v_mfma_f32_16x16x32_bf16 v[56:59], v[192:195], v[166:169], v[56:59]
	v_mfma_f32_16x16x32_bf16 v[48:51], v[192:195], v[170:173], v[48:51]
	v_mfma_f32_16x16x32_bf16 v[40:43], v[192:195], v[174:177], v[40:43]
	s_add_i32 s51, s50, 1
	s_cmp_lg_u32 s50, 2
	s_cselect_b32 s50, s51, 0
	s_add_i32 s51, s49, 1
	s_cmp_lg_u32 s49, 2
	s_cselect_b32 s49, s51, 0
	s_add_u32 s26, s26, 64
	s_addc_u32 s27, s27, 0
	s_cmpk_eq_i32 s26, 0x780
	s_cbranch_scc0 .LBB0_3006
	s_waitcnt vmcnt(6)
	s_waitcnt lgkmcnt(0)
	s_barrier
	ds_read_b128 v[134:137], v139
	ds_read_b128 v[146:149], v139 offset:1024
	ds_read_b128 v[150:153], v139 offset:2048
	ds_read_b128 v[154:157], v139 offset:3072
	ds_read_b128 v[158:161], v141
	ds_read_b128 v[162:165], v141 offset:1024
	ds_read_b128 v[166:169], v141 offset:2048
	ds_read_b128 v[170:173], v141 offset:3072
	s_waitcnt lgkmcnt(0)
	s_nop 0
	v_mfma_f32_16x16x32_bf16 v[84:87], v[134:137], v[158:161], v[84:87]
	v_mfma_f32_16x16x32_bf16 v[76:79], v[134:137], v[162:165], v[76:79]
	v_mfma_f32_16x16x32_bf16 v[68:71], v[134:137], v[166:169], v[68:71]
	v_mfma_f32_16x16x32_bf16 v[60:63], v[134:137], v[170:173], v[60:63]
	v_mfma_f32_16x16x32_bf16 v[52:55], v[146:149], v[158:161], v[52:55]
	v_mfma_f32_16x16x32_bf16 v[44:47], v[146:149], v[162:165], v[44:47]
	v_mfma_f32_16x16x32_bf16 v[36:39], v[146:149], v[166:169], v[36:39]
	v_mfma_f32_16x16x32_bf16 v[32:35], v[146:149], v[170:173], v[32:35]
	v_mfma_f32_16x16x32_bf16 v[28:31], v[150:153], v[158:161], v[28:31]
	v_mfma_f32_16x16x32_bf16 v[24:27], v[150:153], v[162:165], v[24:27]
	v_mfma_f32_16x16x32_bf16 v[20:23], v[150:153], v[166:169], v[20:23]
	v_mfma_f32_16x16x32_bf16 v[16:19], v[150:153], v[170:173], v[16:19]
	v_mfma_f32_16x16x32_bf16 v[12:15], v[154:157], v[158:161], v[12:15]
	v_mfma_f32_16x16x32_bf16 v[8:11], v[154:157], v[162:165], v[8:11]
	v_mfma_f32_16x16x32_bf16 v[4:7], v[154:157], v[166:169], v[4:7]
	v_mfma_f32_16x16x32_bf16 v[0:3], v[154:157], v[170:173], v[0:3]
	ds_read_b128 v[134:137], v139 offset:4096
	ds_read_b128 v[146:149], v139 offset:5120
	ds_read_b128 v[150:153], v139 offset:6144
	ds_read_b128 v[154:157], v139 offset:7168
	s_waitcnt lgkmcnt(0)
	s_nop 0
	v_mfma_f32_16x16x32_bf16 v[124:127], v[134:137], v[158:161], v[124:127]
	v_mfma_f32_16x16x32_bf16 v[120:123], v[134:137], v[162:165], v[120:123]
	v_mfma_f32_16x16x32_bf16 v[174:177], v[134:137], v[166:169], v[116:119]
	v_mfma_f32_16x16x32_bf16 v[134:137], v[134:137], v[170:173], v[112:115]
	v_mfma_f32_16x16x32_bf16 v[178:181], v[146:149], v[158:161], v[108:111]
	v_mfma_f32_16x16x32_bf16 v[182:185], v[146:149], v[162:165], v[104:107]
	v_mfma_f32_16x16x32_bf16 v[186:189], v[146:149], v[166:169], v[100:103]
	v_mfma_f32_16x16x32_bf16 v[146:149], v[146:149], v[170:173], v[96:99]
	v_mfma_f32_16x16x32_bf16 v[190:193], v[150:153], v[158:161], v[92:95]
	v_mfma_f32_16x16x32_bf16 v[194:197], v[150:153], v[162:165], v[88:91]
	v_mfma_f32_16x16x32_bf16 v[198:201], v[150:153], v[166:169], v[80:83]
	v_mfma_f32_16x16x32_bf16 v[150:153], v[150:153], v[170:173], v[72:75]
	v_mfma_f32_16x16x32_bf16 v[158:161], v[154:157], v[158:161], v[64:67]
	v_mfma_f32_16x16x32_bf16 v[162:165], v[154:157], v[162:165], v[56:59]
	v_mfma_f32_16x16x32_bf16 v[166:169], v[154:157], v[166:169], v[48:51]
	v_mfma_f32_16x16x32_bf16 v[154:157], v[154:157], v[170:173], v[40:43]
	s_waitcnt vmcnt(0)
	s_waitcnt lgkmcnt(0)
	s_barrier
	ds_read_b128 v[40:43], v128
	ds_read_b128 v[48:51], v128 offset:1024
	ds_read_b128 v[56:59], v128 offset:2048
	ds_read_b128 v[170:173], v128 offset:3072
	ds_read_b128 v[202:205], v144
	ds_read_b128 v[206:209], v144 offset:1024
	ds_read_b128 v[210:213], v144 offset:2048
	ds_read_b128 v[214:217], v144 offset:3072
	s_waitcnt lgkmcnt(0)
	s_nop 0
	v_mfma_f32_16x16x32_bf16 v[222:225], v[40:43], v[206:209], v[76:79]
	v_mfma_f32_16x16x32_bf16 v[112:115], v[40:43], v[210:213], v[68:71]
	v_mfma_f32_16x16x32_bf16 v[72:75], v[170:173], v[202:205], v[12:15]
	v_mfma_f32_16x16x32_bf16 v[76:79], v[170:173], v[206:209], v[8:11]
	v_mfma_f32_16x16x32_bf16 v[64:67], v[170:173], v[210:213], v[4:7]
	v_mfma_f32_16x16x32_bf16 v[68:71], v[170:173], v[214:217], v[0:3]
	ds_read_b128 v[0:3], v128 offset:4096
	ds_read_b128 v[4:7], v128 offset:5120
	ds_read_b128 v[8:11], v128 offset:6144
	ds_read_b128 v[170:173], v128 offset:7168
	s_waitcnt lgkmcnt(0)
	v_mfma_f32_16x16x32_bf16 v[218:221], v[40:43], v[202:205], v[84:87]
	v_mfma_f32_16x16x32_bf16 v[116:119], v[40:43], v[214:217], v[60:63]
	v_mfma_f32_16x16x32_bf16 v[104:107], v[48:51], v[202:205], v[52:55]
	v_mfma_f32_16x16x32_bf16 v[108:111], v[48:51], v[206:209], v[44:47]
	v_mfma_f32_16x16x32_bf16 v[96:99], v[48:51], v[210:213], v[36:39]
	v_mfma_f32_16x16x32_bf16 v[100:103], v[48:51], v[214:217], v[32:35]
	v_mfma_f32_16x16x32_bf16 v[88:91], v[56:59], v[202:205], v[28:31]
	v_mfma_f32_16x16x32_bf16 v[92:95], v[56:59], v[206:209], v[24:27]
	v_mfma_f32_16x16x32_bf16 v[80:83], v[56:59], v[210:213], v[20:23]
	v_mfma_f32_16x16x32_bf16 v[84:87], v[56:59], v[214:217], v[16:19]
	v_mfma_f32_16x16x32_bf16 v[56:59], v[0:3], v[202:205], v[124:127]
	v_mfma_f32_16x16x32_bf16 v[60:63], v[0:3], v[206:209], v[120:123]
	v_mfma_f32_16x16x32_bf16 v[48:51], v[0:3], v[210:213], v[174:177]
	v_mfma_f32_16x16x32_bf16 v[52:55], v[0:3], v[214:217], v[134:137]
	v_mfma_f32_16x16x32_bf16 v[40:43], v[4:7], v[202:205], v[178:181]
	v_mfma_f32_16x16x32_bf16 v[44:47], v[4:7], v[206:209], v[182:185]
	v_mfma_f32_16x16x32_bf16 v[32:35], v[4:7], v[210:213], v[186:189]
	v_mfma_f32_16x16x32_bf16 v[36:39], v[4:7], v[214:217], v[146:149]
	v_mfma_f32_16x16x32_bf16 v[24:27], v[8:11], v[202:205], v[190:193]
	v_mfma_f32_16x16x32_bf16 v[28:31], v[8:11], v[206:209], v[194:197]
	v_mfma_f32_16x16x32_bf16 v[16:19], v[8:11], v[210:213], v[198:201]
	v_mfma_f32_16x16x32_bf16 v[20:23], v[8:11], v[214:217], v[150:153]
	v_mfma_f32_16x16x32_bf16 v[8:11], v[170:173], v[202:205], v[158:161]
	v_mfma_f32_16x16x32_bf16 v[12:15], v[170:173], v[206:209], v[162:165]
	v_mfma_f32_16x16x32_bf16 v[0:3], v[170:173], v[210:213], v[166:169]
	v_mfma_f32_16x16x32_bf16 v[4:7], v[170:173], v[214:217], v[154:157]
	s_setprio 0
	v_mul_f32_e32 v121, 0xbfb8aa3b, v218
	v_exp_f32_e32 v121, v121
	v_or_b32_e32 v120, s48, v140
	v_ashrrev_i32_e32 v120, 1, v120
	v_or_b32_e32 v122, v120, v138
	v_add_f32_e32 v120, 1.0, v121
	v_rcp_f32_e32 v125, v120
	v_add_u32_e32 v124, s47, v145
	v_mov_b32_e32 v126, v124
	s_waitcnt lgkmcnt(0)
	v_mul_f32_e32 v120, v218, v125
	v_mul_f32_e32 v120, v222, v120
	v_mul_f32_e32 v134, 0xbfb8aa3b, v219
	v_exp_f32_e32 v134, v134
	s_barrier
	v_ashrrev_i32_e32 v123, 31, v122
	v_cvt_pk_bf16_f32 v125, v120, v120
	v_mov_b64_e32 v[120:121], s[52:53]
	v_mad_i64_i32 v[126:127], s[26:27], v126, s45, v[120:121]
	v_lshlrev_b64 v[122:123], 1, v[122:123]
	v_lshl_add_u64 v[126:127], v[126:127], 0, v[122:123]
	global_store_short_d16_hi v[126:127], v125, off
	v_add_f32_e32 v125, 1.0, v134
	v_rcp_f32_e32 v127, v125
	v_or_b32_e32 v134, 1, v124
	v_mov_b32_e32 v135, v134
	v_mul_f32_e32 v125, v219, v127
	v_mul_f32_e32 v125, v223, v125
	v_cvt_pk_bf16_f32 v125, v125, v125
	v_mul_f32_e32 v126, 0xbfb8aa3b, v220
	v_exp_f32_e32 v136, v126
	v_mad_i64_i32 v[126:127], s[26:27], v135, s45, v[120:121]
	v_lshl_add_u64 v[126:127], v[126:127], 0, v[122:123]
	global_store_short_d16_hi v[126:127], v125, off
	v_add_f32_e32 v125, 1.0, v136
	v_rcp_f32_e32 v127, v125
	v_or_b32_e32 v135, 2, v124
	v_mov_b32_e32 v136, v135
	v_mul_f32_e32 v125, v220, v127
	v_mul_f32_e32 v125, v224, v125
	v_cvt_pk_bf16_f32 v125, v125, v125
	v_mul_f32_e32 v126, 0xbfb8aa3b, v221
	v_exp_f32_e32 v137, v126
	v_mad_i64_i32 v[126:127], s[26:27], v136, s45, v[120:121]
	v_lshl_add_u64 v[126:127], v[126:127], 0, v[122:123]
	global_store_short_d16_hi v[126:127], v125, off
	v_add_f32_e32 v125, 1.0, v137
	v_rcp_f32_e32 v127, v125
	v_or_b32_e32 v136, 3, v124
	v_mov_b32_e32 v137, v136
	v_mul_f32_e32 v125, v221, v127
	v_mul_f32_e32 v125, v225, v125
	v_cvt_pk_bf16_f32 v125, v125, v125
	v_mul_f32_e32 v126, 0xbfb8aa3b, v112
	v_exp_f32_e32 v146, v126
	v_mad_i64_i32 v[126:127], s[26:27], v137, s45, v[120:121]
	v_lshl_add_u64 v[126:127], v[126:127], 0, v[122:123]
	v_add_f32_e32 v137, 1.0, v146
	v_rcp_f32_e32 v147, v137
	global_store_short_d16_hi v[126:127], v125, off
	v_mov_b32_e32 v125, v124
	v_mul_f32_e32 v112, v112, v147
	v_mul_f32_e32 v126, 0xbfb8aa3b, v113
	v_exp_f32_e32 v137, v126
	v_mul_f32_e32 v112, v116, v112
	v_cvt_pk_bf16_f32 v112, v112, v112
	v_add_f32_e32 v116, 1.0, v137
	v_mad_i64_i32 v[126:127], s[26:27], v125, s45, v[120:121]
	v_rcp_f32_e32 v137, v116
	v_lshl_add_u64 v[126:127], v[126:127], 0, v[122:123]
	global_store_short_d16_hi v[126:127], v112, off offset:32
	v_mul_f32_e32 v112, v113, v137
	v_mul_f32_e32 v116, 0xbfb8aa3b, v114
	v_exp_f32_e32 v116, v116
	v_mul_f32_e32 v112, v117, v112
	v_cvt_pk_bf16_f32 v117, v112, v112
	v_add_f32_e32 v116, 1.0, v116
	v_rcp_f32_e32 v126, v116
	v_mad_i64_i32 v[112:113], s[26:27], v134, s45, v[120:121]
	v_lshl_add_u64 v[112:113], v[112:113], 0, v[122:123]
	global_store_short_d16_hi v[112:113], v117, off offset:32
	v_mul_f32_e32 v112, v114, v126
	v_mul_f32_e32 v114, 0xbfb8aa3b, v115
	v_exp_f32_e32 v114, v114
	v_mul_f32_e32 v112, v118, v112
	v_add_f32_e32 v114, 1.0, v114
	v_rcp_f32_e32 v118, v114
	v_cvt_pk_bf16_f32 v116, v112, v112
	v_mad_i64_i32 v[112:113], s[26:27], v135, s45, v[120:121]
	v_lshl_add_u64 v[112:113], v[112:113], 0, v[122:123]
	global_store_short_d16_hi v[112:113], v116, off offset:32
	v_mul_f32_e32 v112, v115, v118
	v_mul_f32_e32 v112, v119, v112
	v_cvt_pk_bf16_f32 v114, v112, v112
	v_mul_f32_e32 v112, 0xbfb8aa3b, v104
	v_exp_f32_e32 v115, v112
	s_nop 0
	v_mad_i64_i32 v[112:113], s[26:27], v136, s45, v[120:121]
	v_lshl_add_u64 v[112:113], v[112:113], 0, v[122:123]
	global_store_short_d16_hi v[112:113], v114, off offset:32
	v_add_f32_e32 v112, 1.0, v115
	v_rcp_f32_e32 v114, v112
	v_or_b32_e32 v115, 16, v124
	v_mov_b32_e32 v116, v115
	v_mul_f32_e32 v104, v104, v114
	v_mul_f32_e32 v104, v108, v104
	v_cvt_pk_bf16_f32 v104, v104, v104
	v_mul_f32_e32 v108, 0xbfb8aa3b, v105
	v_exp_f32_e32 v108, v108
	v_mad_i64_i32 v[112:113], s[26:27], v116, s45, v[120:121]
	v_lshl_add_u64 v[112:113], v[112:113], 0, v[122:123]
	global_store_short_d16_hi v[112:113], v104, off
	v_add_f32_e32 v104, 1.0, v108
	v_rcp_f32_e32 v112, v104
	v_or_b32_e32 v113, 17, v124
	v_mov_b32_e32 v114, v113
	v_mul_f32_e32 v104, v105, v112
	v_mul_f32_e32 v104, v109, v104
	v_cvt_pk_bf16_f32 v108, v104, v104
	v_mul_f32_e32 v104, 0xbfb8aa3b, v106
	v_exp_f32_e32 v109, v104
	v_mad_i64_i32 v[104:105], s[26:27], v114, s45, v[120:121]
	v_lshl_add_u64 v[104:105], v[104:105], 0, v[122:123]
	global_store_short_d16_hi v[104:105], v108, off
	v_add_f32_e32 v104, 1.0, v109
	v_rcp_f32_e32 v108, v104
	v_or_b32_e32 v109, 18, v124
	v_mov_b32_e32 v112, v109
	v_mul_f32_e32 v104, v106, v108
	v_mul_f32_e32 v104, v110, v104
	v_cvt_pk_bf16_f32 v106, v104, v104
	v_mul_f32_e32 v104, 0xbfb8aa3b, v107
	v_exp_f32_e32 v108, v104
	v_mad_i64_i32 v[104:105], s[26:27], v112, s45, v[120:121]
	v_lshl_add_u64 v[104:105], v[104:105], 0, v[122:123]
	global_store_short_d16_hi v[104:105], v106, off
	v_add_f32_e32 v104, 1.0, v108
	v_rcp_f32_e32 v106, v104
	v_or_b32_e32 v108, 19, v124
	v_mov_b32_e32 v110, v108
	v_mul_f32_e32 v104, v107, v106
	v_mul_f32_e32 v106, 0xbfb8aa3b, v96
	v_exp_f32_e32 v106, v106
	v_mul_f32_e32 v104, v111, v104
	v_add_f32_e32 v106, 1.0, v106
	v_cvt_pk_bf16_f32 v107, v104, v104
	v_mad_i64_i32 v[104:105], s[26:27], v110, s45, v[120:121]
	v_rcp_f32_e32 v111, v106
	v_lshl_add_u64 v[104:105], v[104:105], 0, v[122:123]
	global_store_short_d16_hi v[104:105], v107, off
	v_mul_f32_e32 v96, v96, v111
	v_mul_f32_e32 v104, 0xbfb8aa3b, v97
	v_exp_f32_e32 v106, v104
	v_mul_f32_e32 v96, v100, v96
	v_cvt_pk_bf16_f32 v96, v96, v96
	v_add_f32_e32 v100, 1.0, v106
	v_rcp_f32_e32 v107, v100
	v_mad_i64_i32 v[104:105], s[26:27], v115, s45, v[120:121]
	v_lshl_add_u64 v[104:105], v[104:105], 0, v[122:123]
	global_store_short_d16_hi v[104:105], v96, off offset:32
	v_mul_f32_e32 v96, v97, v107
	v_mul_f32_e32 v100, 0xbfb8aa3b, v98
	v_exp_f32_e32 v100, v100
	v_mul_f32_e32 v96, v101, v96
	v_add_f32_e32 v100, 1.0, v100
	v_rcp_f32_e32 v105, v100
	v_cvt_pk_bf16_f32 v101, v96, v96
	v_mad_i64_i32 v[96:97], s[26:27], v113, s45, v[120:121]
	v_lshl_add_u64 v[96:97], v[96:97], 0, v[122:123]
	global_store_short_d16_hi v[96:97], v101, off offset:32
	v_mul_f32_e32 v96, v98, v105
	v_mul_f32_e32 v98, 0xbfb8aa3b, v99
	v_exp_f32_e32 v98, v98
	v_mul_f32_e32 v96, v102, v96
	v_add_f32_e32 v98, 1.0, v98
	v_rcp_f32_e32 v102, v98
	v_cvt_pk_bf16_f32 v100, v96, v96
	v_mad_i64_i32 v[96:97], s[26:27], v109, s45, v[120:121]
	v_lshl_add_u64 v[96:97], v[96:97], 0, v[122:123]
	global_store_short_d16_hi v[96:97], v100, off offset:32
	v_mul_f32_e32 v96, v99, v102
	v_mul_f32_e32 v96, v103, v96
	v_cvt_pk_bf16_f32 v98, v96, v96
	v_mul_f32_e32 v96, 0xbfb8aa3b, v88
	v_exp_f32_e32 v99, v96
	s_nop 0
	v_mad_i64_i32 v[96:97], s[26:27], v108, s45, v[120:121]
	v_lshl_add_u64 v[96:97], v[96:97], 0, v[122:123]
	global_store_short_d16_hi v[96:97], v98, off offset:32
	v_add_f32_e32 v96, 1.0, v99
	v_rcp_f32_e32 v98, v96
	v_or_b32_e32 v99, 32, v124
	v_mov_b32_e32 v100, v99
	v_mul_f32_e32 v88, v88, v98
	v_mul_f32_e32 v88, v92, v88
	v_cvt_pk_bf16_f32 v88, v88, v88
	v_mul_f32_e32 v92, 0xbfb8aa3b, v89
	v_exp_f32_e32 v92, v92
	v_mad_i64_i32 v[96:97], s[26:27], v100, s45, v[120:121]
	v_lshl_add_u64 v[96:97], v[96:97], 0, v[122:123]
	global_store_short_d16_hi v[96:97], v88, off
	v_add_f32_e32 v88, 1.0, v92
	v_rcp_f32_e32 v96, v88
	v_or_b32_e32 v97, 33, v124
	v_mov_b32_e32 v98, v97
	v_mul_f32_e32 v88, v89, v96
	v_mul_f32_e32 v88, v93, v88
	v_cvt_pk_bf16_f32 v92, v88, v88
	v_mul_f32_e32 v88, 0xbfb8aa3b, v90
	v_exp_f32_e32 v93, v88
	v_mad_i64_i32 v[88:89], s[26:27], v98, s45, v[120:121]
	v_lshl_add_u64 v[88:89], v[88:89], 0, v[122:123]
	global_store_short_d16_hi v[88:89], v92, off
	v_add_f32_e32 v88, 1.0, v93
	v_rcp_f32_e32 v92, v88
	v_or_b32_e32 v93, 34, v124
	v_mov_b32_e32 v96, v93
	v_mul_f32_e32 v88, v90, v92
	v_mul_f32_e32 v88, v94, v88
	v_cvt_pk_bf16_f32 v90, v88, v88
	v_mul_f32_e32 v88, 0xbfb8aa3b, v91
	v_exp_f32_e32 v92, v88
	v_mad_i64_i32 v[88:89], s[26:27], v96, s45, v[120:121]
	v_lshl_add_u64 v[88:89], v[88:89], 0, v[122:123]
	global_store_short_d16_hi v[88:89], v90, off
	v_add_f32_e32 v88, 1.0, v92
	v_rcp_f32_e32 v90, v88
	v_or_b32_e32 v92, 35, v124
	v_mov_b32_e32 v94, v92
	v_mul_f32_e32 v88, v91, v90
	v_mul_f32_e32 v90, 0xbfb8aa3b, v80
	v_exp_f32_e32 v90, v90
	v_mul_f32_e32 v88, v95, v88
	v_add_f32_e32 v90, 1.0, v90
	v_cvt_pk_bf16_f32 v91, v88, v88
	v_mad_i64_i32 v[88:89], s[26:27], v94, s45, v[120:121]
	v_rcp_f32_e32 v95, v90
	v_lshl_add_u64 v[88:89], v[88:89], 0, v[122:123]
	global_store_short_d16_hi v[88:89], v91, off
	v_mul_f32_e32 v80, v80, v95
	v_mul_f32_e32 v88, 0xbfb8aa3b, v81
	v_exp_f32_e32 v90, v88
	v_mul_f32_e32 v80, v84, v80
	v_cvt_pk_bf16_f32 v80, v80, v80
	v_add_f32_e32 v84, 1.0, v90
	v_rcp_f32_e32 v91, v84
	v_mad_i64_i32 v[88:89], s[26:27], v99, s45, v[120:121]
	v_lshl_add_u64 v[88:89], v[88:89], 0, v[122:123]
	global_store_short_d16_hi v[88:89], v80, off offset:32
	v_mul_f32_e32 v80, v81, v91
	v_mul_f32_e32 v84, 0xbfb8aa3b, v82
	v_exp_f32_e32 v84, v84
	v_mul_f32_e32 v80, v85, v80
	v_add_f32_e32 v84, 1.0, v84
	v_rcp_f32_e32 v89, v84
	v_cvt_pk_bf16_f32 v85, v80, v80
	v_mad_i64_i32 v[80:81], s[26:27], v97, s45, v[120:121]
	v_lshl_add_u64 v[80:81], v[80:81], 0, v[122:123]
	global_store_short_d16_hi v[80:81], v85, off offset:32
	v_mul_f32_e32 v80, v82, v89
	v_mul_f32_e32 v82, 0xbfb8aa3b, v83
	v_exp_f32_e32 v82, v82
	v_mul_f32_e32 v80, v86, v80
	v_add_f32_e32 v82, 1.0, v82
	v_rcp_f32_e32 v86, v82
	v_cvt_pk_bf16_f32 v84, v80, v80
	v_mad_i64_i32 v[80:81], s[26:27], v93, s45, v[120:121]
	v_lshl_add_u64 v[80:81], v[80:81], 0, v[122:123]
	global_store_short_d16_hi v[80:81], v84, off offset:32
	v_mul_f32_e32 v80, v83, v86
	v_mul_f32_e32 v80, v87, v80
	v_cvt_pk_bf16_f32 v82, v80, v80
	v_mul_f32_e32 v80, 0xbfb8aa3b, v72
	v_exp_f32_e32 v83, v80
	s_nop 0
	v_mad_i64_i32 v[80:81], s[26:27], v92, s45, v[120:121]
	v_lshl_add_u64 v[80:81], v[80:81], 0, v[122:123]
	global_store_short_d16_hi v[80:81], v82, off offset:32
	v_add_f32_e32 v80, 1.0, v83
	v_rcp_f32_e32 v82, v80
	v_or_b32_e32 v83, 48, v124
	v_mov_b32_e32 v84, v83
	v_mul_f32_e32 v72, v72, v82
	v_mul_f32_e32 v72, v76, v72
	v_cvt_pk_bf16_f32 v72, v72, v72
	v_mul_f32_e32 v76, 0xbfb8aa3b, v73
	v_exp_f32_e32 v76, v76
	v_mad_i64_i32 v[80:81], s[26:27], v84, s45, v[120:121]
	v_lshl_add_u64 v[80:81], v[80:81], 0, v[122:123]
	global_store_short_d16_hi v[80:81], v72, off
	v_add_f32_e32 v72, 1.0, v76
	v_rcp_f32_e32 v80, v72
	v_or_b32_e32 v81, 49, v124
	v_mov_b32_e32 v82, v81
	v_mul_f32_e32 v72, v73, v80
	v_mul_f32_e32 v72, v77, v72
	v_cvt_pk_bf16_f32 v76, v72, v72
	v_mul_f32_e32 v72, 0xbfb8aa3b, v74
	v_exp_f32_e32 v77, v72
	v_mad_i64_i32 v[72:73], s[26:27], v82, s45, v[120:121]
	v_lshl_add_u64 v[72:73], v[72:73], 0, v[122:123]
	global_store_short_d16_hi v[72:73], v76, off
	v_add_f32_e32 v72, 1.0, v77
	v_rcp_f32_e32 v76, v72
	v_or_b32_e32 v77, 50, v124
	v_mov_b32_e32 v80, v77
	v_mul_f32_e32 v72, v74, v76
	v_mul_f32_e32 v72, v78, v72
	v_cvt_pk_bf16_f32 v74, v72, v72
	v_mul_f32_e32 v72, 0xbfb8aa3b, v75
	v_exp_f32_e32 v76, v72
	v_mad_i64_i32 v[72:73], s[26:27], v80, s45, v[120:121]
	v_lshl_add_u64 v[72:73], v[72:73], 0, v[122:123]
	global_store_short_d16_hi v[72:73], v74, off
	v_add_f32_e32 v72, 1.0, v76
	v_rcp_f32_e32 v74, v72
	v_or_b32_e32 v76, 51, v124
	v_mov_b32_e32 v78, v76
	v_mul_f32_e32 v72, v75, v74
	v_mul_f32_e32 v74, 0xbfb8aa3b, v64
	v_exp_f32_e32 v74, v74
	v_mul_f32_e32 v72, v79, v72
	v_add_f32_e32 v74, 1.0, v74
	v_cvt_pk_bf16_f32 v75, v72, v72
	v_mad_i64_i32 v[72:73], s[26:27], v78, s45, v[120:121]
	v_rcp_f32_e32 v79, v74
	v_lshl_add_u64 v[72:73], v[72:73], 0, v[122:123]
	global_store_short_d16_hi v[72:73], v75, off
	v_mul_f32_e32 v64, v64, v79
	v_mul_f32_e32 v72, 0xbfb8aa3b, v65
	v_exp_f32_e32 v74, v72
	v_mul_f32_e32 v64, v68, v64
	v_cvt_pk_bf16_f32 v64, v64, v64
	v_add_f32_e32 v68, 1.0, v74
	v_rcp_f32_e32 v75, v68
	v_mad_i64_i32 v[72:73], s[26:27], v83, s45, v[120:121]
	v_lshl_add_u64 v[72:73], v[72:73], 0, v[122:123]
	global_store_short_d16_hi v[72:73], v64, off offset:32
	v_mul_f32_e32 v64, v65, v75
	v_mul_f32_e32 v68, 0xbfb8aa3b, v66
	v_exp_f32_e32 v68, v68
	v_mul_f32_e32 v64, v69, v64
	v_add_f32_e32 v68, 1.0, v68
	v_rcp_f32_e32 v73, v68
	v_cvt_pk_bf16_f32 v69, v64, v64
	v_mad_i64_i32 v[64:65], s[26:27], v81, s45, v[120:121]
	v_lshl_add_u64 v[64:65], v[64:65], 0, v[122:123]
	global_store_short_d16_hi v[64:65], v69, off offset:32
	v_mul_f32_e32 v64, v66, v73
	v_mul_f32_e32 v66, 0xbfb8aa3b, v67
	v_exp_f32_e32 v66, v66
	v_mul_f32_e32 v64, v70, v64
	v_add_f32_e32 v66, 1.0, v66
	v_rcp_f32_e32 v70, v66
	v_cvt_pk_bf16_f32 v68, v64, v64
	v_mad_i64_i32 v[64:65], s[26:27], v77, s45, v[120:121]
	v_lshl_add_u64 v[64:65], v[64:65], 0, v[122:123]
	global_store_short_d16_hi v[64:65], v68, off offset:32
	v_mul_f32_e32 v64, v67, v70
	v_mul_f32_e32 v64, v71, v64
	v_cvt_pk_bf16_f32 v66, v64, v64
	v_mad_i64_i32 v[64:65], s[26:27], v76, s45, v[120:121]
	v_lshl_add_u64 v[64:65], v[64:65], 0, v[122:123]
	global_store_short_d16_hi v[64:65], v66, off offset:32
	v_mul_f32_e32 v64, 0xbfb8aa3b, v56
	v_exp_f32_e32 v64, v64
	v_or_b32_e32 v66, 64, v124
	v_mov_b32_e32 v65, v66
	v_add_f32_e32 v64, 1.0, v64
	v_rcp_f32_e32 v68, v64
	s_add_i32 s2, s2, s3
	v_mul_f32_e32 v56, v56, v68
	v_mul_f32_e32 v56, v60, v56
	v_cvt_pk_bf16_f32 v56, v56, v56
	v_mul_f32_e32 v60, 0xbfb8aa3b, v57
	v_exp_f32_e32 v60, v60
	v_mad_i64_i32 v[64:65], s[26:27], v65, s45, v[120:121]
	v_lshl_add_u64 v[64:65], v[64:65], 0, v[122:123]
	global_store_short_d16_hi v[64:65], v56, off
	v_add_f32_e32 v56, 1.0, v60
	v_rcp_f32_e32 v64, v56
	v_or_b32_e32 v65, 0x41, v124
	v_mov_b32_e32 v67, v65
	v_mul_f32_e32 v56, v57, v64
	v_mul_f32_e32 v56, v61, v56
	v_cvt_pk_bf16_f32 v60, v56, v56
	v_mul_f32_e32 v56, 0xbfb8aa3b, v58
	v_exp_f32_e32 v61, v56
	v_mad_i64_i32 v[56:57], s[26:27], v67, s45, v[120:121]
	v_lshl_add_u64 v[56:57], v[56:57], 0, v[122:123]
	global_store_short_d16_hi v[56:57], v60, off
	v_add_f32_e32 v56, 1.0, v61
	v_rcp_f32_e32 v60, v56
	v_or_b32_e32 v61, 0x42, v124
	v_mov_b32_e32 v64, v61
	v_mul_f32_e32 v56, v58, v60
	v_mul_f32_e32 v56, v62, v56
	v_cvt_pk_bf16_f32 v58, v56, v56
	v_mul_f32_e32 v56, 0xbfb8aa3b, v59
	v_exp_f32_e32 v60, v56
	v_mad_i64_i32 v[56:57], s[26:27], v64, s45, v[120:121]
	v_lshl_add_u64 v[56:57], v[56:57], 0, v[122:123]
	global_store_short_d16_hi v[56:57], v58, off
	v_add_f32_e32 v56, 1.0, v60
	v_rcp_f32_e32 v58, v56
	v_or_b32_e32 v60, 0x43, v124
	v_mov_b32_e32 v62, v60
	v_mul_f32_e32 v56, v59, v58
	v_mul_f32_e32 v58, 0xbfb8aa3b, v48
	v_exp_f32_e32 v58, v58
	v_mul_f32_e32 v56, v63, v56
	v_add_f32_e32 v58, 1.0, v58
	v_cvt_pk_bf16_f32 v59, v56, v56
	v_mad_i64_i32 v[56:57], s[26:27], v62, s45, v[120:121]
	v_rcp_f32_e32 v63, v58
	v_lshl_add_u64 v[56:57], v[56:57], 0, v[122:123]
	global_store_short_d16_hi v[56:57], v59, off
	v_mul_f32_e32 v48, v48, v63
	v_mul_f32_e32 v56, 0xbfb8aa3b, v49
	v_exp_f32_e32 v58, v56
	v_mul_f32_e32 v48, v52, v48
	v_cvt_pk_bf16_f32 v48, v48, v48
	v_add_f32_e32 v52, 1.0, v58
	v_rcp_f32_e32 v59, v52
	v_mad_i64_i32 v[56:57], s[26:27], v66, s45, v[120:121]
	v_lshl_add_u64 v[56:57], v[56:57], 0, v[122:123]
	global_store_short_d16_hi v[56:57], v48, off offset:32
	v_mul_f32_e32 v48, v49, v59
	v_mul_f32_e32 v52, 0xbfb8aa3b, v50
	v_exp_f32_e32 v52, v52
	v_mul_f32_e32 v48, v53, v48
	v_add_f32_e32 v52, 1.0, v52
	v_rcp_f32_e32 v57, v52
	v_cvt_pk_bf16_f32 v53, v48, v48
	v_mad_i64_i32 v[48:49], s[26:27], v65, s45, v[120:121]
	v_lshl_add_u64 v[48:49], v[48:49], 0, v[122:123]
	global_store_short_d16_hi v[48:49], v53, off offset:32
	v_mul_f32_e32 v48, v50, v57
	v_mul_f32_e32 v50, 0xbfb8aa3b, v51
	v_exp_f32_e32 v50, v50
	v_mul_f32_e32 v48, v54, v48
	v_add_f32_e32 v50, 1.0, v50
	v_rcp_f32_e32 v54, v50
	v_cvt_pk_bf16_f32 v52, v48, v48
	v_mad_i64_i32 v[48:49], s[26:27], v61, s45, v[120:121]
	v_lshl_add_u64 v[48:49], v[48:49], 0, v[122:123]
	global_store_short_d16_hi v[48:49], v52, off offset:32
	v_mul_f32_e32 v48, v51, v54
	v_mul_f32_e32 v48, v55, v48
	v_cvt_pk_bf16_f32 v50, v48, v48
	v_mul_f32_e32 v48, 0xbfb8aa3b, v40
	v_exp_f32_e32 v51, v48
	s_add_i32 s31, s31, s33
	v_mad_i64_i32 v[48:49], s[26:27], v60, s45, v[120:121]
	v_lshl_add_u64 v[48:49], v[48:49], 0, v[122:123]
	global_store_short_d16_hi v[48:49], v50, off offset:32
	v_add_f32_e32 v48, 1.0, v51
	v_rcp_f32_e32 v50, v48
	v_or_b32_e32 v51, 0x50, v124
	v_mov_b32_e32 v52, v51
	v_mul_f32_e32 v40, v40, v50
	v_mul_f32_e32 v40, v44, v40
	v_cvt_pk_bf16_f32 v40, v40, v40
	v_mul_f32_e32 v44, 0xbfb8aa3b, v41
	v_exp_f32_e32 v44, v44
	v_mad_i64_i32 v[48:49], s[26:27], v52, s45, v[120:121]
	v_lshl_add_u64 v[48:49], v[48:49], 0, v[122:123]
	global_store_short_d16_hi v[48:49], v40, off
	v_add_f32_e32 v40, 1.0, v44
	v_rcp_f32_e32 v48, v40
	v_or_b32_e32 v49, 0x51, v124
	v_mov_b32_e32 v50, v49
	v_mul_f32_e32 v40, v41, v48
	v_mul_f32_e32 v40, v45, v40
	v_cvt_pk_bf16_f32 v44, v40, v40
	v_mul_f32_e32 v40, 0xbfb8aa3b, v42
	v_exp_f32_e32 v45, v40
	v_mad_i64_i32 v[40:41], s[26:27], v50, s45, v[120:121]
	v_lshl_add_u64 v[40:41], v[40:41], 0, v[122:123]
	global_store_short_d16_hi v[40:41], v44, off
	v_add_f32_e32 v40, 1.0, v45
	v_rcp_f32_e32 v44, v40
	v_or_b32_e32 v45, 0x52, v124
	v_mov_b32_e32 v48, v45
	v_mul_f32_e32 v40, v42, v44
	v_mul_f32_e32 v40, v46, v40
	v_cvt_pk_bf16_f32 v42, v40, v40
	v_mul_f32_e32 v40, 0xbfb8aa3b, v43
	v_exp_f32_e32 v44, v40
	v_mad_i64_i32 v[40:41], s[26:27], v48, s45, v[120:121]
	v_lshl_add_u64 v[40:41], v[40:41], 0, v[122:123]
	global_store_short_d16_hi v[40:41], v42, off
	v_add_f32_e32 v40, 1.0, v44
	v_rcp_f32_e32 v42, v40
	v_or_b32_e32 v44, 0x53, v124
	v_mov_b32_e32 v46, v44
	v_mul_f32_e32 v40, v43, v42
	v_mul_f32_e32 v42, 0xbfb8aa3b, v32
	v_exp_f32_e32 v42, v42
	v_mul_f32_e32 v40, v47, v40
	v_add_f32_e32 v42, 1.0, v42
	v_cvt_pk_bf16_f32 v43, v40, v40
	v_mad_i64_i32 v[40:41], s[26:27], v46, s45, v[120:121]
	v_rcp_f32_e32 v47, v42
	v_lshl_add_u64 v[40:41], v[40:41], 0, v[122:123]
	global_store_short_d16_hi v[40:41], v43, off
	v_mul_f32_e32 v32, v32, v47
	v_mul_f32_e32 v40, 0xbfb8aa3b, v33
	v_exp_f32_e32 v42, v40
	v_mul_f32_e32 v32, v36, v32
	v_cvt_pk_bf16_f32 v32, v32, v32
	v_add_f32_e32 v36, 1.0, v42
	v_rcp_f32_e32 v43, v36
	v_mad_i64_i32 v[40:41], s[26:27], v51, s45, v[120:121]
	v_lshl_add_u64 v[40:41], v[40:41], 0, v[122:123]
	global_store_short_d16_hi v[40:41], v32, off offset:32
	v_mul_f32_e32 v32, v33, v43
	v_mul_f32_e32 v36, 0xbfb8aa3b, v34
	v_exp_f32_e32 v36, v36
	v_mul_f32_e32 v32, v37, v32
	v_add_f32_e32 v36, 1.0, v36
	v_rcp_f32_e32 v41, v36
	v_cvt_pk_bf16_f32 v37, v32, v32
	v_mad_i64_i32 v[32:33], s[26:27], v49, s45, v[120:121]
	v_lshl_add_u64 v[32:33], v[32:33], 0, v[122:123]
	global_store_short_d16_hi v[32:33], v37, off offset:32
	v_mul_f32_e32 v32, v34, v41
	v_mul_f32_e32 v34, 0xbfb8aa3b, v35
	v_exp_f32_e32 v34, v34
	v_mul_f32_e32 v32, v38, v32
	v_add_f32_e32 v34, 1.0, v34
	v_rcp_f32_e32 v38, v34
	v_cvt_pk_bf16_f32 v36, v32, v32
	v_mad_i64_i32 v[32:33], s[26:27], v45, s45, v[120:121]
	v_lshl_add_u64 v[32:33], v[32:33], 0, v[122:123]
	global_store_short_d16_hi v[32:33], v36, off offset:32
	v_mul_f32_e32 v32, v35, v38
	v_mul_f32_e32 v32, v39, v32
	v_cvt_pk_bf16_f32 v34, v32, v32
	v_mul_f32_e32 v32, 0xbfb8aa3b, v24
	v_exp_f32_e32 v35, v32
	s_xor_b64 s[0:1], s[0:1], s[4:5]
	v_mad_i64_i32 v[32:33], s[26:27], v44, s45, v[120:121]
	v_lshl_add_u64 v[32:33], v[32:33], 0, v[122:123]
	global_store_short_d16_hi v[32:33], v34, off offset:32
	v_add_f32_e32 v32, 1.0, v35
	v_rcp_f32_e32 v34, v32
	v_or_b32_e32 v35, 0x60, v124
	v_mov_b32_e32 v36, v35
	v_mul_f32_e32 v24, v24, v34
	v_mul_f32_e32 v24, v28, v24
	v_cvt_pk_bf16_f32 v24, v24, v24
	v_mul_f32_e32 v28, 0xbfb8aa3b, v25
	v_exp_f32_e32 v28, v28
	v_mad_i64_i32 v[32:33], s[26:27], v36, s45, v[120:121]
	v_lshl_add_u64 v[32:33], v[32:33], 0, v[122:123]
	global_store_short_d16_hi v[32:33], v24, off
	v_add_f32_e32 v24, 1.0, v28
	v_rcp_f32_e32 v32, v24
	v_or_b32_e32 v33, 0x61, v124
	v_mov_b32_e32 v34, v33
	v_mul_f32_e32 v24, v25, v32
	v_mul_f32_e32 v24, v29, v24
	v_cvt_pk_bf16_f32 v28, v24, v24
	v_mul_f32_e32 v24, 0xbfb8aa3b, v26
	v_exp_f32_e32 v29, v24
	v_mad_i64_i32 v[24:25], s[26:27], v34, s45, v[120:121]
	v_lshl_add_u64 v[24:25], v[24:25], 0, v[122:123]
	global_store_short_d16_hi v[24:25], v28, off
	v_add_f32_e32 v24, 1.0, v29
	v_rcp_f32_e32 v28, v24
	v_or_b32_e32 v29, 0x62, v124
	v_mov_b32_e32 v32, v29
	v_mul_f32_e32 v24, v26, v28
	v_mul_f32_e32 v24, v30, v24
	v_cvt_pk_bf16_f32 v26, v24, v24
	v_mul_f32_e32 v24, 0xbfb8aa3b, v27
	v_exp_f32_e32 v28, v24
	v_mad_i64_i32 v[24:25], s[26:27], v32, s45, v[120:121]
	v_lshl_add_u64 v[24:25], v[24:25], 0, v[122:123]
	global_store_short_d16_hi v[24:25], v26, off
	v_add_f32_e32 v24, 1.0, v28
	v_rcp_f32_e32 v26, v24
	v_or_b32_e32 v28, 0x63, v124
	v_mov_b32_e32 v30, v28
	v_mul_f32_e32 v24, v27, v26
	v_mul_f32_e32 v26, 0xbfb8aa3b, v16
	v_exp_f32_e32 v26, v26
	v_mul_f32_e32 v24, v31, v24
	v_add_f32_e32 v26, 1.0, v26
	v_cvt_pk_bf16_f32 v27, v24, v24
	v_mad_i64_i32 v[24:25], s[26:27], v30, s45, v[120:121]
	v_rcp_f32_e32 v31, v26
	v_lshl_add_u64 v[24:25], v[24:25], 0, v[122:123]
	global_store_short_d16_hi v[24:25], v27, off
	v_mul_f32_e32 v16, v16, v31
	v_mul_f32_e32 v24, 0xbfb8aa3b, v17
	v_exp_f32_e32 v26, v24
	v_mul_f32_e32 v16, v20, v16
	v_cvt_pk_bf16_f32 v16, v16, v16
	v_add_f32_e32 v20, 1.0, v26
	v_rcp_f32_e32 v27, v20
	v_mad_i64_i32 v[24:25], s[26:27], v35, s45, v[120:121]
	v_lshl_add_u64 v[24:25], v[24:25], 0, v[122:123]
	global_store_short_d16_hi v[24:25], v16, off offset:32
	v_mul_f32_e32 v16, v17, v27
	v_mul_f32_e32 v20, 0xbfb8aa3b, v18
	v_exp_f32_e32 v20, v20
	v_mul_f32_e32 v16, v21, v16
	v_add_f32_e32 v20, 1.0, v20
	v_rcp_f32_e32 v25, v20
	v_cvt_pk_bf16_f32 v21, v16, v16
	v_mad_i64_i32 v[16:17], s[26:27], v33, s45, v[120:121]
	v_lshl_add_u64 v[16:17], v[16:17], 0, v[122:123]
	global_store_short_d16_hi v[16:17], v21, off offset:32
	v_mul_f32_e32 v16, v18, v25
	v_mul_f32_e32 v18, 0xbfb8aa3b, v19
	v_exp_f32_e32 v18, v18
	v_mul_f32_e32 v16, v22, v16
	v_add_f32_e32 v18, 1.0, v18
	v_rcp_f32_e32 v22, v18
	v_cvt_pk_bf16_f32 v20, v16, v16
	v_mad_i64_i32 v[16:17], s[26:27], v29, s45, v[120:121]
	v_lshl_add_u64 v[16:17], v[16:17], 0, v[122:123]
	global_store_short_d16_hi v[16:17], v20, off offset:32
	v_mul_f32_e32 v16, v19, v22
	v_mul_f32_e32 v16, v23, v16
	v_cvt_pk_bf16_f32 v18, v16, v16
	v_mul_f32_e32 v16, 0xbfb8aa3b, v8
	v_exp_f32_e32 v19, v16
	s_cmpk_gt_i32 s2, 0x1b7
	v_mad_i64_i32 v[16:17], s[26:27], v28, s45, v[120:121]
	v_lshl_add_u64 v[16:17], v[16:17], 0, v[122:123]
	global_store_short_d16_hi v[16:17], v18, off offset:32
	v_add_f32_e32 v16, 1.0, v19
	v_rcp_f32_e32 v18, v16
	v_or_b32_e32 v19, 0x70, v124
	v_mov_b32_e32 v20, v19
	v_mul_f32_e32 v8, v8, v18
	v_mul_f32_e32 v8, v12, v8
	v_cvt_pk_bf16_f32 v8, v8, v8
	v_mul_f32_e32 v12, 0xbfb8aa3b, v9
	v_exp_f32_e32 v12, v12
	v_mad_i64_i32 v[16:17], s[26:27], v20, s45, v[120:121]
	v_lshl_add_u64 v[16:17], v[16:17], 0, v[122:123]
	global_store_short_d16_hi v[16:17], v8, off
	v_add_f32_e32 v8, 1.0, v12
	v_rcp_f32_e32 v16, v8
	v_or_b32_e32 v17, 0x71, v124
	v_mov_b32_e32 v18, v17
	v_mul_f32_e32 v8, v9, v16
	v_mul_f32_e32 v8, v13, v8
	v_cvt_pk_bf16_f32 v12, v8, v8
	v_mul_f32_e32 v8, 0xbfb8aa3b, v10
	v_exp_f32_e32 v13, v8
	v_mad_i64_i32 v[8:9], s[26:27], v18, s45, v[120:121]
	v_lshl_add_u64 v[8:9], v[8:9], 0, v[122:123]
	global_store_short_d16_hi v[8:9], v12, off
	v_add_f32_e32 v8, 1.0, v13
	v_rcp_f32_e32 v12, v8
	v_or_b32_e32 v13, 0x72, v124
	v_mov_b32_e32 v16, v13
	v_mul_f32_e32 v8, v10, v12
	v_mul_f32_e32 v8, v14, v8
	v_cvt_pk_bf16_f32 v10, v8, v8
	v_mul_f32_e32 v8, 0xbfb8aa3b, v11
	v_exp_f32_e32 v12, v8
	v_mad_i64_i32 v[8:9], s[26:27], v16, s45, v[120:121]
	v_lshl_add_u64 v[8:9], v[8:9], 0, v[122:123]
	global_store_short_d16_hi v[8:9], v10, off
	v_add_f32_e32 v8, 1.0, v12
	v_rcp_f32_e32 v10, v8
	v_or_b32_e32 v12, 0x73, v124
	v_mov_b32_e32 v14, v12
	v_mul_f32_e32 v8, v11, v10
	v_mul_f32_e32 v10, 0xbfb8aa3b, v0
	v_exp_f32_e32 v10, v10
	v_mul_f32_e32 v8, v15, v8
	v_add_f32_e32 v10, 1.0, v10
	v_cvt_pk_bf16_f32 v11, v8, v8
	v_mad_i64_i32 v[8:9], s[26:27], v14, s45, v[120:121]
	v_rcp_f32_e32 v15, v10
	v_lshl_add_u64 v[8:9], v[8:9], 0, v[122:123]
	global_store_short_d16_hi v[8:9], v11, off
	v_mul_f32_e32 v0, v0, v15
	v_mul_f32_e32 v8, 0xbfb8aa3b, v1
	v_exp_f32_e32 v10, v8
	v_mul_f32_e32 v0, v4, v0
	v_cvt_pk_bf16_f32 v0, v0, v0
	v_add_f32_e32 v4, 1.0, v10
	v_rcp_f32_e32 v11, v4
	v_mad_i64_i32 v[8:9], s[26:27], v19, s45, v[120:121]
	v_lshl_add_u64 v[8:9], v[8:9], 0, v[122:123]
	global_store_short_d16_hi v[8:9], v0, off offset:32
	v_mul_f32_e32 v0, v1, v11
	v_mul_f32_e32 v4, 0xbfb8aa3b, v2
	v_exp_f32_e32 v4, v4
	v_mul_f32_e32 v0, v5, v0
	v_add_f32_e32 v4, 1.0, v4
	v_rcp_f32_e32 v9, v4
	v_cvt_pk_bf16_f32 v5, v0, v0
	v_mad_i64_i32 v[0:1], s[26:27], v17, s45, v[120:121]
	v_lshl_add_u64 v[0:1], v[0:1], 0, v[122:123]
	global_store_short_d16_hi v[0:1], v5, off offset:32
	v_mul_f32_e32 v0, v2, v9
	v_mul_f32_e32 v2, 0xbfb8aa3b, v3
	v_exp_f32_e32 v2, v2
	v_mul_f32_e32 v0, v6, v0
	v_add_f32_e32 v2, 1.0, v2
	v_rcp_f32_e32 v6, v2
	v_cvt_pk_bf16_f32 v4, v0, v0
	v_mad_i64_i32 v[0:1], s[26:27], v13, s45, v[120:121]
	v_lshl_add_u64 v[0:1], v[0:1], 0, v[122:123]
	global_store_short_d16_hi v[0:1], v4, off offset:32
	v_mul_f32_e32 v0, v3, v6
	v_mul_f32_e32 v0, v7, v0
	v_cvt_pk_bf16_f32 v2, v0, v0
	v_mad_i64_i32 v[0:1], s[26:27], v12, s45, v[120:121]
	v_lshl_add_u64 v[0:1], v[0:1], 0, v[122:123]
	global_store_short_d16_hi v[0:1], v2, off offset:32
	s_cbranch_scc0 .LBB0_3005

.LBB0_3062:
	s_ashr_i32 s18, s2, 31
	s_lshr_b32 s18, s18, 27
	s_add_i32 s18, s2, s18
	s_ashr_i32 s18, s18, 5
	s_lshl_b32 s19, s18, 2
	s_and_b32 s37, s2, 3
	s_add_i32 s39, s19, s20
	s_or_b32 s19, s39, s37
	s_lshl_b32 s37, s19, 7
	s_lshl_b32 s40, s18, 10
	s_lshl_b32 s18, s2, 5
	v_add_u32_e32 v2, s37, v77
	s_sub_i32 s18, s18, s40
	s_mov_b32 m0, s21
	s_and_b32 s38, s18, 0xffffff80
	v_mad_i64_i32 v[2:3], s[18:19], v2, s24, v[68:69]
	v_add_u32_e32 v0, s38, v77
	s_setprio 2
	global_load_lds_dwordx4 v[2:3], off
	v_lshl_add_u64 v[4:5], v[2:3], 0, s[0:1]
	s_mov_b32 m0, s25
	v_mad_i64_i32 v[0:1], s[18:19], v0, s24, v[66:67]
	global_load_lds_dwordx4 v[4:5], off
	s_mov_b32 m0, s26
	v_lshl_add_u64 v[4:5], v[0:1], 0, s[0:1]
	global_load_lds_dwordx4 v[0:1], off
	s_mov_b32 m0, s27
	s_sub_i32 s18, s22, s40
	global_load_lds_dwordx4 v[4:5], off
	v_lshl_add_u64 v[4:5], v[2:3], 0, 64
	s_mov_b32 m0, s28
	v_lshl_add_u64 v[2:3], v[2:3], 0, s[4:5]
	global_load_lds_dwordx4 v[4:5], off
	s_mov_b32 m0, s29
	s_and_b32 s41, s17, 3
	global_load_lds_dwordx4 v[2:3], off
	v_lshl_add_u64 v[2:3], v[0:1], 0, 64
	s_mov_b32 m0, s31
	v_lshl_add_u64 v[0:1], v[0:1], 0, s[4:5]
	global_load_lds_dwordx4 v[2:3], off
	s_mov_b32 m0, s33
	s_and_b32 s18, s18, 0xffffff80
	global_load_lds_dwordx4 v[0:1], off
	v_add_u32_e32 v0, s18, v77
	s_add_i32 s39, s39, s41
	v_mad_i64_i32 v[72:73], s[18:19], v0, s24, v[66:67]
	v_lshl_add_u32 v0, s39, 7, v77
	v_mad_i64_i32 v[74:75], s[18:19], v0, s24, v[68:69]
	s_mov_b64 s[18:19], 0
	s_mov_b32 s39, 2
	s_mov_b32 s40, 0
	v_mov_b32_e32 v20, 0
	v_mov_b32_e32 v21, v65
	v_mov_b32_e32 v22, v65
	v_mov_b32_e32 v23, v65
	v_mov_b32_e32 v0, 0
	v_mov_b32_e32 v1, v65
	v_mov_b32_e32 v2, v65
	v_mov_b32_e32 v3, v65
	v_mov_b32_e32 v4, 0
	v_mov_b32_e32 v5, v65
	v_mov_b32_e32 v6, v65
	v_mov_b32_e32 v7, v65
	v_mov_b32_e32 v8, 0
	v_mov_b32_e32 v9, v65
	v_mov_b32_e32 v10, v65
	v_mov_b32_e32 v11, v65
	v_mov_b32_e32 v12, 0
	v_mov_b32_e32 v13, v65
	v_mov_b32_e32 v14, v65
	v_mov_b32_e32 v15, v65
	v_mov_b32_e32 v16, 0
	v_mov_b32_e32 v17, v65
	v_mov_b32_e32 v18, v65
	v_mov_b32_e32 v19, v65
	v_mov_b32_e32 v24, 0
	v_mov_b32_e32 v25, v65
	v_mov_b32_e32 v26, v65
	v_mov_b32_e32 v27, v65
	v_mov_b32_e32 v28, 0
	v_mov_b32_e32 v29, v65
	v_mov_b32_e32 v30, v65
	v_mov_b32_e32 v31, v65
	v_mov_b32_e32 v32, 0
	v_mov_b32_e32 v33, v65
	v_mov_b32_e32 v34, v65
	v_mov_b32_e32 v35, v65
	v_mov_b32_e32 v36, 0
	v_mov_b32_e32 v37, v65
	v_mov_b32_e32 v38, v65
	v_mov_b32_e32 v39, v65
	v_mov_b32_e32 v40, 0
	v_mov_b32_e32 v41, v65
	v_mov_b32_e32 v42, v65
	v_mov_b32_e32 v43, v65
	v_mov_b32_e32 v44, 0
	v_mov_b32_e32 v45, v65
	v_mov_b32_e32 v46, v65
	v_mov_b32_e32 v47, v65
	v_mov_b32_e32 v48, 0
	v_mov_b32_e32 v49, v65
	v_mov_b32_e32 v50, v65
	v_mov_b32_e32 v51, v65
	v_mov_b32_e32 v52, 0
	v_mov_b32_e32 v53, v65
	v_mov_b32_e32 v54, v65
	v_mov_b32_e32 v55, v65
	v_mov_b32_e32 v56, 0
	v_mov_b32_e32 v57, v65
	v_mov_b32_e32 v58, v65
	v_mov_b32_e32 v59, v65
	v_mov_b32_e32 v60, 0
	v_mov_b32_e32 v61, v65
	v_mov_b32_e32 v62, v65
	v_mov_b32_e32 v63, v65
.LBB0_3063:
	s_lshl_b32 s41, s39, 14
	s_waitcnt vmcnt(0)
	v_lshl_add_u64 v[116:117], v[74:75], 0, s[18:19]
	s_add_i32 s41, s21, s41
	s_waitcnt lgkmcnt(0)
	s_barrier
	s_lshl_b32 s98, s40, 14
	v_add_u32_e32 v120, s98, v80
	v_or_b32_e32 v121, s98, v81
	ds_read_b128 v[84:87], v120
	ds_read_b128 v[88:91], v120 offset:1024
	ds_read_b128 v[92:95], v120 offset:2048
	ds_read_b128 v[96:99], v120 offset:3072
	ds_read_b128 v[100:103], v121
	ds_read_b128 v[104:107], v121 offset:1024
	ds_read_b128 v[108:111], v121 offset:2048
	ds_read_b128 v[112:115], v121 offset:3072
	v_lshl_add_u64 v[162:163], v[116:117], 0, s[6:7]
	s_mov_b32 m0, s41
	v_lshl_add_u64 v[118:119], v[72:73], 0, s[18:19]
	v_lshl_add_u64 v[164:165], v[116:117], 0, s[8:9]
	global_load_lds_dwordx4 v[162:163], off
	s_add_i32 m0, s41, 0x400
	v_lshl_add_u64 v[166:167], v[118:119], 0, s[6:7]
	global_load_lds_dwordx4 v[164:165], off
	s_add_i32 m0, s41, 0x2000
	s_lshl_b32 s42, s40, 14
	global_load_lds_dwordx4 v[166:167], off
	s_add_i32 m0, s41, 0x2400
	s_add_i32 s41, s40, 1
	s_cmp_lg_u32 s40, 3
	s_cselect_b32 s40, s41, 0
	s_add_i32 s41, s39, 1
	v_lshl_add_u64 v[168:169], v[118:119], 0, s[8:9]
	s_cmp_lg_u32 s39, 3
	global_load_lds_dwordx4 v[168:169], off
	s_cselect_b32 s39, s41, 0
	s_waitcnt lgkmcnt(0)
	s_lshl_b32 s41, s39, 14
	s_add_i32 s41, s21, s41
	v_mfma_f32_16x16x32_bf16 v[60:63], v[100:103], v[84:87], v[60:63]
	v_mfma_f32_16x16x32_bf16 v[56:59], v[104:107], v[84:87], v[56:59]
	s_mov_b32 m0, s41
	v_mfma_f32_16x16x32_bf16 v[52:55], v[108:111], v[84:87], v[52:55]
	v_mfma_f32_16x16x32_bf16 v[48:51], v[112:115], v[84:87], v[48:51]
	v_lshl_add_u64 v[84:85], v[116:117], 0, s[10:11]
	v_lshl_add_u64 v[86:87], v[116:117], 0, s[12:13]
	global_load_lds_dwordx4 v[84:85], off
	s_add_i32 m0, s41, 0x400
	v_mfma_f32_16x16x32_bf16 v[44:47], v[100:103], v[88:91], v[44:47]
	global_load_lds_dwordx4 v[86:87], off
	s_add_i32 m0, s41, 0x2000
	v_mfma_f32_16x16x32_bf16 v[40:43], v[104:107], v[88:91], v[40:43]
	v_mfma_f32_16x16x32_bf16 v[36:39], v[108:111], v[88:91], v[36:39]
	v_mfma_f32_16x16x32_bf16 v[32:35], v[112:115], v[88:91], v[32:35]
	v_lshl_add_u64 v[88:89], v[118:119], 0, s[10:11]
	v_lshl_add_u64 v[90:91], v[118:119], 0, s[12:13]
	global_load_lds_dwordx4 v[88:89], off
	s_add_i32 m0, s41, 0x2400
	v_mfma_f32_16x16x32_bf16 v[28:31], v[100:103], v[92:95], v[28:31]
	global_load_lds_dwordx4 v[90:91], off
	s_lshl_b32 s41, s40, 14
	v_mfma_f32_16x16x32_bf16 v[24:27], v[104:107], v[92:95], v[24:27]
	v_add_u32_e32 v116, s41, v80
	v_or_b32_e32 v117, s41, v81
	s_add_i32 s41, s40, 1
	v_mfma_f32_16x16x32_bf16 v[16:19], v[108:111], v[92:95], v[16:19]
	s_cmp_lg_u32 s40, 3
	s_cselect_b32 s40, s41, 0
	s_add_i32 s41, s39, 1
	v_mfma_f32_16x16x32_bf16 v[12:15], v[112:115], v[92:95], v[12:15]
	s_cmp_lg_u32 s39, 3
	s_cselect_b32 s39, s41, 0
	s_add_u32 s18, s18, 0x80
	v_mfma_f32_16x16x32_bf16 v[8:11], v[100:103], v[96:99], v[8:11]
	s_addc_u32 s19, s19, 0
	s_cmpk_eq_i32 s18, 0x1580
	v_mfma_f32_16x16x32_bf16 v[4:7], v[104:107], v[96:99], v[4:7]
	v_mfma_f32_16x16x32_bf16 v[0:3], v[108:111], v[96:99], v[0:3]
	v_mfma_f32_16x16x32_bf16 v[20:23], v[112:115], v[96:99], v[20:23]
	ds_read_b128 v[84:87], v116
	ds_read_b128 v[88:91], v116 offset:1024
	ds_read_b128 v[92:95], v116 offset:2048
	ds_read_b128 v[96:99], v116 offset:3072
	ds_read_b128 v[100:103], v117
	ds_read_b128 v[104:107], v117 offset:1024
	ds_read_b128 v[108:111], v117 offset:2048
	ds_read_b128 v[112:115], v117 offset:3072
	s_waitcnt lgkmcnt(0)
	s_nop 0
	v_mfma_f32_16x16x32_bf16 v[60:63], v[100:103], v[84:87], v[60:63]
	v_mfma_f32_16x16x32_bf16 v[56:59], v[104:107], v[84:87], v[56:59]
	v_mfma_f32_16x16x32_bf16 v[52:55], v[108:111], v[84:87], v[52:55]
	v_mfma_f32_16x16x32_bf16 v[48:51], v[112:115], v[84:87], v[48:51]
	v_mfma_f32_16x16x32_bf16 v[44:47], v[100:103], v[88:91], v[44:47]
	v_mfma_f32_16x16x32_bf16 v[40:43], v[104:107], v[88:91], v[40:43]
	v_mfma_f32_16x16x32_bf16 v[36:39], v[108:111], v[88:91], v[36:39]
	v_mfma_f32_16x16x32_bf16 v[32:35], v[112:115], v[88:91], v[32:35]
	v_mfma_f32_16x16x32_bf16 v[28:31], v[100:103], v[92:95], v[28:31]
	v_mfma_f32_16x16x32_bf16 v[24:27], v[104:107], v[92:95], v[24:27]
	v_mfma_f32_16x16x32_bf16 v[16:19], v[108:111], v[92:95], v[16:19]
	v_mfma_f32_16x16x32_bf16 v[12:15], v[112:115], v[92:95], v[12:15]
	v_mfma_f32_16x16x32_bf16 v[8:11], v[100:103], v[96:99], v[8:11]
	v_mfma_f32_16x16x32_bf16 v[4:7], v[104:107], v[96:99], v[4:7]
	v_mfma_f32_16x16x32_bf16 v[0:3], v[108:111], v[96:99], v[0:3]
	v_mfma_f32_16x16x32_bf16 v[20:23], v[112:115], v[96:99], v[20:23]
	s_cbranch_scc0 .LBB0_3063
	s_waitcnt vmcnt(4)
	s_waitcnt lgkmcnt(0)
	s_barrier
	ds_read_b128 v[72:75], v80 offset:32768
	ds_read_b128 v[84:87], v80 offset:33792
	ds_read_b128 v[88:91], v80 offset:34816
	ds_read_b128 v[92:95], v80 offset:35840
	ds_read_b128 v[96:99], v81 offset:32768
	ds_read_b128 v[100:103], v81 offset:33792
	ds_read_b128 v[104:107], v81 offset:34816
	ds_read_b128 v[108:111], v81 offset:35840
	s_waitcnt lgkmcnt(0)
	s_waitcnt vmcnt(0)
	s_waitcnt lgkmcnt(0)
	s_barrier
	v_mfma_f32_16x16x32_bf16 v[112:115], v[96:99], v[72:75], v[60:63]
	v_readlane_b32 s40, v241, 1
	v_readlane_b32 s48, v241, 9
	v_mfma_f32_16x16x32_bf16 v[116:119], v[100:103], v[72:75], v[56:59]
	v_readlane_b32 s49, v241, 10
	s_add_i32 s2, s2, s3
	s_add_i32 s22, s22, s23
	v_mfma_f32_16x16x32_bf16 v[120:123], v[104:107], v[72:75], v[52:55]
	v_readlane_b32 s41, v241, 2
	v_readlane_b32 s42, v241, 3
	v_readlane_b32 s43, v241, 4
	v_mfma_f32_16x16x32_bf16 v[124:127], v[108:111], v[72:75], v[48:51]
	v_add_u32_e32 v74, s37, v78
	v_cmp_lt_i32_e32 vcc, s35, v74
	v_readlane_b32 s44, v241, 5
	v_mfma_f32_16x16x32_bf16 v[60:63], v[104:107], v[88:91], v[16:19]
	v_readlane_b32 s45, v241, 6
	v_readlane_b32 s46, v241, 7
	v_readlane_b32 s47, v241, 8
	v_add_u32_e32 v16, 0xfffff000, v74
	v_lshrrev_b32_e32 v16, 12, v16
	v_mfma_f32_16x16x32_bf16 v[152:155], v[100:103], v[88:91], v[24:27]
	v_add_u32_e32 v16, 6, v16
	v_readlane_b32 s50, v241, 11
	v_readlane_b32 s51, v241, 12
	v_or_b32_e32 v24, s38, v79
	v_mfma_f32_16x16x32_bf16 v[56:59], v[108:111], v[88:91], v[12:15]
	v_ashrrev_i32_e32 v25, 31, v24
	v_lshlrev_b64 v[72:73], 2, v[24:25]
	v_readlane_b32 s52, v241, 13
	v_cndmask_b32_e32 v12, 5, v16, vcc
	v_mad_u64_u32 v[12:13], s[18:19], v12, s30, v[70:71]
	v_mfma_f32_16x16x32_bf16 v[48:51], v[96:99], v[92:95], v[8:11]
	v_readlane_b32 s53, v241, 14
	v_readlane_b32 s54, v241, 15
	v_readlane_b32 s55, v241, 16
	v_lshl_add_u64 v[8:9], v[12:13], 0, v[72:73]
	v_lshl_add_u64 v[12:13], v[8:9], 0, v[64:65]
	v_mfma_f32_16x16x32_bf16 v[128:131], v[96:99], v[84:87], v[44:47]
	v_add_co_u32_e32 v18, vcc, s36, v12
	v_lshl_add_u64 v[16:17], v[12:13], 0, s[14:15]
	v_mfma_f32_16x16x32_bf16 v[132:135], v[100:103], v[84:87], v[40:43]
	v_addc_co_u32_e32 v19, vcc, 0, v13, vcc
	v_mfma_f32_16x16x32_bf16 v[136:139], v[104:107], v[84:87], v[36:39]
	v_mfma_f32_16x16x32_bf16 v[84:87], v[108:111], v[84:87], v[32:35]
	v_mfma_f32_16x16x32_bf16 v[140:143], v[96:99], v[88:91], v[28:31]
	ds_read_b128 v[144:147], v80 offset:49152
	ds_read_b128 v[148:151], v80 offset:50176
	ds_read_b128 v[52:55], v80 offset:51200
	ds_read_b128 v[28:31], v80 offset:52224
	ds_read_b128 v[44:47], v81 offset:49152
	ds_read_b128 v[40:43], v81 offset:50176
	ds_read_b128 v[36:39], v81 offset:51200
	ds_read_b128 v[32:35], v81 offset:52224
	s_waitcnt lgkmcnt(0)
	s_waitcnt lgkmcnt(0)
	s_barrier
	v_or_b32_e32 v96, v74, v76
	v_mfma_f32_16x16x32_bf16 v[24:27], v[100:103], v[92:95], v[4:7]
	v_or_b32_e32 v156, 16, v96
	v_or_b32_e32 v158, 32, v96
	v_or_b32_e32 v74, 48, v96
	v_mfma_f32_16x16x32_bf16 v[4:7], v[104:107], v[92:95], v[0:3]
	s_nop 2
	global_load_dwordx4 v[0:3], v[16:17], off offset:64
	global_load_dwordx4 v[12:15], v[16:17], off offset:128
	v_mfma_f32_16x16x32_bf16 v[8:11], v[108:111], v[92:95], v[20:23]
	s_nop 2
	global_load_dwordx4 v[20:23], v[18:19], off
	s_nop 0
	global_load_dwordx4 v[16:19], v[16:17], off offset:192
	s_nop 0
	v_mov_b32_e32 v236, v96
	v_ashrrev_i32_e32 v237, 31, v96
	v_lshlrev_b64 v[236:237], 12, v[236:237]
	v_lshl_add_u64 v[236:237], s[48:49], 0, v[236:237]
	v_lshl_add_u64 v[236:237], v[236:237], 0, v[72:73]
	v_lshl_add_u64 v[236:237], v[236:237], 0, v[64:65]
	v_mov_b32_e32 v238, v156
	v_ashrrev_i32_e32 v239, 31, v156
	v_lshlrev_b64 v[238:239], 12, v[238:239]
	v_lshl_add_u64 v[238:239], s[48:49], 0, v[238:239]
	v_lshl_add_u64 v[238:239], v[238:239], 0, v[72:73]
	v_lshl_add_u64 v[238:239], v[238:239], 0, v[64:65]
	v_mov_b32_e32 v242, v158
	v_ashrrev_i32_e32 v243, 31, v158
	v_lshlrev_b64 v[242:243], 12, v[242:243]
	v_lshl_add_u64 v[242:243], s[48:49], 0, v[242:243]
	v_lshl_add_u64 v[242:243], v[242:243], 0, v[72:73]
	v_lshl_add_u64 v[242:243], v[242:243], 0, v[64:65]
	v_mov_b32_e32 v244, v74
	v_ashrrev_i32_e32 v245, 31, v74
	v_lshlrev_b64 v[244:245], 12, v[244:245]
	v_lshl_add_u64 v[244:245], s[48:49], 0, v[244:245]
	v_lshl_add_u64 v[244:245], v[244:245], 0, v[72:73]
	v_lshl_add_u64 v[244:245], v[244:245], 0, v[64:65]
	global_load_dwordx4 v[170:173], v[236:237], off
	global_load_dwordx4 v[174:177], v[236:237], off offset:64
	global_load_dwordx4 v[178:181], v[236:237], off offset:128
	global_load_dwordx4 v[182:185], v[236:237], off offset:192
	global_load_dwordx4 v[186:189], v[238:239], off
	global_load_dwordx4 v[190:193], v[238:239], off offset:64
	global_load_dwordx4 v[194:197], v[238:239], off offset:128
	global_load_dwordx4 v[198:201], v[238:239], off offset:192
	global_load_dwordx4 v[202:205], v[242:243], off
	global_load_dwordx4 v[206:209], v[242:243], off offset:64
	global_load_dwordx4 v[210:213], v[242:243], off offset:128
	global_load_dwordx4 v[214:217], v[242:243], off offset:192
	global_load_dwordx4 v[218:221], v[244:245], off
	global_load_dwordx4 v[222:225], v[244:245], off offset:64
	global_load_dwordx4 v[228:231], v[244:245], off offset:128
	global_load_dwordx4 v[232:235], v[244:245], off offset:192
	v_mfma_f32_16x16x32_bf16 v[88:91], v[44:47], v[144:147], v[112:115]
	s_waitcnt vmcnt(15)
	v_pk_mul_f32 v[170:171], v[170:171], s[16:17] op_sel_hi:[1,0]
	v_mfma_f32_16x16x32_bf16 v[96:99], v[36:39], v[144:147], v[120:123]
	v_mul_f32_e64 v172, v172, s16
	v_mul_f32_e64 v173, v173, s16
	s_waitcnt vmcnt(14)
	v_pk_mul_f32 v[174:175], v[174:175], s[16:17] op_sel_hi:[1,0]
	v_pk_mul_f32 v[176:177], v[176:177], s[16:17] op_sel_hi:[1,0]
	v_mfma_f32_16x16x32_bf16 v[92:95], v[40:43], v[144:147], v[116:119]
	s_waitcnt vmcnt(13)
	v_mul_f32_e64 v178, v178, s16
	v_mul_f32_e64 v179, v179, s16
	v_pk_mul_f32 v[180:181], v[180:181], s[16:17] op_sel_hi:[1,0]
	v_pk_fma_f32 v[88:89], v[88:89], v[20:21], v[170:171]
	v_mfma_f32_16x16x32_bf16 v[104:107], v[32:35], v[144:147], v[124:127]
	v_fma_f32 v90, v90, v22, v172
	v_fma_f32 v91, v91, v23, v173
	v_pk_fma_f32 v[92:93], v[92:93], v[0:1], v[174:175]
	v_pk_fma_f32 v[94:95], v[94:95], v[2:3], v[176:177]
	v_pk_fma_f32 v[96:97], v[96:97], v[12:13], v[178:179]
	v_pk_fma_f32 v[98:99], v[98:99], v[14:15], v[180:181]
	v_mfma_f32_16x16x32_bf16 v[116:119], v[44:47], v[148:151], v[128:131]
	s_waitcnt vmcnt(12)
	v_pk_mul_f32 v[182:183], v[182:183], s[16:17] op_sel_hi:[1,0]
	v_pk_mul_f32 v[184:185], v[184:185], s[16:17] op_sel_hi:[1,0]
	v_pk_fma_f32 v[170:171], v[104:105], v[16:17], v[182:183]
	v_pk_fma_f32 v[172:173], v[106:107], v[18:19], v[184:185]
	global_store_dwordx4 v[236:237], v[88:91], off
	global_store_dwordx4 v[236:237], v[92:95], off offset:64
	global_store_dwordx4 v[236:237], v[96:99], off offset:128
	global_store_dwordx4 v[236:237], v[170:173], off offset:192
	v_mfma_f32_16x16x32_bf16 v[124:127], v[40:43], v[148:151], v[132:135]
	v_mfma_f32_16x16x32_bf16 v[92:95], v[36:39], v[148:151], v[136:139]
	s_waitcnt vmcnt(15)
	v_pk_mul_f32 v[186:187], v[186:187], s[16:17] op_sel_hi:[1,0]
	v_mfma_f32_16x16x32_bf16 v[84:87], v[32:35], v[148:151], v[84:87]
	v_mul_f32_e64 v188, v188, s16
	v_mul_f32_e64 v189, v189, s16
	s_waitcnt vmcnt(14)
	v_pk_mul_f32 v[190:191], v[190:191], s[16:17] op_sel_hi:[1,0]
	v_pk_mul_f32 v[192:193], v[192:193], s[16:17] op_sel_hi:[1,0]
	s_waitcnt vmcnt(13)
	v_pk_mul_f32 v[194:195], v[194:195], s[16:17] op_sel_hi:[1,0]
	v_pk_mul_f32 v[196:197], v[196:197], s[16:17] op_sel_hi:[1,0]
	s_waitcnt vmcnt(12)
	v_pk_mul_f32 v[198:199], v[198:199], s[16:17] op_sel_hi:[1,0]
	v_pk_mul_f32 v[200:201], v[200:201], s[16:17] op_sel_hi:[1,0]
	v_pk_fma_f32 v[186:187], v[116:117], v[20:21], v[186:187]
	v_pk_fma_f32 v[188:189], v[118:119], v[22:23], v[188:189]
	v_pk_fma_f32 v[190:191], v[124:125], v[0:1], v[190:191]
	v_pk_fma_f32 v[192:193], v[126:127], v[2:3], v[192:193]
	v_pk_fma_f32 v[92:93], v[92:93], v[12:13], v[194:195]
	v_pk_fma_f32 v[94:95], v[94:95], v[14:15], v[196:197]
	v_pk_fma_f32 v[84:85], v[84:85], v[16:17], v[198:199]
	v_pk_fma_f32 v[86:87], v[86:87], v[18:19], v[200:201]
	global_store_dwordx4 v[238:239], v[186:189], off
	global_store_dwordx4 v[238:239], v[190:193], off offset:64
	global_store_dwordx4 v[238:239], v[92:95], off offset:128
	global_store_dwordx4 v[238:239], v[84:87], off offset:192
	v_mfma_f32_16x16x32_bf16 v[174:177], v[44:47], v[52:55], v[140:143]
	v_mfma_f32_16x16x32_bf16 v[186:189], v[40:43], v[52:55], v[152:155]
	v_mfma_f32_16x16x32_bf16 v[60:63], v[36:39], v[52:55], v[60:63]
	v_mfma_f32_16x16x32_bf16 v[52:55], v[32:35], v[52:55], v[56:59]
	v_mfma_f32_16x16x32_bf16 v[44:47], v[44:47], v[28:31], v[48:51]
	s_waitcnt vmcnt(15)
	v_pk_mul_f32 v[56:57], v[202:203], s[16:17] op_sel_hi:[1,0]
	v_pk_mul_f32 v[58:59], v[204:205], s[16:17] op_sel_hi:[1,0]
	s_waitcnt vmcnt(14)
	v_pk_mul_f32 v[202:203], v[206:207], s[16:17] op_sel_hi:[1,0]
	v_pk_mul_f32 v[204:205], v[208:209], s[16:17] op_sel_hi:[1,0]
	s_waitcnt vmcnt(13)
	v_pk_mul_f32 v[206:207], v[210:211], s[16:17] op_sel_hi:[1,0]
	v_pk_mul_f32 v[208:209], v[212:213], s[16:17] op_sel_hi:[1,0]
	s_waitcnt vmcnt(12)
	v_pk_mul_f32 v[210:211], v[214:215], s[16:17] op_sel_hi:[1,0]
	v_pk_mul_f32 v[212:213], v[216:217], s[16:17] op_sel_hi:[1,0]
	v_pk_fma_f32 v[56:57], v[174:175], v[20:21], v[56:57]
	v_pk_fma_f32 v[58:59], v[176:177], v[22:23], v[58:59]
	v_pk_fma_f32 v[202:203], v[186:187], v[0:1], v[202:203]
	v_pk_fma_f32 v[204:205], v[188:189], v[2:3], v[204:205]
	v_pk_fma_f32 v[60:61], v[60:61], v[12:13], v[206:207]
	v_pk_fma_f32 v[62:63], v[62:63], v[14:15], v[208:209]
	v_pk_fma_f32 v[52:53], v[52:53], v[16:17], v[210:211]
	v_pk_fma_f32 v[54:55], v[54:55], v[18:19], v[212:213]
	global_store_dwordx4 v[242:243], v[56:59], off
	global_store_dwordx4 v[242:243], v[202:205], off offset:64
	global_store_dwordx4 v[242:243], v[60:63], off offset:128
	global_store_dwordx4 v[242:243], v[52:55], off offset:192
	v_mfma_f32_16x16x32_bf16 v[24:27], v[40:43], v[28:31], v[24:27]
	v_mfma_f32_16x16x32_bf16 v[4:7], v[36:39], v[28:31], v[4:7]
	s_add_i32 s17, s17, s34
	s_cmpk_gt_i32 s2, 0x9f
	s_waitcnt vmcnt(13)
	v_pk_mul_f32 v[36:37], v[228:229], s[16:17] op_sel_hi:[1,0]
	v_mfma_f32_16x16x32_bf16 v[8:11], v[32:35], v[28:31], v[8:11]
	s_setprio 0
	v_mul_f32_e64 v28, v218, s16
	v_mul_f32_e64 v29, v219, s16
	v_pk_mul_f32 v[30:31], v[220:221], s[16:17] op_sel_hi:[1,0]
	v_pk_mul_f32 v[32:33], v[222:223], s[16:17] op_sel_hi:[1,0]
	v_pk_mul_f32 v[34:35], v[224:225], s[16:17] op_sel_hi:[1,0]
	v_pk_mul_f32 v[38:39], v[230:231], s[16:17] op_sel_hi:[1,0]
	s_waitcnt vmcnt(12)
	v_pk_mul_f32 v[232:233], v[232:233], s[16:17] op_sel_hi:[1,0]
	v_pk_mul_f32 v[234:235], v[234:235], s[16:17] op_sel_hi:[1,0]
	v_pk_fma_f32 v[20:21], v[44:45], v[20:21], v[28:29]
	v_pk_fma_f32 v[22:23], v[46:47], v[22:23], v[30:31]
	v_pk_fma_f32 v[0:1], v[24:25], v[0:1], v[32:33]
	v_pk_fma_f32 v[2:3], v[26:27], v[2:3], v[34:35]
	v_pk_fma_f32 v[4:5], v[4:5], v[12:13], v[36:37]
	v_pk_fma_f32 v[6:7], v[6:7], v[14:15], v[38:39]
	v_pk_fma_f32 v[8:9], v[8:9], v[16:17], v[232:233]
	v_pk_fma_f32 v[10:11], v[10:11], v[18:19], v[234:235]
	global_store_dwordx4 v[244:245], v[20:23], off
	global_store_dwordx4 v[244:245], v[0:3], off offset:64
	global_store_dwordx4 v[244:245], v[4:7], off offset:128
	global_store_dwordx4 v[244:245], v[8:11], off offset:192
	s_cbranch_scc0 .LBB0_3062
